# v20 + end-of-MFMA-segment barrier issued one MFMA early, trailing MFMA at s_setprio 3
# speedup vs baseline: 1.0008x; 1.0008x over previous
.LBB0_303:
	s_ashr_i32 s35, s34, 31
	s_lshl_b64 s[8:9], s[34:35], 20
	s_add_u32 s36, s53, s8
	s_addc_u32 s37, s54, s9
	s_and_b64 s[8:9], s[2:3], exec
	s_cselect_b32 s35, s37, s5
	s_cselect_b32 s52, s36, s4
	s_ashr_i32 s31, s30, 31
	s_lshl_b64 s[8:9], s[30:31], 20
	s_add_u32 s38, s55, s8
	s_addc_u32 s39, s56, s9
	s_and_b64 s[8:9], s[2:3], exec
	s_cselect_b32 s31, s39, s7
	s_cselect_b32 s77, s38, s6
	s_add_u32 s4, s4, 0x80080
	s_addc_u32 s5, s5, 0
	s_add_u32 s78, s6, 0x100
	s_addc_u32 s79, s7, 0
	s_mov_b32 s80, -2
	s_waitcnt lgkmcnt(0)
	ds_read_b128 v[2:5], v234
	ds_read_b128 v[6:9], v234 offset:1024
	ds_read_b128 v[10:13], v234 offset:2048
	ds_read_b128 v[14:17], v234 offset:3072
	ds_read_b128 v[18:21], v235
	ds_read_b128 v[22:25], v235 offset:1024
	ds_read_b128 v[26:29], v235 offset:2048
	ds_read_b128 v[30:33], v235 offset:3072
	s_add_u32 s6, s4, 0xfff80080
	s_addc_u32 s7, s5, -1
	s_cmp_eq_u32 s80, 28
	s_cselect_b32 s9, s35, s7
	s_cselect_b32 s8, s52, s6
	s_cselect_b32 s7, s31, s79
	s_cselect_b32 s6, s77, s78
	v_lshl_add_u64 v[214:215], s[4:5], 0, v[206:207]
	s_add_i32 m0, s43, 0xc000
	ds_read_b128 v[98:101], v236
	ds_read_b128 v[102:105], v236 offset:1024
	ds_read_b128 v[106:109], v236 offset:2048
	ds_read_b128 v[110:113], v236 offset:3072
	ds_read_b128 v[178:181], v236 offset:4096
	ds_read_b128 v[182:185], v236 offset:5120
	ds_read_b128 v[186:189], v236 offset:6144
	ds_read_b128 v[190:193], v236 offset:7168
	global_load_lds_dwordx4 v[214:215], off
	v_lshl_add_u64 v[214:215], s[4:5], 0, v[208:209]
	s_add_i32 m0, s43, 0xe000
	s_nop 0
	global_load_lds_dwordx4 v[214:215], off
	s_waitcnt vmcnt(8)
	s_waitcnt lgkmcnt(0)
	s_barrier
	s_waitcnt lgkmcnt(0)
	v_mfma_i32_16x16x64_i8 v[174:177], v[2:5], v[98:101], 0
	v_mfma_i32_16x16x64_i8 v[170:173], v[10:13], v[98:101], 0
	v_mfma_i32_16x16x64_i8 v[158:161], v[2:5], v[106:109], 0
	v_mfma_i32_16x16x64_i8 v[154:157], v[10:13], v[106:109], 0
	v_mfma_i32_16x16x64_i8 v[142:145], v[2:5], v[178:181], 0
	v_mfma_i32_16x16x64_i8 v[138:141], v[10:13], v[178:181], 0
	v_mfma_i32_16x16x64_i8 v[126:129], v[2:5], v[186:189], 0
	v_mfma_i32_16x16x64_i8 v[122:125], v[10:13], v[186:189], 0
	v_mfma_i32_16x16x64_i8 v[174:177], v[6:9], v[102:105], v[174:177]
	v_mfma_i32_16x16x64_i8 v[170:173], v[14:17], v[102:105], v[170:173]
	v_mfma_i32_16x16x64_i8 v[158:161], v[6:9], v[110:113], v[158:161]
	v_mfma_i32_16x16x64_i8 v[154:157], v[14:17], v[110:113], v[154:157]
	v_mfma_i32_16x16x64_i8 v[142:145], v[6:9], v[182:185], v[142:145]
	v_mfma_i32_16x16x64_i8 v[138:141], v[14:17], v[182:185], v[138:141]
	v_mfma_i32_16x16x64_i8 v[126:129], v[6:9], v[190:193], v[126:129]
	v_mfma_i32_16x16x64_i8 v[122:125], v[14:17], v[190:193], v[122:125]
	v_mfma_i32_16x16x64_i8 v[166:169], v[18:21], v[98:101], 0
	v_mfma_i32_16x16x64_i8 v[98:101], v[26:29], v[98:101], 0
	v_mfma_i32_16x16x64_i8 v[166:169], v[22:25], v[102:105], v[166:169]
	v_mfma_i32_16x16x64_i8 v[98:101], v[30:33], v[102:105], v[98:101]
	v_mfma_i32_16x16x64_i8 v[102:105], v[18:21], v[106:109], 0
	v_mfma_i32_16x16x64_i8 v[106:109], v[26:29], v[106:109], 0
	v_mfma_i32_16x16x64_i8 v[130:133], v[26:29], v[178:181], 0
	v_mfma_i32_16x16x64_i8 v[118:121], v[18:21], v[186:189], 0
	v_mfma_i32_16x16x64_i8 v[114:117], v[26:29], v[186:189], 0
	v_mfma_i32_16x16x64_i8 v[102:105], v[22:25], v[110:113], v[102:105]
	v_mfma_i32_16x16x64_i8 v[106:109], v[30:33], v[110:113], v[106:109]
	v_mfma_i32_16x16x64_i8 v[110:113], v[18:21], v[178:181], 0
	v_mfma_i32_16x16x64_i8 v[130:133], v[30:33], v[182:185], v[130:133]
	v_mfma_i32_16x16x64_i8 v[118:121], v[22:25], v[190:193], v[118:121]
	v_mfma_i32_16x16x64_i8 v[114:117], v[30:33], v[190:193], v[114:117]
	s_setprio 3
	s_barrier
	v_mfma_i32_16x16x64_i8 v[110:113], v[22:25], v[182:185], v[110:113]
	s_setprio 0
	s_add_i32 s81, s70, s41
	v_lshl_add_u64 v[226:227], s[6:7], 0, v[196:197]
	s_mov_b32 m0, s81
	ds_read_b128 v[134:137], v236 offset:16384
	ds_read_b128 v[146:149], v236 offset:17408
	ds_read_b128 v[150:153], v236 offset:18432
	ds_read_b128 v[162:165], v236 offset:19456
	ds_read_b128 v[178:181], v236 offset:20480
	ds_read_b128 v[182:185], v236 offset:21504
	ds_read_b128 v[186:189], v236 offset:22528
	ds_read_b128 v[190:193], v236 offset:23552
	global_load_lds_dwordx4 v[226:227], off
	s_add_i32 m0, s81, 0x2000
	s_add_u32 s82, s6, 0x80000
	v_lshl_add_u64 v[244:245], s[6:7], 0, v[198:199]
	s_addc_u32 s83, s7, 0
	s_add_i32 s81, s71, s41
	global_load_lds_dwordx4 v[244:245], off
	v_lshl_add_u64 v[214:215], s[82:83], 0, v[196:197]
	s_mov_b32 m0, s81
	v_lshl_add_u64 v[246:247], s[8:9], 0, v[196:197]
	global_load_lds_dwordx4 v[214:215], off
	v_lshl_add_u64 v[214:215], s[82:83], 0, v[198:199]
	s_add_i32 m0, s81, 0x2000
	v_lshl_add_u64 v[248:249], s[8:9], 0, v[198:199]
	global_load_lds_dwordx4 v[214:215], off
	s_mov_b32 m0, s43
	s_nop 0
	global_load_lds_dwordx4 v[246:247], off
	s_mov_b32 m0, s57
	s_nop 0
	global_load_lds_dwordx4 v[248:249], off
	s_waitcnt vmcnt(8)
	s_waitcnt lgkmcnt(0)
	s_barrier
	s_waitcnt lgkmcnt(0)
	v_mfma_i32_16x16x64_i8 v[94:97], v[2:5], v[134:137], 0
	v_mfma_i32_16x16x64_i8 v[90:93], v[10:13], v[134:137], 0
	v_mfma_i32_16x16x64_i8 v[78:81], v[2:5], v[150:153], 0
	v_mfma_i32_16x16x64_i8 v[74:77], v[10:13], v[150:153], 0
	v_mfma_i32_16x16x64_i8 v[62:65], v[2:5], v[178:181], 0
	v_mfma_i32_16x16x64_i8 v[58:61], v[10:13], v[178:181], 0
	v_mfma_i32_16x16x64_i8 v[2:5], v[2:5], v[186:189], 0
	v_mfma_i32_16x16x64_i8 v[94:97], v[6:9], v[146:149], v[94:97]
	v_mfma_i32_16x16x64_i8 v[90:93], v[14:17], v[146:149], v[90:93]
	v_mfma_i32_16x16x64_i8 v[78:81], v[6:9], v[162:165], v[78:81]
	v_mfma_i32_16x16x64_i8 v[74:77], v[14:17], v[162:165], v[74:77]
	v_mfma_i32_16x16x64_i8 v[62:65], v[6:9], v[182:185], v[62:65]
	v_mfma_i32_16x16x64_i8 v[58:61], v[14:17], v[182:185], v[58:61]
	v_mfma_i32_16x16x64_i8 v[2:5], v[6:9], v[190:193], v[2:5]
	v_mfma_i32_16x16x64_i8 v[6:9], v[10:13], v[186:189], 0
	v_mfma_i32_16x16x64_i8 v[6:9], v[14:17], v[190:193], v[6:9]
	v_mfma_i32_16x16x64_i8 v[42:45], v[18:21], v[150:153], 0
	v_mfma_i32_16x16x64_i8 v[70:73], v[22:25], v[162:165], v[42:45]
	v_mfma_i32_16x16x64_i8 v[42:45], v[26:29], v[150:153], 0
	v_mfma_i32_16x16x64_i8 v[66:69], v[30:33], v[162:165], v[42:45]
	v_mfma_i32_16x16x64_i8 v[42:45], v[18:21], v[178:181], 0
	v_mfma_i32_16x16x64_i8 v[10:13], v[18:21], v[134:137], 0
	v_mfma_i32_16x16x64_i8 v[54:57], v[22:25], v[182:185], v[42:45]
	v_mfma_i32_16x16x64_i8 v[42:45], v[26:29], v[178:181], 0
	v_mfma_i32_16x16x64_i8 v[18:21], v[18:21], v[186:189], 0
	v_mfma_i32_16x16x64_i8 v[10:13], v[22:25], v[146:149], v[10:13]
	v_mfma_i32_16x16x64_i8 v[14:17], v[26:29], v[134:137], 0
	v_mfma_i32_16x16x64_i8 v[50:53], v[30:33], v[182:185], v[42:45]
	v_mfma_i32_16x16x64_i8 v[18:21], v[22:25], v[190:193], v[18:21]
	v_mfma_i32_16x16x64_i8 v[22:25], v[26:29], v[186:189], 0
	v_mfma_i32_16x16x64_i8 v[14:17], v[30:33], v[146:149], v[14:17]
	s_setprio 3
	s_barrier
	v_mfma_i32_16x16x64_i8 v[22:25], v[30:33], v[190:193], v[22:25]
	s_setprio 0
	s_add_i32 s81, 0, 0x18000
	s_add_i32 s82, 0, 0x1c000
	v_add_u32_e32 v38, s81, v229
	v_add_u32_e32 v42, s82, v229
	ds_read_b128 v[26:29], v38
	ds_read_b128 v[30:33], v38 offset:1024
	ds_read_b128 v[34:37], v38 offset:2048
	ds_read_b128 v[38:41], v38 offset:3072
	ds_read_b128 v[178:181], v42
	ds_read_b128 v[182:185], v42 offset:1024
	ds_read_b128 v[186:189], v42 offset:2048
	ds_read_b128 v[190:193], v42 offset:3072
	s_add_u32 s8, s8, 0x80000
	s_addc_u32 s9, s9, 0
	s_mov_b32 m0, s60
	v_lshl_add_u64 v[134:135], s[8:9], 0, v[196:197]
	ds_read_b128 v[42:45], v236 offset:32768
	ds_read_b128 v[46:49], v236 offset:33792
	ds_read_b128 v[82:85], v236 offset:34816
	ds_read_b128 v[86:89], v236 offset:35840
	ds_read_b128 v[214:217], v236 offset:36864
	ds_read_b128 v[218:221], v236 offset:37888
	ds_read_b128 v[222:225], v236 offset:38912
	ds_read_b128 v[240:243], v236 offset:39936
	global_load_lds_dwordx4 v[134:135], off
	v_lshl_add_u64 v[134:135], s[8:9], 0, v[198:199]
	s_mov_b32 m0, s61
	s_nop 0
	global_load_lds_dwordx4 v[134:135], off
	s_waitcnt vmcnt(8)
	s_waitcnt lgkmcnt(0)
	s_barrier
	s_waitcnt lgkmcnt(0)
	v_mfma_i32_16x16x64_i8 v[134:137], v[26:29], v[42:45], v[174:177]
	v_mfma_i32_16x16x64_i8 v[174:177], v[30:33], v[46:49], v[134:137]
	v_mfma_i32_16x16x64_i8 v[134:137], v[34:37], v[42:45], v[170:173]
	v_mfma_i32_16x16x64_i8 v[170:173], v[38:41], v[46:49], v[134:137]
	v_mfma_i32_16x16x64_i8 v[134:137], v[26:29], v[82:85], v[158:161]
	v_mfma_i32_16x16x64_i8 v[158:161], v[30:33], v[86:89], v[134:137]
	v_mfma_i32_16x16x64_i8 v[134:137], v[34:37], v[82:85], v[154:157]
	v_mfma_i32_16x16x64_i8 v[154:157], v[38:41], v[86:89], v[134:137]
	v_mfma_i32_16x16x64_i8 v[134:137], v[26:29], v[214:217], v[142:145]
	v_mfma_i32_16x16x64_i8 v[142:145], v[30:33], v[218:221], v[134:137]
	v_mfma_i32_16x16x64_i8 v[134:137], v[34:37], v[214:217], v[138:141]
	v_mfma_i32_16x16x64_i8 v[126:129], v[26:29], v[222:225], v[126:129]
	v_mfma_i32_16x16x64_i8 v[122:125], v[34:37], v[222:225], v[122:125]
	v_mfma_i32_16x16x64_i8 v[138:141], v[38:41], v[218:221], v[134:137]
	v_mfma_i32_16x16x64_i8 v[126:129], v[30:33], v[240:243], v[126:129]
	v_mfma_i32_16x16x64_i8 v[122:125], v[38:41], v[240:243], v[122:125]
	v_mfma_i32_16x16x64_i8 v[134:137], v[178:181], v[42:45], v[166:169]
	v_mfma_i32_16x16x64_i8 v[42:45], v[186:189], v[42:45], v[98:101]
	v_mfma_i32_16x16x64_i8 v[162:165], v[190:193], v[46:49], v[42:45]
	v_mfma_i32_16x16x64_i8 v[42:45], v[178:181], v[82:85], v[102:105]
	v_mfma_i32_16x16x64_i8 v[150:153], v[182:185], v[86:89], v[42:45]
	v_mfma_i32_16x16x64_i8 v[42:45], v[186:189], v[82:85], v[106:109]
	v_mfma_i32_16x16x64_i8 v[146:149], v[190:193], v[86:89], v[42:45]
	v_mfma_i32_16x16x64_i8 v[42:45], v[178:181], v[214:217], v[110:113]
	v_mfma_i32_16x16x64_i8 v[166:169], v[182:185], v[46:49], v[134:137]
	v_mfma_i32_16x16x64_i8 v[134:137], v[182:185], v[218:221], v[42:45]
	v_mfma_i32_16x16x64_i8 v[42:45], v[186:189], v[214:217], v[130:133]
	v_mfma_i32_16x16x64_i8 v[130:133], v[190:193], v[218:221], v[42:45]
	v_mfma_i32_16x16x64_i8 v[42:45], v[178:181], v[222:225], v[118:121]
	v_mfma_i32_16x16x64_i8 v[118:121], v[182:185], v[240:243], v[42:45]
	v_mfma_i32_16x16x64_i8 v[42:45], v[186:189], v[222:225], v[114:117]
	s_setprio 3
	s_barrier
	v_mfma_i32_16x16x64_i8 v[114:117], v[190:193], v[240:243], v[42:45]
	s_setprio 0
	s_add_i32 s8, s81, s41
	s_nop 3
	v_lshl_add_u64 v[42:43], v[226:227], 0, s[24:25]
	s_mov_b32 m0, s8
	ds_read_b128 v[82:85], v236 offset:49152
	ds_read_b128 v[98:101], v236 offset:50176
	ds_read_b128 v[102:105], v236 offset:51200
	ds_read_b128 v[106:109], v236 offset:52224
	ds_read_b128 v[110:113], v236 offset:53248
	ds_read_b128 v[214:217], v236 offset:54272
	ds_read_b128 v[218:221], v236 offset:55296
	ds_read_b128 v[222:225], v236 offset:56320
	global_load_lds_dwordx4 v[42:43], off
	s_add_i32 m0, s8, 0x2000
	s_add_u32 s6, s6, 0x80080
	v_lshl_add_u64 v[42:43], v[244:245], 0, s[24:25]
	s_addc_u32 s7, s7, 0
	s_add_i32 s8, s82, s41
	global_load_lds_dwordx4 v[42:43], off
	v_lshl_add_u64 v[42:43], s[6:7], 0, v[196:197]
	s_mov_b32 m0, s8
	s_nop 0
	global_load_lds_dwordx4 v[42:43], off
	v_lshl_add_u64 v[42:43], s[6:7], 0, v[198:199]
	s_add_i32 m0, s8, 0x2000
	s_nop 0
	global_load_lds_dwordx4 v[42:43], off
	v_lshl_add_u64 v[42:43], v[246:247], 0, s[24:25]
	s_mov_b32 m0, s63
	s_nop 0
	global_load_lds_dwordx4 v[42:43], off
	v_lshl_add_u64 v[42:43], v[248:249], 0, s[24:25]
	s_mov_b32 m0, s64
	s_nop 0
	global_load_lds_dwordx4 v[42:43], off
	s_waitcnt vmcnt(8)
	s_waitcnt lgkmcnt(0)
	s_barrier
	s_waitcnt lgkmcnt(0)
	v_mfma_i32_16x16x64_i8 v[42:45], v[26:29], v[82:85], v[94:97]
	v_mfma_i32_16x16x64_i8 v[94:97], v[30:33], v[98:101], v[42:45]
	v_mfma_i32_16x16x64_i8 v[42:45], v[34:37], v[82:85], v[90:93]
	v_mfma_i32_16x16x64_i8 v[90:93], v[38:41], v[98:101], v[42:45]
	v_mfma_i32_16x16x64_i8 v[42:45], v[26:29], v[102:105], v[78:81]
	v_mfma_i32_16x16x64_i8 v[78:81], v[30:33], v[106:109], v[42:45]
	v_mfma_i32_16x16x64_i8 v[42:45], v[34:37], v[102:105], v[74:77]
	v_mfma_i32_16x16x64_i8 v[74:77], v[38:41], v[106:109], v[42:45]
	v_mfma_i32_16x16x64_i8 v[42:45], v[26:29], v[110:113], v[62:65]
	v_mfma_i32_16x16x64_i8 v[2:5], v[26:29], v[218:221], v[2:5]
	v_mfma_i32_16x16x64_i8 v[62:65], v[30:33], v[214:217], v[42:45]
	v_mfma_i32_16x16x64_i8 v[42:45], v[34:37], v[110:113], v[58:61]
	v_mfma_i32_16x16x64_i8 v[46:49], v[30:33], v[222:225], v[2:5]
	v_mfma_i32_16x16x64_i8 v[2:5], v[34:37], v[218:221], v[6:9]
	v_mfma_i32_16x16x64_i8 v[58:61], v[38:41], v[214:217], v[42:45]
	v_mfma_i32_16x16x64_i8 v[42:45], v[38:41], v[222:225], v[2:5]
	v_mfma_i32_16x16x64_i8 v[2:5], v[178:181], v[82:85], v[10:13]
	v_mfma_i32_16x16x64_i8 v[86:89], v[182:185], v[98:101], v[2:5]
	v_mfma_i32_16x16x64_i8 v[2:5], v[186:189], v[82:85], v[14:17]
	v_mfma_i32_16x16x64_i8 v[82:85], v[190:193], v[98:101], v[2:5]
	v_mfma_i32_16x16x64_i8 v[2:5], v[178:181], v[102:105], v[70:73]
	v_mfma_i32_16x16x64_i8 v[70:73], v[182:185], v[106:109], v[2:5]
	v_mfma_i32_16x16x64_i8 v[2:5], v[186:189], v[102:105], v[66:69]
	v_mfma_i32_16x16x64_i8 v[66:69], v[190:193], v[106:109], v[2:5]
	v_mfma_i32_16x16x64_i8 v[2:5], v[178:181], v[110:113], v[54:57]
	v_mfma_i32_16x16x64_i8 v[54:57], v[182:185], v[214:217], v[2:5]
	v_mfma_i32_16x16x64_i8 v[2:5], v[186:189], v[110:113], v[50:53]
	v_mfma_i32_16x16x64_i8 v[50:53], v[190:193], v[214:217], v[2:5]
	v_mfma_i32_16x16x64_i8 v[2:5], v[178:181], v[218:221], v[18:21]
	v_mfma_i32_16x16x64_i8 v[38:41], v[182:185], v[222:225], v[2:5]
	v_mfma_i32_16x16x64_i8 v[2:5], v[186:189], v[218:221], v[22:25]
	s_setprio 3
	s_barrier
	v_mfma_i32_16x16x64_i8 v[34:37], v[190:193], v[222:225], v[2:5]
	s_setprio 0
	s_add_i32 s80, s80, 2
	s_add_u32 s4, s4, 0x100
	s_addc_u32 s5, s5, 0
	s_add_u32 s78, s78, 0x100
	s_addc_u32 s79, s79, 0
	s_cmp_gt_u32 s80, 29
.LBB0_304:
	s_waitcnt lgkmcnt(0)
	ds_read_b128 v[2:5], v234
	ds_read_b128 v[6:9], v234 offset:1024
	ds_read_b128 v[10:13], v234 offset:2048
	ds_read_b128 v[14:17], v234 offset:3072
	ds_read_b128 v[18:21], v235
	ds_read_b128 v[22:25], v235 offset:1024
	ds_read_b128 v[26:29], v235 offset:2048
	ds_read_b128 v[30:33], v235 offset:3072
	s_add_u32 s6, s4, 0xfff80080
	s_addc_u32 s7, s5, -1
	s_cmp_eq_u32 s80, 28
	s_cselect_b32 s9, s35, s7
	s_cselect_b32 s8, s52, s6
	s_cselect_b32 s7, s31, s79
	s_cselect_b32 s6, s77, s78
	v_lshl_add_u64 v[214:215], s[4:5], 0, v[206:207]
	s_add_i32 m0, s43, 0xc000
	ds_read_b128 v[98:101], v236
	ds_read_b128 v[102:105], v236 offset:1024
	ds_read_b128 v[106:109], v236 offset:2048
	ds_read_b128 v[110:113], v236 offset:3072
	ds_read_b128 v[178:181], v236 offset:4096
	ds_read_b128 v[182:185], v236 offset:5120
	ds_read_b128 v[186:189], v236 offset:6144
	ds_read_b128 v[190:193], v236 offset:7168
	global_load_lds_dwordx4 v[214:215], off
	v_lshl_add_u64 v[214:215], s[4:5], 0, v[208:209]
	s_add_i32 m0, s43, 0xe000
	s_nop 0
	global_load_lds_dwordx4 v[214:215], off
	s_waitcnt vmcnt(8)
	s_waitcnt lgkmcnt(0)
	s_barrier
	s_waitcnt lgkmcnt(0)
	v_mfma_i32_16x16x64_i8 v[174:177], v[2:5], v[98:101], v[174:177]
	v_mfma_i32_16x16x64_i8 v[170:173], v[10:13], v[98:101], v[170:173]
	v_mfma_i32_16x16x64_i8 v[158:161], v[2:5], v[106:109], v[158:161]
	v_mfma_i32_16x16x64_i8 v[154:157], v[10:13], v[106:109], v[154:157]
	v_mfma_i32_16x16x64_i8 v[142:145], v[2:5], v[178:181], v[142:145]
	v_mfma_i32_16x16x64_i8 v[138:141], v[10:13], v[178:181], v[138:141]
	v_mfma_i32_16x16x64_i8 v[126:129], v[2:5], v[186:189], v[126:129]
	v_mfma_i32_16x16x64_i8 v[122:125], v[10:13], v[186:189], v[122:125]
	v_mfma_i32_16x16x64_i8 v[174:177], v[6:9], v[102:105], v[174:177]
	v_mfma_i32_16x16x64_i8 v[170:173], v[14:17], v[102:105], v[170:173]
	v_mfma_i32_16x16x64_i8 v[158:161], v[6:9], v[110:113], v[158:161]
	v_mfma_i32_16x16x64_i8 v[154:157], v[14:17], v[110:113], v[154:157]
	v_mfma_i32_16x16x64_i8 v[142:145], v[6:9], v[182:185], v[142:145]
	v_mfma_i32_16x16x64_i8 v[138:141], v[14:17], v[182:185], v[138:141]
	v_mfma_i32_16x16x64_i8 v[126:129], v[6:9], v[190:193], v[126:129]
	v_mfma_i32_16x16x64_i8 v[122:125], v[14:17], v[190:193], v[122:125]
	v_mfma_i32_16x16x64_i8 v[166:169], v[18:21], v[98:101], v[166:169]
	v_mfma_i32_16x16x64_i8 v[98:101], v[26:29], v[98:101], v[162:165]
	v_mfma_i32_16x16x64_i8 v[166:169], v[22:25], v[102:105], v[166:169]
	v_mfma_i32_16x16x64_i8 v[98:101], v[30:33], v[102:105], v[98:101]
	v_mfma_i32_16x16x64_i8 v[102:105], v[18:21], v[106:109], v[150:153]
	v_mfma_i32_16x16x64_i8 v[106:109], v[26:29], v[106:109], v[146:149]
	v_mfma_i32_16x16x64_i8 v[130:133], v[26:29], v[178:181], v[130:133]
	v_mfma_i32_16x16x64_i8 v[118:121], v[18:21], v[186:189], v[118:121]
	v_mfma_i32_16x16x64_i8 v[114:117], v[26:29], v[186:189], v[114:117]
	v_mfma_i32_16x16x64_i8 v[102:105], v[22:25], v[110:113], v[102:105]
	v_mfma_i32_16x16x64_i8 v[106:109], v[30:33], v[110:113], v[106:109]
	v_mfma_i32_16x16x64_i8 v[110:113], v[18:21], v[178:181], v[134:137]
	v_mfma_i32_16x16x64_i8 v[130:133], v[30:33], v[182:185], v[130:133]
	v_mfma_i32_16x16x64_i8 v[118:121], v[22:25], v[190:193], v[118:121]
	v_mfma_i32_16x16x64_i8 v[114:117], v[30:33], v[190:193], v[114:117]
	s_setprio 3
	s_barrier
	v_mfma_i32_16x16x64_i8 v[110:113], v[22:25], v[182:185], v[110:113]
	s_setprio 0
	s_add_i32 s81, s70, s41
	v_lshl_add_u64 v[226:227], s[6:7], 0, v[196:197]
	s_mov_b32 m0, s81
	ds_read_b128 v[134:137], v236 offset:16384
	ds_read_b128 v[146:149], v236 offset:17408
	ds_read_b128 v[150:153], v236 offset:18432
	ds_read_b128 v[162:165], v236 offset:19456
	ds_read_b128 v[178:181], v236 offset:20480
	ds_read_b128 v[182:185], v236 offset:21504
	ds_read_b128 v[186:189], v236 offset:22528
	ds_read_b128 v[190:193], v236 offset:23552
	global_load_lds_dwordx4 v[226:227], off
	s_add_i32 m0, s81, 0x2000
	s_add_u32 s82, s6, 0x80000
	v_lshl_add_u64 v[244:245], s[6:7], 0, v[198:199]
	s_addc_u32 s83, s7, 0
	s_add_i32 s81, s71, s41
	global_load_lds_dwordx4 v[244:245], off
	v_lshl_add_u64 v[214:215], s[82:83], 0, v[196:197]
	s_mov_b32 m0, s81
	v_lshl_add_u64 v[246:247], s[8:9], 0, v[196:197]
	global_load_lds_dwordx4 v[214:215], off
	v_lshl_add_u64 v[214:215], s[82:83], 0, v[198:199]
	s_add_i32 m0, s81, 0x2000
	v_lshl_add_u64 v[248:249], s[8:9], 0, v[198:199]
	global_load_lds_dwordx4 v[214:215], off
	s_mov_b32 m0, s43
	s_nop 0
	global_load_lds_dwordx4 v[246:247], off
	s_mov_b32 m0, s57
	s_nop 0
	global_load_lds_dwordx4 v[248:249], off
	s_waitcnt vmcnt(8)
	s_waitcnt lgkmcnt(0)
	s_barrier
	s_waitcnt lgkmcnt(0)
	v_mfma_i32_16x16x64_i8 v[94:97], v[2:5], v[134:137], v[94:97]
	v_mfma_i32_16x16x64_i8 v[90:93], v[10:13], v[134:137], v[90:93]
	v_mfma_i32_16x16x64_i8 v[78:81], v[2:5], v[150:153], v[78:81]
	v_mfma_i32_16x16x64_i8 v[74:77], v[10:13], v[150:153], v[74:77]
	v_mfma_i32_16x16x64_i8 v[62:65], v[2:5], v[178:181], v[62:65]
	v_mfma_i32_16x16x64_i8 v[58:61], v[10:13], v[178:181], v[58:61]
	v_mfma_i32_16x16x64_i8 v[2:5], v[2:5], v[186:189], v[46:49]
	v_mfma_i32_16x16x64_i8 v[94:97], v[6:9], v[146:149], v[94:97]
	v_mfma_i32_16x16x64_i8 v[90:93], v[14:17], v[146:149], v[90:93]
	v_mfma_i32_16x16x64_i8 v[78:81], v[6:9], v[162:165], v[78:81]
	v_mfma_i32_16x16x64_i8 v[74:77], v[14:17], v[162:165], v[74:77]
	v_mfma_i32_16x16x64_i8 v[62:65], v[6:9], v[182:185], v[62:65]
	v_mfma_i32_16x16x64_i8 v[58:61], v[14:17], v[182:185], v[58:61]
	v_mfma_i32_16x16x64_i8 v[2:5], v[6:9], v[190:193], v[2:5]
	v_mfma_i32_16x16x64_i8 v[6:9], v[10:13], v[186:189], v[42:45]
	v_mfma_i32_16x16x64_i8 v[6:9], v[14:17], v[190:193], v[6:9]
	v_mfma_i32_16x16x64_i8 v[42:45], v[18:21], v[150:153], v[70:73]
	v_mfma_i32_16x16x64_i8 v[70:73], v[22:25], v[162:165], v[42:45]
	v_mfma_i32_16x16x64_i8 v[42:45], v[26:29], v[150:153], v[66:69]
	v_mfma_i32_16x16x64_i8 v[66:69], v[30:33], v[162:165], v[42:45]
	v_mfma_i32_16x16x64_i8 v[42:45], v[18:21], v[178:181], v[54:57]
	v_mfma_i32_16x16x64_i8 v[10:13], v[18:21], v[134:137], v[86:89]
	v_mfma_i32_16x16x64_i8 v[54:57], v[22:25], v[182:185], v[42:45]
	v_mfma_i32_16x16x64_i8 v[42:45], v[26:29], v[178:181], v[50:53]
	v_mfma_i32_16x16x64_i8 v[18:21], v[18:21], v[186:189], v[38:41]
	v_mfma_i32_16x16x64_i8 v[10:13], v[22:25], v[146:149], v[10:13]
	v_mfma_i32_16x16x64_i8 v[14:17], v[26:29], v[134:137], v[82:85]
	v_mfma_i32_16x16x64_i8 v[50:53], v[30:33], v[182:185], v[42:45]
	v_mfma_i32_16x16x64_i8 v[18:21], v[22:25], v[190:193], v[18:21]
	v_mfma_i32_16x16x64_i8 v[22:25], v[26:29], v[186:189], v[34:37]
	v_mfma_i32_16x16x64_i8 v[14:17], v[30:33], v[146:149], v[14:17]
	s_setprio 3
	s_barrier
	v_mfma_i32_16x16x64_i8 v[22:25], v[30:33], v[190:193], v[22:25]
	s_setprio 0
	s_add_i32 s81, 0, 0x18000
	s_add_i32 s82, 0, 0x1c000
	v_add_u32_e32 v38, s81, v229
	v_add_u32_e32 v42, s82, v229
	ds_read_b128 v[26:29], v38
	ds_read_b128 v[30:33], v38 offset:1024
	ds_read_b128 v[34:37], v38 offset:2048
	ds_read_b128 v[38:41], v38 offset:3072
	ds_read_b128 v[178:181], v42
	ds_read_b128 v[182:185], v42 offset:1024
	ds_read_b128 v[186:189], v42 offset:2048
	ds_read_b128 v[190:193], v42 offset:3072
	s_add_u32 s8, s8, 0x80000
	s_addc_u32 s9, s9, 0
	s_mov_b32 m0, s60
	v_lshl_add_u64 v[134:135], s[8:9], 0, v[196:197]
	ds_read_b128 v[42:45], v236 offset:32768
	ds_read_b128 v[46:49], v236 offset:33792
	ds_read_b128 v[82:85], v236 offset:34816
	ds_read_b128 v[86:89], v236 offset:35840
	ds_read_b128 v[214:217], v236 offset:36864
	ds_read_b128 v[218:221], v236 offset:37888
	ds_read_b128 v[222:225], v236 offset:38912
	ds_read_b128 v[240:243], v236 offset:39936
	global_load_lds_dwordx4 v[134:135], off
	v_lshl_add_u64 v[134:135], s[8:9], 0, v[198:199]
	s_mov_b32 m0, s61
	s_nop 0
	global_load_lds_dwordx4 v[134:135], off
	s_waitcnt vmcnt(8)
	s_waitcnt lgkmcnt(0)
	s_barrier
	s_waitcnt lgkmcnt(0)
	v_mfma_i32_16x16x64_i8 v[134:137], v[26:29], v[42:45], v[174:177]
	v_mfma_i32_16x16x64_i8 v[174:177], v[30:33], v[46:49], v[134:137]
	v_mfma_i32_16x16x64_i8 v[134:137], v[34:37], v[42:45], v[170:173]
	v_mfma_i32_16x16x64_i8 v[170:173], v[38:41], v[46:49], v[134:137]
	v_mfma_i32_16x16x64_i8 v[134:137], v[26:29], v[82:85], v[158:161]
	v_mfma_i32_16x16x64_i8 v[158:161], v[30:33], v[86:89], v[134:137]
	v_mfma_i32_16x16x64_i8 v[134:137], v[34:37], v[82:85], v[154:157]
	v_mfma_i32_16x16x64_i8 v[154:157], v[38:41], v[86:89], v[134:137]
	v_mfma_i32_16x16x64_i8 v[134:137], v[26:29], v[214:217], v[142:145]
	v_mfma_i32_16x16x64_i8 v[142:145], v[30:33], v[218:221], v[134:137]
	v_mfma_i32_16x16x64_i8 v[134:137], v[34:37], v[214:217], v[138:141]
	v_mfma_i32_16x16x64_i8 v[126:129], v[26:29], v[222:225], v[126:129]
	v_mfma_i32_16x16x64_i8 v[122:125], v[34:37], v[222:225], v[122:125]
	v_mfma_i32_16x16x64_i8 v[138:141], v[38:41], v[218:221], v[134:137]
	v_mfma_i32_16x16x64_i8 v[126:129], v[30:33], v[240:243], v[126:129]
	v_mfma_i32_16x16x64_i8 v[122:125], v[38:41], v[240:243], v[122:125]
	v_mfma_i32_16x16x64_i8 v[134:137], v[178:181], v[42:45], v[166:169]
	v_mfma_i32_16x16x64_i8 v[42:45], v[186:189], v[42:45], v[98:101]
	v_mfma_i32_16x16x64_i8 v[162:165], v[190:193], v[46:49], v[42:45]
	v_mfma_i32_16x16x64_i8 v[42:45], v[178:181], v[82:85], v[102:105]
	v_mfma_i32_16x16x64_i8 v[150:153], v[182:185], v[86:89], v[42:45]
	v_mfma_i32_16x16x64_i8 v[42:45], v[186:189], v[82:85], v[106:109]
	v_mfma_i32_16x16x64_i8 v[146:149], v[190:193], v[86:89], v[42:45]
	v_mfma_i32_16x16x64_i8 v[42:45], v[178:181], v[214:217], v[110:113]
	v_mfma_i32_16x16x64_i8 v[166:169], v[182:185], v[46:49], v[134:137]
	v_mfma_i32_16x16x64_i8 v[134:137], v[182:185], v[218:221], v[42:45]
	v_mfma_i32_16x16x64_i8 v[42:45], v[186:189], v[214:217], v[130:133]
	v_mfma_i32_16x16x64_i8 v[130:133], v[190:193], v[218:221], v[42:45]
	v_mfma_i32_16x16x64_i8 v[42:45], v[178:181], v[222:225], v[118:121]
	v_mfma_i32_16x16x64_i8 v[118:121], v[182:185], v[240:243], v[42:45]
	v_mfma_i32_16x16x64_i8 v[42:45], v[186:189], v[222:225], v[114:117]
	s_setprio 3
	s_barrier
	v_mfma_i32_16x16x64_i8 v[114:117], v[190:193], v[240:243], v[42:45]
	s_setprio 0
	s_add_i32 s8, s81, s41
	s_nop 3
	v_lshl_add_u64 v[42:43], v[226:227], 0, s[24:25]
	s_mov_b32 m0, s8
	ds_read_b128 v[82:85], v236 offset:49152
	ds_read_b128 v[98:101], v236 offset:50176
	ds_read_b128 v[102:105], v236 offset:51200
	ds_read_b128 v[106:109], v236 offset:52224
	ds_read_b128 v[110:113], v236 offset:53248
	ds_read_b128 v[214:217], v236 offset:54272
	ds_read_b128 v[218:221], v236 offset:55296
	ds_read_b128 v[222:225], v236 offset:56320
	global_load_lds_dwordx4 v[42:43], off
	s_add_i32 m0, s8, 0x2000
	s_add_u32 s6, s6, 0x80080
	v_lshl_add_u64 v[42:43], v[244:245], 0, s[24:25]
	s_addc_u32 s7, s7, 0
	s_add_i32 s8, s82, s41
	global_load_lds_dwordx4 v[42:43], off
	v_lshl_add_u64 v[42:43], s[6:7], 0, v[196:197]
	s_mov_b32 m0, s8
	s_nop 0
	global_load_lds_dwordx4 v[42:43], off
	v_lshl_add_u64 v[42:43], s[6:7], 0, v[198:199]
	s_add_i32 m0, s8, 0x2000
	s_nop 0
	global_load_lds_dwordx4 v[42:43], off
	v_lshl_add_u64 v[42:43], v[246:247], 0, s[24:25]
	s_mov_b32 m0, s63
	s_nop 0
	global_load_lds_dwordx4 v[42:43], off
	v_lshl_add_u64 v[42:43], v[248:249], 0, s[24:25]
	s_mov_b32 m0, s64
	s_nop 0
	global_load_lds_dwordx4 v[42:43], off
	s_waitcnt vmcnt(8)
	s_waitcnt lgkmcnt(0)
	s_barrier
	s_waitcnt lgkmcnt(0)
	v_mfma_i32_16x16x64_i8 v[42:45], v[26:29], v[82:85], v[94:97]
	v_mfma_i32_16x16x64_i8 v[94:97], v[30:33], v[98:101], v[42:45]
	v_mfma_i32_16x16x64_i8 v[42:45], v[34:37], v[82:85], v[90:93]
	v_mfma_i32_16x16x64_i8 v[90:93], v[38:41], v[98:101], v[42:45]
	v_mfma_i32_16x16x64_i8 v[42:45], v[26:29], v[102:105], v[78:81]
	v_mfma_i32_16x16x64_i8 v[78:81], v[30:33], v[106:109], v[42:45]
	v_mfma_i32_16x16x64_i8 v[42:45], v[34:37], v[102:105], v[74:77]
	v_mfma_i32_16x16x64_i8 v[74:77], v[38:41], v[106:109], v[42:45]
	v_mfma_i32_16x16x64_i8 v[42:45], v[26:29], v[110:113], v[62:65]
	v_mfma_i32_16x16x64_i8 v[2:5], v[26:29], v[218:221], v[2:5]
	v_mfma_i32_16x16x64_i8 v[62:65], v[30:33], v[214:217], v[42:45]
	v_mfma_i32_16x16x64_i8 v[42:45], v[34:37], v[110:113], v[58:61]
	v_mfma_i32_16x16x64_i8 v[46:49], v[30:33], v[222:225], v[2:5]
	v_mfma_i32_16x16x64_i8 v[2:5], v[34:37], v[218:221], v[6:9]
	v_mfma_i32_16x16x64_i8 v[58:61], v[38:41], v[214:217], v[42:45]
	v_mfma_i32_16x16x64_i8 v[42:45], v[38:41], v[222:225], v[2:5]
	v_mfma_i32_16x16x64_i8 v[2:5], v[178:181], v[82:85], v[10:13]
	v_mfma_i32_16x16x64_i8 v[86:89], v[182:185], v[98:101], v[2:5]
	v_mfma_i32_16x16x64_i8 v[2:5], v[186:189], v[82:85], v[14:17]
	v_mfma_i32_16x16x64_i8 v[82:85], v[190:193], v[98:101], v[2:5]
	v_mfma_i32_16x16x64_i8 v[2:5], v[178:181], v[102:105], v[70:73]
	v_mfma_i32_16x16x64_i8 v[70:73], v[182:185], v[106:109], v[2:5]
	v_mfma_i32_16x16x64_i8 v[2:5], v[186:189], v[102:105], v[66:69]
	v_mfma_i32_16x16x64_i8 v[66:69], v[190:193], v[106:109], v[2:5]
	v_mfma_i32_16x16x64_i8 v[2:5], v[178:181], v[110:113], v[54:57]
	v_mfma_i32_16x16x64_i8 v[54:57], v[182:185], v[214:217], v[2:5]
	v_mfma_i32_16x16x64_i8 v[2:5], v[186:189], v[110:113], v[50:53]
	v_mfma_i32_16x16x64_i8 v[50:53], v[190:193], v[214:217], v[2:5]
	v_mfma_i32_16x16x64_i8 v[2:5], v[178:181], v[218:221], v[18:21]
	v_mfma_i32_16x16x64_i8 v[38:41], v[182:185], v[222:225], v[2:5]
	v_mfma_i32_16x16x64_i8 v[2:5], v[186:189], v[218:221], v[22:25]
	s_setprio 3
	s_barrier
	v_mfma_i32_16x16x64_i8 v[34:37], v[190:193], v[222:225], v[2:5]
	s_setprio 0
	s_add_i32 s80, s80, 2
	s_add_u32 s4, s4, 0x100
	s_addc_u32 s5, s5, 0
	s_add_u32 s78, s78, 0x100
	s_addc_u32 s79, s79, 0
	s_cmp_gt_u32 s80, 29
	s_cbranch_scc0 .LBB0_304
	s_and_b64 vcc, exec, s[12:13]
	s_cbranch_vccz .LBB0_307
	s_barrier

.LBB0_1231:
	s_ashr_i32 s23, s22, 31
	s_lshl_b64 s[24:25], s[22:23], 20
	s_add_u32 s24, s17, s24
	s_addc_u32 s25, s36, s25
	s_and_b64 s[26:27], s[0:1], exec
	s_cselect_b32 s23, s25, s29
	s_cselect_b32 s66, s24, s28
	s_ashr_i32 s15, s14, 31
	s_lshl_b64 s[26:27], s[14:15], 20
	s_add_u32 s26, s37, s26
	s_addc_u32 s27, s38, s27
	s_and_b64 s[34:35], s[0:1], exec
	s_cselect_b32 s15, s27, s31
	s_cselect_b32 s67, s26, s30
	s_add_u32 s28, s28, 0x80080
	s_addc_u32 s29, s29, 0
	s_add_u32 s68, s30, 0x100
	s_addc_u32 s69, s31, 0
	s_mov_b32 s70, -2
	ds_read_b128 v[106:109], v197
	ds_read_b128 v[114:117], v197 offset:1024
	ds_read_b128 v[122:125], v197 offset:2048
	ds_read_b128 v[130:133], v197 offset:3072
	ds_read_b128 v[146:149], v201
	ds_read_b128 v[150:153], v201 offset:1024
	ds_read_b128 v[154:157], v201 offset:2048
	ds_read_b128 v[158:161], v201 offset:3072
	s_add_u32 s30, s28, 0xfff80080
	s_addc_u32 s31, s29, -1
	s_cmp_eq_u32 s70, 28
	s_cselect_b32 s35, s23, s31
	s_cselect_b32 s34, s66, s30
	s_cselect_b32 s31, s15, s69
	s_cselect_b32 s30, s67, s68
	v_lshl_add_u64 v[194:195], s[28:29], 0, v[174:175]
	s_add_i32 m0, s19, 0xc000
	ds_read_b128 v[162:165], v204
	ds_read_b128 v[182:185], v204 offset:1024
	ds_read_b128 v[186:189], v204 offset:2048
	ds_read_b128 v[206:209], v204 offset:3072
	ds_read_b128 v[210:213], v204 offset:4096
	ds_read_b128 v[214:217], v204 offset:5120
	ds_read_b128 v[218:221], v204 offset:6144
	ds_read_b128 v[222:225], v204 offset:7168
	global_load_lds_dwordx4 v[194:195], off
	v_lshl_add_u64 v[194:195], s[28:29], 0, v[176:177]
	s_add_i32 m0, s19, 0xe000
	s_nop 0
	global_load_lds_dwordx4 v[194:195], off
	s_waitcnt vmcnt(8)
	s_waitcnt lgkmcnt(0)
	s_barrier
	s_waitcnt lgkmcnt(0)
	v_mfma_i32_16x16x64_i8 v[142:145], v[106:109], v[162:165], 0
	v_mfma_i32_16x16x64_i8 v[138:141], v[122:125], v[162:165], 0
	v_mfma_i32_16x16x64_i8 v[118:121], v[106:109], v[186:189], 0
	v_mfma_i32_16x16x64_i8 v[110:113], v[122:125], v[186:189], 0
	v_mfma_i32_16x16x64_i8 v[94:97], v[106:109], v[210:213], 0
	v_mfma_i32_16x16x64_i8 v[90:93], v[122:125], v[210:213], 0
	v_mfma_i32_16x16x64_i8 v[78:81], v[106:109], v[218:221], 0
	v_mfma_i32_16x16x64_i8 v[74:77], v[122:125], v[218:221], 0
	v_mfma_i32_16x16x64_i8 v[142:145], v[114:117], v[182:185], v[142:145]
	v_mfma_i32_16x16x64_i8 v[138:141], v[130:133], v[182:185], v[138:141]
	v_mfma_i32_16x16x64_i8 v[118:121], v[114:117], v[206:209], v[118:121]
	v_mfma_i32_16x16x64_i8 v[110:113], v[130:133], v[206:209], v[110:113]
	v_mfma_i32_16x16x64_i8 v[94:97], v[114:117], v[214:217], v[94:97]
	v_mfma_i32_16x16x64_i8 v[90:93], v[130:133], v[214:217], v[90:93]
	v_mfma_i32_16x16x64_i8 v[78:81], v[114:117], v[222:225], v[78:81]
	v_mfma_i32_16x16x64_i8 v[74:77], v[130:133], v[222:225], v[74:77]
	v_mfma_i32_16x16x64_i8 v[134:137], v[146:149], v[162:165], 0
	v_mfma_i32_16x16x64_i8 v[126:129], v[154:157], v[162:165], 0
	v_mfma_i32_16x16x64_i8 v[102:105], v[146:149], v[186:189], 0
	v_mfma_i32_16x16x64_i8 v[98:101], v[154:157], v[186:189], 0
	v_mfma_i32_16x16x64_i8 v[86:89], v[146:149], v[210:213], 0
	v_mfma_i32_16x16x64_i8 v[82:85], v[154:157], v[210:213], 0
	v_mfma_i32_16x16x64_i8 v[70:73], v[146:149], v[218:221], 0
	v_mfma_i32_16x16x64_i8 v[66:69], v[154:157], v[218:221], 0
	v_mfma_i32_16x16x64_i8 v[134:137], v[150:153], v[182:185], v[134:137]
	v_mfma_i32_16x16x64_i8 v[126:129], v[158:161], v[182:185], v[126:129]
	v_mfma_i32_16x16x64_i8 v[102:105], v[150:153], v[206:209], v[102:105]
	v_mfma_i32_16x16x64_i8 v[98:101], v[158:161], v[206:209], v[98:101]
	v_mfma_i32_16x16x64_i8 v[86:89], v[150:153], v[214:217], v[86:89]
	v_mfma_i32_16x16x64_i8 v[82:85], v[158:161], v[214:217], v[82:85]
	v_mfma_i32_16x16x64_i8 v[70:73], v[150:153], v[222:225], v[70:73]
	s_setprio 3
	s_barrier
	v_mfma_i32_16x16x64_i8 v[66:69], v[158:161], v[222:225], v[66:69]
	s_setprio 0
	s_add_i32 s71, s63, s39
	v_lshl_add_u64 v[194:195], s[30:31], 0, v[168:169]
	s_mov_b32 m0, s71
	ds_read_b128 v[162:165], v204 offset:16384
	ds_read_b128 v[182:185], v204 offset:17408
	ds_read_b128 v[186:189], v204 offset:18432
	ds_read_b128 v[206:209], v204 offset:19456
	ds_read_b128 v[210:213], v204 offset:20480
	ds_read_b128 v[214:217], v204 offset:21504
	ds_read_b128 v[218:221], v204 offset:22528
	ds_read_b128 v[222:225], v204 offset:23552
	global_load_lds_dwordx4 v[194:195], off
	s_add_i32 m0, s71, 0x2000
	s_add_u32 s72, s30, 0x80000
	v_lshl_add_u64 v[198:199], s[30:31], 0, v[172:173]
	s_addc_u32 s73, s31, 0
	s_add_i32 s71, s64, s39
	global_load_lds_dwordx4 v[198:199], off
	v_lshl_add_u64 v[202:203], s[72:73], 0, v[168:169]
	s_mov_b32 m0, s71
	v_lshl_add_u64 v[226:227], s[34:35], 0, v[170:171]
	global_load_lds_dwordx4 v[202:203], off
	v_lshl_add_u64 v[202:203], s[72:73], 0, v[172:173]
	s_add_i32 m0, s71, 0x2000
	s_nop 0
	global_load_lds_dwordx4 v[202:203], off
	v_lshl_add_u64 v[202:203], s[34:35], 0, v[166:167]
	s_mov_b32 m0, s19
	s_nop 0
	global_load_lds_dwordx4 v[202:203], off
	s_mov_b32 m0, s40
	s_nop 0
	global_load_lds_dwordx4 v[226:227], off
	s_waitcnt vmcnt(8)
	s_waitcnt lgkmcnt(0)
	s_barrier
	s_waitcnt lgkmcnt(0)
	v_mfma_i32_16x16x64_i8 v[62:65], v[106:109], v[162:165], 0
	v_mfma_i32_16x16x64_i8 v[58:61], v[122:125], v[162:165], 0
	v_mfma_i32_16x16x64_i8 v[46:49], v[106:109], v[186:189], 0
	v_mfma_i32_16x16x64_i8 v[42:45], v[122:125], v[186:189], 0
	v_mfma_i32_16x16x64_i8 v[30:33], v[106:109], v[210:213], 0
	v_mfma_i32_16x16x64_i8 v[26:29], v[122:125], v[210:213], 0
	v_mfma_i32_16x16x64_i8 v[14:17], v[106:109], v[218:221], 0
	v_mfma_i32_16x16x64_i8 v[10:13], v[122:125], v[218:221], 0
	v_mfma_i32_16x16x64_i8 v[62:65], v[114:117], v[182:185], v[62:65]
	v_mfma_i32_16x16x64_i8 v[58:61], v[130:133], v[182:185], v[58:61]
	v_mfma_i32_16x16x64_i8 v[46:49], v[114:117], v[206:209], v[46:49]
	v_mfma_i32_16x16x64_i8 v[42:45], v[130:133], v[206:209], v[42:45]
	v_mfma_i32_16x16x64_i8 v[30:33], v[114:117], v[214:217], v[30:33]
	v_mfma_i32_16x16x64_i8 v[26:29], v[130:133], v[214:217], v[26:29]
	v_mfma_i32_16x16x64_i8 v[14:17], v[114:117], v[222:225], v[14:17]
	v_mfma_i32_16x16x64_i8 v[10:13], v[130:133], v[222:225], v[10:13]
	v_mfma_i32_16x16x64_i8 v[54:57], v[146:149], v[162:165], 0
	v_mfma_i32_16x16x64_i8 v[50:53], v[154:157], v[162:165], 0
	v_mfma_i32_16x16x64_i8 v[38:41], v[146:149], v[186:189], 0
	v_mfma_i32_16x16x64_i8 v[34:37], v[154:157], v[186:189], 0
	v_mfma_i32_16x16x64_i8 v[22:25], v[146:149], v[210:213], 0
	v_mfma_i32_16x16x64_i8 v[18:21], v[154:157], v[210:213], 0
	v_mfma_i32_16x16x64_i8 v[6:9], v[146:149], v[218:221], 0
	v_mfma_i32_16x16x64_i8 v[2:5], v[154:157], v[218:221], 0
	v_mfma_i32_16x16x64_i8 v[54:57], v[150:153], v[182:185], v[54:57]
	v_mfma_i32_16x16x64_i8 v[50:53], v[158:161], v[182:185], v[50:53]
	v_mfma_i32_16x16x64_i8 v[38:41], v[150:153], v[206:209], v[38:41]
	v_mfma_i32_16x16x64_i8 v[34:37], v[158:161], v[206:209], v[34:37]
	v_mfma_i32_16x16x64_i8 v[22:25], v[150:153], v[214:217], v[22:25]
	v_mfma_i32_16x16x64_i8 v[18:21], v[158:161], v[214:217], v[18:21]
	v_mfma_i32_16x16x64_i8 v[6:9], v[150:153], v[222:225], v[6:9]
	s_setprio 3
	s_barrier
	v_mfma_i32_16x16x64_i8 v[2:5], v[158:161], v[222:225], v[2:5]
	s_setprio 0
	s_add_i32 s71, 0, 0x18000
	s_add_i32 s72, 0, 0x1c000
	v_add_u32_e32 v130, s71, v193
	v_add_u32_e32 v158, s72, v193
	ds_read_b128 v[106:109], v130
	ds_read_b128 v[114:117], v130 offset:1024
	ds_read_b128 v[122:125], v130 offset:2048
	ds_read_b128 v[130:133], v130 offset:3072
	ds_read_b128 v[146:149], v158
	ds_read_b128 v[150:153], v158 offset:1024
	ds_read_b128 v[154:157], v158 offset:2048
	ds_read_b128 v[158:161], v158 offset:3072
	s_add_u32 s34, s34, 0x80000
	s_addc_u32 s35, s35, 0
	s_mov_b32 m0, s41
	v_lshl_add_u64 v[228:229], s[34:35], 0, v[166:167]
	ds_read_b128 v[162:165], v204 offset:32768
	ds_read_b128 v[182:185], v204 offset:33792
	ds_read_b128 v[186:189], v204 offset:34816
	ds_read_b128 v[206:209], v204 offset:35840
	ds_read_b128 v[210:213], v204 offset:36864
	ds_read_b128 v[214:217], v204 offset:37888
	ds_read_b128 v[218:221], v204 offset:38912
	ds_read_b128 v[222:225], v204 offset:39936
	global_load_lds_dwordx4 v[228:229], off
	v_lshl_add_u64 v[228:229], s[34:35], 0, v[170:171]
	s_mov_b32 m0, s42
	s_nop 0
	global_load_lds_dwordx4 v[228:229], off
	s_waitcnt vmcnt(8)
	s_waitcnt lgkmcnt(0)
	s_barrier
	s_waitcnt lgkmcnt(0)
	v_mfma_i32_16x16x64_i8 v[142:145], v[106:109], v[162:165], v[142:145]
	v_mfma_i32_16x16x64_i8 v[138:141], v[122:125], v[162:165], v[138:141]
	v_mfma_i32_16x16x64_i8 v[118:121], v[106:109], v[186:189], v[118:121]
	v_mfma_i32_16x16x64_i8 v[110:113], v[122:125], v[186:189], v[110:113]
	v_mfma_i32_16x16x64_i8 v[94:97], v[106:109], v[210:213], v[94:97]
	v_mfma_i32_16x16x64_i8 v[90:93], v[122:125], v[210:213], v[90:93]
	v_mfma_i32_16x16x64_i8 v[78:81], v[106:109], v[218:221], v[78:81]
	v_mfma_i32_16x16x64_i8 v[74:77], v[122:125], v[218:221], v[74:77]
	v_mfma_i32_16x16x64_i8 v[142:145], v[114:117], v[182:185], v[142:145]
	v_mfma_i32_16x16x64_i8 v[138:141], v[130:133], v[182:185], v[138:141]
	v_mfma_i32_16x16x64_i8 v[118:121], v[114:117], v[206:209], v[118:121]
	v_mfma_i32_16x16x64_i8 v[110:113], v[130:133], v[206:209], v[110:113]
	v_mfma_i32_16x16x64_i8 v[94:97], v[114:117], v[214:217], v[94:97]
	v_mfma_i32_16x16x64_i8 v[90:93], v[130:133], v[214:217], v[90:93]
	v_mfma_i32_16x16x64_i8 v[78:81], v[114:117], v[222:225], v[78:81]
	v_mfma_i32_16x16x64_i8 v[74:77], v[130:133], v[222:225], v[74:77]
	v_mfma_i32_16x16x64_i8 v[134:137], v[146:149], v[162:165], v[134:137]
	v_mfma_i32_16x16x64_i8 v[126:129], v[154:157], v[162:165], v[126:129]
	v_mfma_i32_16x16x64_i8 v[102:105], v[146:149], v[186:189], v[102:105]
	v_mfma_i32_16x16x64_i8 v[98:101], v[154:157], v[186:189], v[98:101]
	v_mfma_i32_16x16x64_i8 v[86:89], v[146:149], v[210:213], v[86:89]
	v_mfma_i32_16x16x64_i8 v[82:85], v[154:157], v[210:213], v[82:85]
	v_mfma_i32_16x16x64_i8 v[70:73], v[146:149], v[218:221], v[70:73]
	v_mfma_i32_16x16x64_i8 v[66:69], v[154:157], v[218:221], v[66:69]
	v_mfma_i32_16x16x64_i8 v[134:137], v[150:153], v[182:185], v[134:137]
	v_mfma_i32_16x16x64_i8 v[126:129], v[158:161], v[182:185], v[126:129]
	v_mfma_i32_16x16x64_i8 v[102:105], v[150:153], v[206:209], v[102:105]
	v_mfma_i32_16x16x64_i8 v[98:101], v[158:161], v[206:209], v[98:101]
	v_mfma_i32_16x16x64_i8 v[86:89], v[150:153], v[214:217], v[86:89]
	v_mfma_i32_16x16x64_i8 v[82:85], v[158:161], v[214:217], v[82:85]
	v_mfma_i32_16x16x64_i8 v[70:73], v[150:153], v[222:225], v[70:73]
	s_setprio 3
	s_barrier
	v_mfma_i32_16x16x64_i8 v[66:69], v[158:161], v[222:225], v[66:69]
	s_setprio 0
	s_add_i32 s34, s71, s39
	v_lshl_add_u64 v[194:195], v[194:195], 0, s[10:11]
	s_mov_b32 m0, s34
	ds_read_b128 v[162:165], v204 offset:49152
	ds_read_b128 v[182:185], v204 offset:50176
	ds_read_b128 v[186:189], v204 offset:51200
	ds_read_b128 v[206:209], v204 offset:52224
	ds_read_b128 v[210:213], v204 offset:53248
	ds_read_b128 v[214:217], v204 offset:54272
	ds_read_b128 v[218:221], v204 offset:55296
	ds_read_b128 v[222:225], v204 offset:56320
	global_load_lds_dwordx4 v[194:195], off
	s_add_i32 m0, s34, 0x2000
	s_add_u32 s30, s30, 0x80080
	v_lshl_add_u64 v[194:195], v[198:199], 0, s[10:11]
	s_addc_u32 s31, s31, 0
	s_add_i32 s34, s72, s39
	global_load_lds_dwordx4 v[194:195], off
	v_lshl_add_u64 v[194:195], s[30:31], 0, v[168:169]
	s_mov_b32 m0, s34
	s_nop 0
	global_load_lds_dwordx4 v[194:195], off
	v_lshl_add_u64 v[194:195], s[30:31], 0, v[172:173]
	s_add_i32 m0, s34, 0x2000
	s_nop 0
	global_load_lds_dwordx4 v[194:195], off
	v_lshl_add_u64 v[194:195], v[202:203], 0, s[10:11]
	s_mov_b32 m0, s60
	s_nop 0
	global_load_lds_dwordx4 v[194:195], off
	v_lshl_add_u64 v[194:195], v[226:227], 0, s[10:11]
	s_mov_b32 m0, s61
	s_nop 0
	global_load_lds_dwordx4 v[194:195], off
	s_waitcnt vmcnt(8)
	s_waitcnt lgkmcnt(0)
	s_barrier
	s_waitcnt lgkmcnt(0)
	v_mfma_i32_16x16x64_i8 v[62:65], v[106:109], v[162:165], v[62:65]
	v_mfma_i32_16x16x64_i8 v[58:61], v[122:125], v[162:165], v[58:61]
	v_mfma_i32_16x16x64_i8 v[46:49], v[106:109], v[186:189], v[46:49]
	v_mfma_i32_16x16x64_i8 v[42:45], v[122:125], v[186:189], v[42:45]
	v_mfma_i32_16x16x64_i8 v[30:33], v[106:109], v[210:213], v[30:33]
	v_mfma_i32_16x16x64_i8 v[26:29], v[122:125], v[210:213], v[26:29]
	v_mfma_i32_16x16x64_i8 v[14:17], v[106:109], v[218:221], v[14:17]
	v_mfma_i32_16x16x64_i8 v[10:13], v[122:125], v[218:221], v[10:13]
	v_mfma_i32_16x16x64_i8 v[62:65], v[114:117], v[182:185], v[62:65]
	v_mfma_i32_16x16x64_i8 v[58:61], v[130:133], v[182:185], v[58:61]
	v_mfma_i32_16x16x64_i8 v[46:49], v[114:117], v[206:209], v[46:49]
	v_mfma_i32_16x16x64_i8 v[42:45], v[130:133], v[206:209], v[42:45]
	v_mfma_i32_16x16x64_i8 v[30:33], v[114:117], v[214:217], v[30:33]
	v_mfma_i32_16x16x64_i8 v[26:29], v[130:133], v[214:217], v[26:29]
	v_mfma_i32_16x16x64_i8 v[14:17], v[114:117], v[222:225], v[14:17]
	v_mfma_i32_16x16x64_i8 v[10:13], v[130:133], v[222:225], v[10:13]
	v_mfma_i32_16x16x64_i8 v[54:57], v[146:149], v[162:165], v[54:57]
	v_mfma_i32_16x16x64_i8 v[50:53], v[154:157], v[162:165], v[50:53]
	v_mfma_i32_16x16x64_i8 v[38:41], v[146:149], v[186:189], v[38:41]
	v_mfma_i32_16x16x64_i8 v[34:37], v[154:157], v[186:189], v[34:37]
	v_mfma_i32_16x16x64_i8 v[22:25], v[146:149], v[210:213], v[22:25]
	v_mfma_i32_16x16x64_i8 v[18:21], v[154:157], v[210:213], v[18:21]
	v_mfma_i32_16x16x64_i8 v[6:9], v[146:149], v[218:221], v[6:9]
	v_mfma_i32_16x16x64_i8 v[2:5], v[154:157], v[218:221], v[2:5]
	v_mfma_i32_16x16x64_i8 v[54:57], v[150:153], v[182:185], v[54:57]
	v_mfma_i32_16x16x64_i8 v[50:53], v[158:161], v[182:185], v[50:53]
	v_mfma_i32_16x16x64_i8 v[38:41], v[150:153], v[206:209], v[38:41]
	v_mfma_i32_16x16x64_i8 v[34:37], v[158:161], v[206:209], v[34:37]
	v_mfma_i32_16x16x64_i8 v[22:25], v[150:153], v[214:217], v[22:25]
	v_mfma_i32_16x16x64_i8 v[18:21], v[158:161], v[214:217], v[18:21]
	v_mfma_i32_16x16x64_i8 v[6:9], v[150:153], v[222:225], v[6:9]
	s_setprio 3
	s_barrier
	v_mfma_i32_16x16x64_i8 v[2:5], v[158:161], v[222:225], v[2:5]
	s_setprio 0
	s_add_i32 s70, s70, 2
	s_add_u32 s28, s28, 0x100
	s_addc_u32 s29, s29, 0
	s_add_u32 s68, s68, 0x100
	s_addc_u32 s69, s69, 0
	s_cmp_gt_u32 s70, 29
.LBB0_1232:
	ds_read_b128 v[106:109], v197
	ds_read_b128 v[114:117], v197 offset:1024
	ds_read_b128 v[122:125], v197 offset:2048
	ds_read_b128 v[130:133], v197 offset:3072
	ds_read_b128 v[146:149], v201
	ds_read_b128 v[150:153], v201 offset:1024
	ds_read_b128 v[154:157], v201 offset:2048
	ds_read_b128 v[158:161], v201 offset:3072
	s_add_u32 s30, s28, 0xfff80080
	s_addc_u32 s31, s29, -1
	s_cmp_eq_u32 s70, 28
	s_cselect_b32 s35, s23, s31
	s_cselect_b32 s34, s66, s30
	s_cselect_b32 s31, s15, s69
	s_cselect_b32 s30, s67, s68
	v_lshl_add_u64 v[194:195], s[28:29], 0, v[174:175]
	s_add_i32 m0, s19, 0xc000
	ds_read_b128 v[162:165], v204
	ds_read_b128 v[182:185], v204 offset:1024
	ds_read_b128 v[186:189], v204 offset:2048
	ds_read_b128 v[206:209], v204 offset:3072
	ds_read_b128 v[210:213], v204 offset:4096
	ds_read_b128 v[214:217], v204 offset:5120
	ds_read_b128 v[218:221], v204 offset:6144
	ds_read_b128 v[222:225], v204 offset:7168
	global_load_lds_dwordx4 v[194:195], off
	v_lshl_add_u64 v[194:195], s[28:29], 0, v[176:177]
	s_add_i32 m0, s19, 0xe000
	s_nop 0
	global_load_lds_dwordx4 v[194:195], off
	s_waitcnt vmcnt(8)
	s_waitcnt lgkmcnt(0)
	s_barrier
	s_waitcnt lgkmcnt(0)
	v_mfma_i32_16x16x64_i8 v[142:145], v[106:109], v[162:165], v[142:145]
	v_mfma_i32_16x16x64_i8 v[138:141], v[122:125], v[162:165], v[138:141]
	v_mfma_i32_16x16x64_i8 v[118:121], v[106:109], v[186:189], v[118:121]
	v_mfma_i32_16x16x64_i8 v[110:113], v[122:125], v[186:189], v[110:113]
	v_mfma_i32_16x16x64_i8 v[94:97], v[106:109], v[210:213], v[94:97]
	v_mfma_i32_16x16x64_i8 v[90:93], v[122:125], v[210:213], v[90:93]
	v_mfma_i32_16x16x64_i8 v[78:81], v[106:109], v[218:221], v[78:81]
	v_mfma_i32_16x16x64_i8 v[74:77], v[122:125], v[218:221], v[74:77]
	v_mfma_i32_16x16x64_i8 v[142:145], v[114:117], v[182:185], v[142:145]
	v_mfma_i32_16x16x64_i8 v[138:141], v[130:133], v[182:185], v[138:141]
	v_mfma_i32_16x16x64_i8 v[118:121], v[114:117], v[206:209], v[118:121]
	v_mfma_i32_16x16x64_i8 v[110:113], v[130:133], v[206:209], v[110:113]
	v_mfma_i32_16x16x64_i8 v[94:97], v[114:117], v[214:217], v[94:97]
	v_mfma_i32_16x16x64_i8 v[90:93], v[130:133], v[214:217], v[90:93]
	v_mfma_i32_16x16x64_i8 v[78:81], v[114:117], v[222:225], v[78:81]
	v_mfma_i32_16x16x64_i8 v[74:77], v[130:133], v[222:225], v[74:77]
	v_mfma_i32_16x16x64_i8 v[134:137], v[146:149], v[162:165], v[134:137]
	v_mfma_i32_16x16x64_i8 v[126:129], v[154:157], v[162:165], v[126:129]
	v_mfma_i32_16x16x64_i8 v[102:105], v[146:149], v[186:189], v[102:105]
	v_mfma_i32_16x16x64_i8 v[98:101], v[154:157], v[186:189], v[98:101]
	v_mfma_i32_16x16x64_i8 v[86:89], v[146:149], v[210:213], v[86:89]
	v_mfma_i32_16x16x64_i8 v[82:85], v[154:157], v[210:213], v[82:85]
	v_mfma_i32_16x16x64_i8 v[70:73], v[146:149], v[218:221], v[70:73]
	v_mfma_i32_16x16x64_i8 v[66:69], v[154:157], v[218:221], v[66:69]
	v_mfma_i32_16x16x64_i8 v[134:137], v[150:153], v[182:185], v[134:137]
	v_mfma_i32_16x16x64_i8 v[126:129], v[158:161], v[182:185], v[126:129]
	v_mfma_i32_16x16x64_i8 v[102:105], v[150:153], v[206:209], v[102:105]
	v_mfma_i32_16x16x64_i8 v[98:101], v[158:161], v[206:209], v[98:101]
	v_mfma_i32_16x16x64_i8 v[86:89], v[150:153], v[214:217], v[86:89]
	v_mfma_i32_16x16x64_i8 v[82:85], v[158:161], v[214:217], v[82:85]
	v_mfma_i32_16x16x64_i8 v[70:73], v[150:153], v[222:225], v[70:73]
	s_setprio 3
	s_barrier
	v_mfma_i32_16x16x64_i8 v[66:69], v[158:161], v[222:225], v[66:69]
	s_setprio 0
	s_add_i32 s71, s63, s39
	v_lshl_add_u64 v[194:195], s[30:31], 0, v[168:169]
	s_mov_b32 m0, s71
	ds_read_b128 v[162:165], v204 offset:16384
	ds_read_b128 v[182:185], v204 offset:17408
	ds_read_b128 v[186:189], v204 offset:18432
	ds_read_b128 v[206:209], v204 offset:19456
	ds_read_b128 v[210:213], v204 offset:20480
	ds_read_b128 v[214:217], v204 offset:21504
	ds_read_b128 v[218:221], v204 offset:22528
	ds_read_b128 v[222:225], v204 offset:23552
	global_load_lds_dwordx4 v[194:195], off
	s_add_i32 m0, s71, 0x2000
	s_add_u32 s72, s30, 0x80000
	v_lshl_add_u64 v[198:199], s[30:31], 0, v[172:173]
	s_addc_u32 s73, s31, 0
	s_add_i32 s71, s64, s39
	global_load_lds_dwordx4 v[198:199], off
	v_lshl_add_u64 v[202:203], s[72:73], 0, v[168:169]
	s_mov_b32 m0, s71
	v_lshl_add_u64 v[226:227], s[34:35], 0, v[170:171]
	global_load_lds_dwordx4 v[202:203], off
	v_lshl_add_u64 v[202:203], s[72:73], 0, v[172:173]
	s_add_i32 m0, s71, 0x2000
	s_nop 0
	global_load_lds_dwordx4 v[202:203], off
	v_lshl_add_u64 v[202:203], s[34:35], 0, v[166:167]
	s_mov_b32 m0, s19
	s_nop 0
	global_load_lds_dwordx4 v[202:203], off
	s_mov_b32 m0, s40
	s_nop 0
	global_load_lds_dwordx4 v[226:227], off
	s_waitcnt vmcnt(8)
	s_waitcnt lgkmcnt(0)
	s_barrier
	s_waitcnt lgkmcnt(0)
	v_mfma_i32_16x16x64_i8 v[62:65], v[106:109], v[162:165], v[62:65]
	v_mfma_i32_16x16x64_i8 v[58:61], v[122:125], v[162:165], v[58:61]
	v_mfma_i32_16x16x64_i8 v[46:49], v[106:109], v[186:189], v[46:49]
	v_mfma_i32_16x16x64_i8 v[42:45], v[122:125], v[186:189], v[42:45]
	v_mfma_i32_16x16x64_i8 v[30:33], v[106:109], v[210:213], v[30:33]
	v_mfma_i32_16x16x64_i8 v[26:29], v[122:125], v[210:213], v[26:29]
	v_mfma_i32_16x16x64_i8 v[14:17], v[106:109], v[218:221], v[14:17]
	v_mfma_i32_16x16x64_i8 v[10:13], v[122:125], v[218:221], v[10:13]
	v_mfma_i32_16x16x64_i8 v[62:65], v[114:117], v[182:185], v[62:65]
	v_mfma_i32_16x16x64_i8 v[58:61], v[130:133], v[182:185], v[58:61]
	v_mfma_i32_16x16x64_i8 v[46:49], v[114:117], v[206:209], v[46:49]
	v_mfma_i32_16x16x64_i8 v[42:45], v[130:133], v[206:209], v[42:45]
	v_mfma_i32_16x16x64_i8 v[30:33], v[114:117], v[214:217], v[30:33]
	v_mfma_i32_16x16x64_i8 v[26:29], v[130:133], v[214:217], v[26:29]
	v_mfma_i32_16x16x64_i8 v[14:17], v[114:117], v[222:225], v[14:17]
	v_mfma_i32_16x16x64_i8 v[10:13], v[130:133], v[222:225], v[10:13]
	v_mfma_i32_16x16x64_i8 v[54:57], v[146:149], v[162:165], v[54:57]
	v_mfma_i32_16x16x64_i8 v[50:53], v[154:157], v[162:165], v[50:53]
	v_mfma_i32_16x16x64_i8 v[38:41], v[146:149], v[186:189], v[38:41]
	v_mfma_i32_16x16x64_i8 v[34:37], v[154:157], v[186:189], v[34:37]
	v_mfma_i32_16x16x64_i8 v[22:25], v[146:149], v[210:213], v[22:25]
	v_mfma_i32_16x16x64_i8 v[18:21], v[154:157], v[210:213], v[18:21]
	v_mfma_i32_16x16x64_i8 v[6:9], v[146:149], v[218:221], v[6:9]
	v_mfma_i32_16x16x64_i8 v[2:5], v[154:157], v[218:221], v[2:5]
	v_mfma_i32_16x16x64_i8 v[54:57], v[150:153], v[182:185], v[54:57]
	v_mfma_i32_16x16x64_i8 v[50:53], v[158:161], v[182:185], v[50:53]
	v_mfma_i32_16x16x64_i8 v[38:41], v[150:153], v[206:209], v[38:41]
	v_mfma_i32_16x16x64_i8 v[34:37], v[158:161], v[206:209], v[34:37]
	v_mfma_i32_16x16x64_i8 v[22:25], v[150:153], v[214:217], v[22:25]
	v_mfma_i32_16x16x64_i8 v[18:21], v[158:161], v[214:217], v[18:21]
	v_mfma_i32_16x16x64_i8 v[6:9], v[150:153], v[222:225], v[6:9]
	s_setprio 3
	s_barrier
	v_mfma_i32_16x16x64_i8 v[2:5], v[158:161], v[222:225], v[2:5]
	s_setprio 0
	s_add_i32 s71, 0, 0x18000
	s_add_i32 s72, 0, 0x1c000
	v_add_u32_e32 v130, s71, v193
	v_add_u32_e32 v158, s72, v193
	ds_read_b128 v[106:109], v130
	ds_read_b128 v[114:117], v130 offset:1024
	ds_read_b128 v[122:125], v130 offset:2048
	ds_read_b128 v[130:133], v130 offset:3072
	ds_read_b128 v[146:149], v158
	ds_read_b128 v[150:153], v158 offset:1024
	ds_read_b128 v[154:157], v158 offset:2048
	ds_read_b128 v[158:161], v158 offset:3072
	s_add_u32 s34, s34, 0x80000
	s_addc_u32 s35, s35, 0
	s_mov_b32 m0, s41
	v_lshl_add_u64 v[228:229], s[34:35], 0, v[166:167]
	ds_read_b128 v[162:165], v204 offset:32768
	ds_read_b128 v[182:185], v204 offset:33792
	ds_read_b128 v[186:189], v204 offset:34816
	ds_read_b128 v[206:209], v204 offset:35840
	ds_read_b128 v[210:213], v204 offset:36864
	ds_read_b128 v[214:217], v204 offset:37888
	ds_read_b128 v[218:221], v204 offset:38912
	ds_read_b128 v[222:225], v204 offset:39936
	global_load_lds_dwordx4 v[228:229], off
	v_lshl_add_u64 v[228:229], s[34:35], 0, v[170:171]
	s_mov_b32 m0, s42
	s_nop 0
	global_load_lds_dwordx4 v[228:229], off
	s_waitcnt vmcnt(8)
	s_waitcnt lgkmcnt(0)
	s_barrier
	s_waitcnt lgkmcnt(0)
	v_mfma_i32_16x16x64_i8 v[142:145], v[106:109], v[162:165], v[142:145]
	v_mfma_i32_16x16x64_i8 v[138:141], v[122:125], v[162:165], v[138:141]
	v_mfma_i32_16x16x64_i8 v[118:121], v[106:109], v[186:189], v[118:121]
	v_mfma_i32_16x16x64_i8 v[110:113], v[122:125], v[186:189], v[110:113]
	v_mfma_i32_16x16x64_i8 v[94:97], v[106:109], v[210:213], v[94:97]
	v_mfma_i32_16x16x64_i8 v[90:93], v[122:125], v[210:213], v[90:93]
	v_mfma_i32_16x16x64_i8 v[78:81], v[106:109], v[218:221], v[78:81]
	v_mfma_i32_16x16x64_i8 v[74:77], v[122:125], v[218:221], v[74:77]
	v_mfma_i32_16x16x64_i8 v[142:145], v[114:117], v[182:185], v[142:145]
	v_mfma_i32_16x16x64_i8 v[138:141], v[130:133], v[182:185], v[138:141]
	v_mfma_i32_16x16x64_i8 v[118:121], v[114:117], v[206:209], v[118:121]
	v_mfma_i32_16x16x64_i8 v[110:113], v[130:133], v[206:209], v[110:113]
	v_mfma_i32_16x16x64_i8 v[94:97], v[114:117], v[214:217], v[94:97]
	v_mfma_i32_16x16x64_i8 v[90:93], v[130:133], v[214:217], v[90:93]
	v_mfma_i32_16x16x64_i8 v[78:81], v[114:117], v[222:225], v[78:81]
	v_mfma_i32_16x16x64_i8 v[74:77], v[130:133], v[222:225], v[74:77]
	v_mfma_i32_16x16x64_i8 v[134:137], v[146:149], v[162:165], v[134:137]
	v_mfma_i32_16x16x64_i8 v[126:129], v[154:157], v[162:165], v[126:129]
	v_mfma_i32_16x16x64_i8 v[102:105], v[146:149], v[186:189], v[102:105]
	v_mfma_i32_16x16x64_i8 v[98:101], v[154:157], v[186:189], v[98:101]
	v_mfma_i32_16x16x64_i8 v[86:89], v[146:149], v[210:213], v[86:89]
	v_mfma_i32_16x16x64_i8 v[82:85], v[154:157], v[210:213], v[82:85]
	v_mfma_i32_16x16x64_i8 v[70:73], v[146:149], v[218:221], v[70:73]
	v_mfma_i32_16x16x64_i8 v[66:69], v[154:157], v[218:221], v[66:69]
	v_mfma_i32_16x16x64_i8 v[134:137], v[150:153], v[182:185], v[134:137]
	v_mfma_i32_16x16x64_i8 v[126:129], v[158:161], v[182:185], v[126:129]
	v_mfma_i32_16x16x64_i8 v[102:105], v[150:153], v[206:209], v[102:105]
	v_mfma_i32_16x16x64_i8 v[98:101], v[158:161], v[206:209], v[98:101]
	v_mfma_i32_16x16x64_i8 v[86:89], v[150:153], v[214:217], v[86:89]
	v_mfma_i32_16x16x64_i8 v[82:85], v[158:161], v[214:217], v[82:85]
	v_mfma_i32_16x16x64_i8 v[70:73], v[150:153], v[222:225], v[70:73]
	s_setprio 3
	s_barrier
	v_mfma_i32_16x16x64_i8 v[66:69], v[158:161], v[222:225], v[66:69]
	s_setprio 0
	s_add_i32 s34, s71, s39
	v_lshl_add_u64 v[194:195], v[194:195], 0, s[10:11]
	s_mov_b32 m0, s34
	ds_read_b128 v[162:165], v204 offset:49152
	ds_read_b128 v[182:185], v204 offset:50176
	ds_read_b128 v[186:189], v204 offset:51200
	ds_read_b128 v[206:209], v204 offset:52224
	ds_read_b128 v[210:213], v204 offset:53248
	ds_read_b128 v[214:217], v204 offset:54272
	ds_read_b128 v[218:221], v204 offset:55296
	ds_read_b128 v[222:225], v204 offset:56320
	global_load_lds_dwordx4 v[194:195], off
	s_add_i32 m0, s34, 0x2000
	s_add_u32 s30, s30, 0x80080
	v_lshl_add_u64 v[194:195], v[198:199], 0, s[10:11]
	s_addc_u32 s31, s31, 0
	s_add_i32 s34, s72, s39
	global_load_lds_dwordx4 v[194:195], off
	v_lshl_add_u64 v[194:195], s[30:31], 0, v[168:169]
	s_mov_b32 m0, s34
	s_nop 0
	global_load_lds_dwordx4 v[194:195], off
	v_lshl_add_u64 v[194:195], s[30:31], 0, v[172:173]
	s_add_i32 m0, s34, 0x2000
	s_nop 0
	global_load_lds_dwordx4 v[194:195], off
	v_lshl_add_u64 v[194:195], v[202:203], 0, s[10:11]
	s_mov_b32 m0, s60
	s_nop 0
	global_load_lds_dwordx4 v[194:195], off
	v_lshl_add_u64 v[194:195], v[226:227], 0, s[10:11]
	s_mov_b32 m0, s61
	s_nop 0
	global_load_lds_dwordx4 v[194:195], off
	s_waitcnt vmcnt(8)
	s_waitcnt lgkmcnt(0)
	s_barrier
	s_waitcnt lgkmcnt(0)
	v_mfma_i32_16x16x64_i8 v[62:65], v[106:109], v[162:165], v[62:65]
	v_mfma_i32_16x16x64_i8 v[58:61], v[122:125], v[162:165], v[58:61]
	v_mfma_i32_16x16x64_i8 v[46:49], v[106:109], v[186:189], v[46:49]
	v_mfma_i32_16x16x64_i8 v[42:45], v[122:125], v[186:189], v[42:45]
	v_mfma_i32_16x16x64_i8 v[30:33], v[106:109], v[210:213], v[30:33]
	v_mfma_i32_16x16x64_i8 v[26:29], v[122:125], v[210:213], v[26:29]
	v_mfma_i32_16x16x64_i8 v[14:17], v[106:109], v[218:221], v[14:17]
	v_mfma_i32_16x16x64_i8 v[10:13], v[122:125], v[218:221], v[10:13]
	v_mfma_i32_16x16x64_i8 v[62:65], v[114:117], v[182:185], v[62:65]
	v_mfma_i32_16x16x64_i8 v[58:61], v[130:133], v[182:185], v[58:61]
	v_mfma_i32_16x16x64_i8 v[46:49], v[114:117], v[206:209], v[46:49]
	v_mfma_i32_16x16x64_i8 v[42:45], v[130:133], v[206:209], v[42:45]
	v_mfma_i32_16x16x64_i8 v[30:33], v[114:117], v[214:217], v[30:33]
	v_mfma_i32_16x16x64_i8 v[26:29], v[130:133], v[214:217], v[26:29]
	v_mfma_i32_16x16x64_i8 v[14:17], v[114:117], v[222:225], v[14:17]
	v_mfma_i32_16x16x64_i8 v[10:13], v[130:133], v[222:225], v[10:13]
	v_mfma_i32_16x16x64_i8 v[54:57], v[146:149], v[162:165], v[54:57]
	v_mfma_i32_16x16x64_i8 v[50:53], v[154:157], v[162:165], v[50:53]
	v_mfma_i32_16x16x64_i8 v[38:41], v[146:149], v[186:189], v[38:41]
	v_mfma_i32_16x16x64_i8 v[34:37], v[154:157], v[186:189], v[34:37]
	v_mfma_i32_16x16x64_i8 v[22:25], v[146:149], v[210:213], v[22:25]
	v_mfma_i32_16x16x64_i8 v[18:21], v[154:157], v[210:213], v[18:21]
	v_mfma_i32_16x16x64_i8 v[6:9], v[146:149], v[218:221], v[6:9]
	v_mfma_i32_16x16x64_i8 v[2:5], v[154:157], v[218:221], v[2:5]
	v_mfma_i32_16x16x64_i8 v[54:57], v[150:153], v[182:185], v[54:57]
	v_mfma_i32_16x16x64_i8 v[50:53], v[158:161], v[182:185], v[50:53]
	v_mfma_i32_16x16x64_i8 v[38:41], v[150:153], v[206:209], v[38:41]
	v_mfma_i32_16x16x64_i8 v[34:37], v[158:161], v[206:209], v[34:37]
	v_mfma_i32_16x16x64_i8 v[22:25], v[150:153], v[214:217], v[22:25]
	v_mfma_i32_16x16x64_i8 v[18:21], v[158:161], v[214:217], v[18:21]
	v_mfma_i32_16x16x64_i8 v[6:9], v[150:153], v[222:225], v[6:9]
	s_setprio 3
	s_barrier
	v_mfma_i32_16x16x64_i8 v[2:5], v[158:161], v[222:225], v[2:5]
	s_setprio 0
	s_add_i32 s70, s70, 2
	s_add_u32 s28, s28, 0x100
	s_addc_u32 s29, s29, 0
	s_add_u32 s68, s68, 0x100
	s_addc_u32 s69, s69, 0
	s_cmp_gt_u32 s70, 29
	s_cbranch_scc0 .LBB0_1232
	s_and_b64 vcc, exec, s[12:13]
	s_cbranch_vccz .LBB0_1235
	s_barrier

.LBB0_1366:
	s_ashr_i32 s35, s34, 31
	s_lshl_b64 s[18:19], s[34:35], 20
	s_add_u32 s36, s29, s18
	s_addc_u32 s37, s60, s19
	s_and_b64 s[18:19], s[2:3], exec
	s_cselect_b32 s35, s37, s5
	s_cselect_b32 s43, s36, s4
	s_ashr_i32 s31, s30, 31
	s_lshl_b64 s[18:19], s[30:31], 20
	s_add_u32 s38, s61, s18
	s_addc_u32 s39, s62, s19
	s_and_b64 s[18:19], s[2:3], exec
	s_cselect_b32 s31, s39, s7
	s_cselect_b32 vcc_lo, s38, s6
	s_add_u32 vcc_hi, s6, 0x100
	s_addc_u32 s79, s7, 0
	s_mov_b32 s80, -2
	ds_read_b128 v[130:133], v234
	ds_read_b128 v[134:137], v234 offset:1024
	ds_read_b128 v[162:165], v234 offset:2048
	ds_read_b128 v[166:169], v234 offset:3072
	ds_read_b128 v[170:173], v235
	ds_read_b128 v[174:177], v235 offset:1024
	ds_read_b128 v[178:181], v235 offset:2048
	ds_read_b128 v[182:185], v235 offset:3072
	s_add_u32 s6, s4, 0x100
	s_addc_u32 s7, s5, 0
	s_cmp_eq_u32 s80, 28
	s_cselect_b32 s57, s35, s7
	s_cselect_b32 s56, s43, s6
	s_cselect_b32 s19, s31, s79
	s_cselect_b32 s18, vcc_lo, vcc_hi
	v_lshl_add_u64 v[218:219], s[4:5], 0, v[154:155]
	s_add_i32 m0, s65, 0xc000
	ds_read_b128 v[186:189], v236
	ds_read_b128 v[190:193], v236 offset:1024
	ds_read_b128 v[194:197], v236 offset:2048
	ds_read_b128 v[198:201], v236 offset:3072
	ds_read_b128 v[202:205], v236 offset:4096
	ds_read_b128 v[206:209], v236 offset:5120
	ds_read_b128 v[210:213], v236 offset:6144
	ds_read_b128 v[214:217], v236 offset:7168
	global_load_lds_dwordx4 v[218:219], off
	v_lshl_add_u64 v[218:219], s[4:5], 0, v[156:157]
	s_add_i32 m0, s65, 0xe000
	s_nop 0
	global_load_lds_dwordx4 v[218:219], off
	s_waitcnt vmcnt(8)
	s_waitcnt lgkmcnt(0)
	s_barrier
	s_waitcnt lgkmcnt(0)
	v_mfma_i32_16x16x64_i8 v[118:121], v[130:133], v[186:189], 0
	v_mfma_i32_16x16x64_i8 v[102:105], v[162:165], v[186:189], 0
	v_mfma_i32_16x16x64_i8 v[114:117], v[130:133], v[194:197], 0
	v_mfma_i32_16x16x64_i8 v[98:101], v[162:165], v[194:197], 0
	v_mfma_i32_16x16x64_i8 v[126:129], v[130:133], v[202:205], 0
	v_mfma_i32_16x16x64_i8 v[110:113], v[162:165], v[202:205], 0
	v_mfma_i32_16x16x64_i8 v[122:125], v[130:133], v[210:213], 0
	v_mfma_i32_16x16x64_i8 v[106:109], v[162:165], v[210:213], 0
	v_mfma_i32_16x16x64_i8 v[118:121], v[134:137], v[190:193], v[118:121]
	v_mfma_i32_16x16x64_i8 v[102:105], v[166:169], v[190:193], v[102:105]
	v_mfma_i32_16x16x64_i8 v[114:117], v[134:137], v[198:201], v[114:117]
	v_mfma_i32_16x16x64_i8 v[98:101], v[166:169], v[198:201], v[98:101]
	v_mfma_i32_16x16x64_i8 v[126:129], v[134:137], v[206:209], v[126:129]
	v_mfma_i32_16x16x64_i8 v[110:113], v[166:169], v[206:209], v[110:113]
	v_mfma_i32_16x16x64_i8 v[122:125], v[134:137], v[214:217], v[122:125]
	v_mfma_i32_16x16x64_i8 v[106:109], v[166:169], v[214:217], v[106:109]
	v_mfma_i32_16x16x64_i8 v[86:89], v[170:173], v[186:189], 0
	v_mfma_i32_16x16x64_i8 v[70:73], v[178:181], v[186:189], 0
	v_mfma_i32_16x16x64_i8 v[82:85], v[170:173], v[194:197], 0
	v_mfma_i32_16x16x64_i8 v[66:69], v[178:181], v[194:197], 0
	v_mfma_i32_16x16x64_i8 v[94:97], v[170:173], v[202:205], 0
	v_mfma_i32_16x16x64_i8 v[78:81], v[178:181], v[202:205], 0
	v_mfma_i32_16x16x64_i8 v[90:93], v[170:173], v[210:213], 0
	v_mfma_i32_16x16x64_i8 v[74:77], v[178:181], v[210:213], 0
	v_mfma_i32_16x16x64_i8 v[86:89], v[174:177], v[190:193], v[86:89]
	v_mfma_i32_16x16x64_i8 v[70:73], v[182:185], v[190:193], v[70:73]
	v_mfma_i32_16x16x64_i8 v[82:85], v[174:177], v[198:201], v[82:85]
	v_mfma_i32_16x16x64_i8 v[66:69], v[182:185], v[198:201], v[66:69]
	v_mfma_i32_16x16x64_i8 v[94:97], v[174:177], v[206:209], v[94:97]
	v_mfma_i32_16x16x64_i8 v[78:81], v[182:185], v[206:209], v[78:81]
	v_mfma_i32_16x16x64_i8 v[90:93], v[174:177], v[214:217], v[90:93]
	s_setprio 3
	s_barrier
	v_mfma_i32_16x16x64_i8 v[74:77], v[182:185], v[214:217], v[74:77]
	s_setprio 0
	s_add_i32 s4, s97, s63
	v_lshl_add_u64 v[218:219], s[18:19], 0, v[144:145]
	s_mov_b32 m0, s4
	ds_read_b128 v[186:189], v236 offset:16384
	ds_read_b128 v[190:193], v236 offset:17408
	ds_read_b128 v[194:197], v236 offset:18432
	ds_read_b128 v[198:201], v236 offset:19456
	ds_read_b128 v[202:205], v236 offset:20480
	ds_read_b128 v[206:209], v236 offset:21504
	ds_read_b128 v[210:213], v236 offset:22528
	ds_read_b128 v[214:217], v236 offset:23552
	global_load_lds_dwordx4 v[218:219], off
	s_add_i32 m0, s4, 0x2000
	s_add_u32 s4, s18, 0x80000
	v_lshl_add_u64 v[220:221], s[18:19], 0, v[148:149]
	s_addc_u32 s5, s19, 0
	s_add_i32 s81, s0, s63
	global_load_lds_dwordx4 v[220:221], off
	v_lshl_add_u64 v[222:223], s[4:5], 0, v[144:145]
	s_mov_b32 m0, s81
	v_lshl_add_u64 v[224:225], s[56:57], 0, v[146:147]
	global_load_lds_dwordx4 v[222:223], off
	v_lshl_add_u64 v[222:223], s[4:5], 0, v[148:149]
	s_add_i32 m0, s81, 0x2000
	s_nop 0
	global_load_lds_dwordx4 v[222:223], off
	v_lshl_add_u64 v[222:223], s[56:57], 0, v[142:143]
	s_mov_b32 m0, s65
	s_nop 0
	global_load_lds_dwordx4 v[222:223], off
	s_mov_b32 m0, s66
	s_nop 0
	global_load_lds_dwordx4 v[224:225], off
	s_waitcnt vmcnt(8)
	s_waitcnt lgkmcnt(0)
	s_barrier
	s_waitcnt lgkmcnt(0)
	v_mfma_i32_16x16x64_i8 v[54:57], v[130:133], v[186:189], 0
	v_mfma_i32_16x16x64_i8 v[18:21], v[162:165], v[186:189], 0
	v_mfma_i32_16x16x64_i8 v[50:53], v[130:133], v[194:197], 0
	v_mfma_i32_16x16x64_i8 v[22:25], v[162:165], v[194:197], 0
	v_mfma_i32_16x16x64_i8 v[62:65], v[130:133], v[202:205], 0
	v_mfma_i32_16x16x64_i8 v[30:33], v[162:165], v[202:205], 0
	v_mfma_i32_16x16x64_i8 v[58:61], v[130:133], v[210:213], 0
	v_mfma_i32_16x16x64_i8 v[26:29], v[162:165], v[210:213], 0
	v_mfma_i32_16x16x64_i8 v[54:57], v[134:137], v[190:193], v[54:57]
	v_mfma_i32_16x16x64_i8 v[18:21], v[166:169], v[190:193], v[18:21]
	v_mfma_i32_16x16x64_i8 v[50:53], v[134:137], v[198:201], v[50:53]
	v_mfma_i32_16x16x64_i8 v[22:25], v[166:169], v[198:201], v[22:25]
	v_mfma_i32_16x16x64_i8 v[62:65], v[134:137], v[206:209], v[62:65]
	v_mfma_i32_16x16x64_i8 v[30:33], v[166:169], v[206:209], v[30:33]
	v_mfma_i32_16x16x64_i8 v[58:61], v[134:137], v[214:217], v[58:61]
	v_mfma_i32_16x16x64_i8 v[26:29], v[166:169], v[214:217], v[26:29]
	v_mfma_i32_16x16x64_i8 v[46:49], v[170:173], v[186:189], 0
	v_mfma_i32_16x16x64_i8 v[14:17], v[178:181], v[186:189], 0
	v_mfma_i32_16x16x64_i8 v[42:45], v[170:173], v[194:197], 0
	v_mfma_i32_16x16x64_i8 v[10:13], v[178:181], v[194:197], 0
	v_mfma_i32_16x16x64_i8 v[38:41], v[170:173], v[202:205], 0
	v_mfma_i32_16x16x64_i8 v[6:9], v[178:181], v[202:205], 0
	v_mfma_i32_16x16x64_i8 v[34:37], v[170:173], v[210:213], 0
	v_mfma_i32_16x16x64_i8 v[2:5], v[178:181], v[210:213], 0
	v_mfma_i32_16x16x64_i8 v[46:49], v[174:177], v[190:193], v[46:49]
	v_mfma_i32_16x16x64_i8 v[14:17], v[182:185], v[190:193], v[14:17]
	v_mfma_i32_16x16x64_i8 v[42:45], v[174:177], v[198:201], v[42:45]
	v_mfma_i32_16x16x64_i8 v[10:13], v[182:185], v[198:201], v[10:13]
	v_mfma_i32_16x16x64_i8 v[38:41], v[174:177], v[206:209], v[38:41]
	v_mfma_i32_16x16x64_i8 v[6:9], v[182:185], v[206:209], v[6:9]
	v_mfma_i32_16x16x64_i8 v[34:37], v[174:177], v[214:217], v[34:37]
	s_setprio 3
	s_barrier
	v_mfma_i32_16x16x64_i8 v[2:5], v[182:185], v[214:217], v[2:5]
	s_setprio 0
	s_add_i32 s81, 0, 0x18000
	s_add_i32 s82, 0, 0x1c000
	v_add_u32_e32 v166, s81, v232
	v_add_u32_e32 v182, s82, v232
	ds_read_b128 v[130:133], v166
	ds_read_b128 v[134:137], v166 offset:1024
	ds_read_b128 v[162:165], v166 offset:2048
	ds_read_b128 v[166:169], v166 offset:3072
	ds_read_b128 v[170:173], v182
	ds_read_b128 v[174:177], v182 offset:1024
	ds_read_b128 v[178:181], v182 offset:2048
	ds_read_b128 v[182:185], v182 offset:3072
	s_add_u32 s4, s56, 0x80000
	s_addc_u32 s5, s57, 0
	s_mov_b32 m0, s67
	v_lshl_add_u64 v[226:227], s[4:5], 0, v[142:143]
	ds_read_b128 v[186:189], v236 offset:32768
	ds_read_b128 v[190:193], v236 offset:33792
	ds_read_b128 v[194:197], v236 offset:34816
	ds_read_b128 v[198:201], v236 offset:35840
	ds_read_b128 v[202:205], v236 offset:36864
	ds_read_b128 v[206:209], v236 offset:37888
	ds_read_b128 v[210:213], v236 offset:38912
	ds_read_b128 v[214:217], v236 offset:39936
	global_load_lds_dwordx4 v[226:227], off
	v_lshl_add_u64 v[226:227], s[4:5], 0, v[146:147]
	s_mov_b32 m0, s68
	s_nop 0
	global_load_lds_dwordx4 v[226:227], off
	s_waitcnt vmcnt(8)
	s_waitcnt lgkmcnt(0)
	s_barrier
	s_waitcnt lgkmcnt(0)
	v_mfma_i32_16x16x64_i8 v[118:121], v[130:133], v[186:189], v[118:121]
	v_mfma_i32_16x16x64_i8 v[102:105], v[162:165], v[186:189], v[102:105]
	v_mfma_i32_16x16x64_i8 v[114:117], v[130:133], v[194:197], v[114:117]
	v_mfma_i32_16x16x64_i8 v[98:101], v[162:165], v[194:197], v[98:101]
	v_mfma_i32_16x16x64_i8 v[126:129], v[130:133], v[202:205], v[126:129]
	v_mfma_i32_16x16x64_i8 v[110:113], v[162:165], v[202:205], v[110:113]
	v_mfma_i32_16x16x64_i8 v[122:125], v[130:133], v[210:213], v[122:125]
	v_mfma_i32_16x16x64_i8 v[106:109], v[162:165], v[210:213], v[106:109]
	v_mfma_i32_16x16x64_i8 v[118:121], v[134:137], v[190:193], v[118:121]
	v_mfma_i32_16x16x64_i8 v[102:105], v[166:169], v[190:193], v[102:105]
	v_mfma_i32_16x16x64_i8 v[114:117], v[134:137], v[198:201], v[114:117]
	v_mfma_i32_16x16x64_i8 v[98:101], v[166:169], v[198:201], v[98:101]
	v_mfma_i32_16x16x64_i8 v[126:129], v[134:137], v[206:209], v[126:129]
	v_mfma_i32_16x16x64_i8 v[110:113], v[166:169], v[206:209], v[110:113]
	v_mfma_i32_16x16x64_i8 v[122:125], v[134:137], v[214:217], v[122:125]
	v_mfma_i32_16x16x64_i8 v[106:109], v[166:169], v[214:217], v[106:109]
	v_mfma_i32_16x16x64_i8 v[86:89], v[170:173], v[186:189], v[86:89]
	v_mfma_i32_16x16x64_i8 v[70:73], v[178:181], v[186:189], v[70:73]
	v_mfma_i32_16x16x64_i8 v[82:85], v[170:173], v[194:197], v[82:85]
	v_mfma_i32_16x16x64_i8 v[66:69], v[178:181], v[194:197], v[66:69]
	v_mfma_i32_16x16x64_i8 v[94:97], v[170:173], v[202:205], v[94:97]
	v_mfma_i32_16x16x64_i8 v[78:81], v[178:181], v[202:205], v[78:81]
	v_mfma_i32_16x16x64_i8 v[90:93], v[170:173], v[210:213], v[90:93]
	v_mfma_i32_16x16x64_i8 v[74:77], v[178:181], v[210:213], v[74:77]
	v_mfma_i32_16x16x64_i8 v[86:89], v[174:177], v[190:193], v[86:89]
	v_mfma_i32_16x16x64_i8 v[70:73], v[182:185], v[190:193], v[70:73]
	v_mfma_i32_16x16x64_i8 v[82:85], v[174:177], v[198:201], v[82:85]
	v_mfma_i32_16x16x64_i8 v[66:69], v[182:185], v[198:201], v[66:69]
	v_mfma_i32_16x16x64_i8 v[94:97], v[174:177], v[206:209], v[94:97]
	v_mfma_i32_16x16x64_i8 v[78:81], v[182:185], v[206:209], v[78:81]
	v_mfma_i32_16x16x64_i8 v[90:93], v[174:177], v[214:217], v[90:93]
	s_setprio 3
	s_barrier
	v_mfma_i32_16x16x64_i8 v[74:77], v[182:185], v[214:217], v[74:77]
	s_setprio 0
	s_add_i32 s4, s81, s63
	v_lshl_add_u64 v[218:219], v[218:219], 0, s[22:23]
	s_mov_b32 m0, s4
	ds_read_b128 v[186:189], v236 offset:49152
	ds_read_b128 v[190:193], v236 offset:50176
	ds_read_b128 v[194:197], v236 offset:51200
	ds_read_b128 v[198:201], v236 offset:52224
	ds_read_b128 v[202:205], v236 offset:53248
	ds_read_b128 v[206:209], v236 offset:54272
	ds_read_b128 v[210:213], v236 offset:55296
	ds_read_b128 v[214:217], v236 offset:56320
	global_load_lds_dwordx4 v[218:219], off
	s_add_i32 m0, s4, 0x2000
	s_add_u32 s4, s18, 0x80080
	v_lshl_add_u64 v[218:219], v[220:221], 0, s[22:23]
	s_addc_u32 s5, s19, 0
	s_add_i32 s18, s82, s63
	global_load_lds_dwordx4 v[218:219], off
	v_lshl_add_u64 v[218:219], s[4:5], 0, v[144:145]
	s_mov_b32 m0, s18
	s_nop 0
	global_load_lds_dwordx4 v[218:219], off
	v_lshl_add_u64 v[218:219], s[4:5], 0, v[148:149]
	s_add_i32 m0, s18, 0x2000
	s_nop 0
	global_load_lds_dwordx4 v[218:219], off
	v_lshl_add_u64 v[218:219], v[222:223], 0, s[22:23]
	s_mov_b32 m0, s77
	s_nop 0
	global_load_lds_dwordx4 v[218:219], off
	v_lshl_add_u64 v[218:219], v[224:225], 0, s[22:23]
	s_mov_b32 m0, s78
	s_nop 0
	global_load_lds_dwordx4 v[218:219], off
	s_waitcnt vmcnt(8)
	s_waitcnt lgkmcnt(0)
	s_barrier
	s_waitcnt lgkmcnt(0)
	v_mfma_i32_16x16x64_i8 v[54:57], v[130:133], v[186:189], v[54:57]
	v_mfma_i32_16x16x64_i8 v[18:21], v[162:165], v[186:189], v[18:21]
	v_mfma_i32_16x16x64_i8 v[50:53], v[130:133], v[194:197], v[50:53]
	v_mfma_i32_16x16x64_i8 v[22:25], v[162:165], v[194:197], v[22:25]
	v_mfma_i32_16x16x64_i8 v[62:65], v[130:133], v[202:205], v[62:65]
	v_mfma_i32_16x16x64_i8 v[30:33], v[162:165], v[202:205], v[30:33]
	v_mfma_i32_16x16x64_i8 v[58:61], v[130:133], v[210:213], v[58:61]
	v_mfma_i32_16x16x64_i8 v[26:29], v[162:165], v[210:213], v[26:29]
	v_mfma_i32_16x16x64_i8 v[54:57], v[134:137], v[190:193], v[54:57]
	v_mfma_i32_16x16x64_i8 v[18:21], v[166:169], v[190:193], v[18:21]
	v_mfma_i32_16x16x64_i8 v[50:53], v[134:137], v[198:201], v[50:53]
	v_mfma_i32_16x16x64_i8 v[22:25], v[166:169], v[198:201], v[22:25]
	v_mfma_i32_16x16x64_i8 v[62:65], v[134:137], v[206:209], v[62:65]
	v_mfma_i32_16x16x64_i8 v[30:33], v[166:169], v[206:209], v[30:33]
	v_mfma_i32_16x16x64_i8 v[58:61], v[134:137], v[214:217], v[58:61]
	v_mfma_i32_16x16x64_i8 v[26:29], v[166:169], v[214:217], v[26:29]
	v_mfma_i32_16x16x64_i8 v[46:49], v[170:173], v[186:189], v[46:49]
	v_mfma_i32_16x16x64_i8 v[14:17], v[178:181], v[186:189], v[14:17]
	v_mfma_i32_16x16x64_i8 v[42:45], v[170:173], v[194:197], v[42:45]
	v_mfma_i32_16x16x64_i8 v[10:13], v[178:181], v[194:197], v[10:13]
	v_mfma_i32_16x16x64_i8 v[38:41], v[170:173], v[202:205], v[38:41]
	v_mfma_i32_16x16x64_i8 v[6:9], v[178:181], v[202:205], v[6:9]
	v_mfma_i32_16x16x64_i8 v[34:37], v[170:173], v[210:213], v[34:37]
	v_mfma_i32_16x16x64_i8 v[2:5], v[178:181], v[210:213], v[2:5]
	v_mfma_i32_16x16x64_i8 v[46:49], v[174:177], v[190:193], v[46:49]
	v_mfma_i32_16x16x64_i8 v[14:17], v[182:185], v[190:193], v[14:17]
	v_mfma_i32_16x16x64_i8 v[42:45], v[174:177], v[198:201], v[42:45]
	v_mfma_i32_16x16x64_i8 v[10:13], v[182:185], v[198:201], v[10:13]
	v_mfma_i32_16x16x64_i8 v[38:41], v[174:177], v[206:209], v[38:41]
	v_mfma_i32_16x16x64_i8 v[6:9], v[182:185], v[206:209], v[6:9]
	v_mfma_i32_16x16x64_i8 v[34:37], v[174:177], v[214:217], v[34:37]
	s_setprio 3
	s_barrier
	v_mfma_i32_16x16x64_i8 v[2:5], v[182:185], v[214:217], v[2:5]
	s_setprio 0
	s_add_i32 s80, s80, 2
	s_add_u32 vcc_hi, vcc_hi, 0x100
	s_addc_u32 s79, s79, 0
	s_cmp_gt_u32 s80, 29
	s_mov_b64 s[4:5], s[6:7]
.LBB0_1367:
	ds_read_b128 v[130:133], v234
	ds_read_b128 v[134:137], v234 offset:1024
	ds_read_b128 v[162:165], v234 offset:2048
	ds_read_b128 v[166:169], v234 offset:3072
	ds_read_b128 v[170:173], v235
	ds_read_b128 v[174:177], v235 offset:1024
	ds_read_b128 v[178:181], v235 offset:2048
	ds_read_b128 v[182:185], v235 offset:3072
	s_add_u32 s6, s4, 0x100
	s_addc_u32 s7, s5, 0
	s_cmp_eq_u32 s80, 28
	s_cselect_b32 s57, s35, s7
	s_cselect_b32 s56, s43, s6
	s_cselect_b32 s19, s31, s79
	s_cselect_b32 s18, vcc_lo, vcc_hi
	v_lshl_add_u64 v[218:219], s[4:5], 0, v[154:155]
	s_add_i32 m0, s65, 0xc000
	ds_read_b128 v[186:189], v236
	ds_read_b128 v[190:193], v236 offset:1024
	ds_read_b128 v[194:197], v236 offset:2048
	ds_read_b128 v[198:201], v236 offset:3072
	ds_read_b128 v[202:205], v236 offset:4096
	ds_read_b128 v[206:209], v236 offset:5120
	ds_read_b128 v[210:213], v236 offset:6144
	ds_read_b128 v[214:217], v236 offset:7168
	global_load_lds_dwordx4 v[218:219], off
	v_lshl_add_u64 v[218:219], s[4:5], 0, v[156:157]
	s_add_i32 m0, s65, 0xe000
	s_nop 0
	global_load_lds_dwordx4 v[218:219], off
	s_waitcnt vmcnt(8)
	s_waitcnt lgkmcnt(0)
	s_barrier
	s_waitcnt lgkmcnt(0)
	v_mfma_i32_16x16x64_i8 v[118:121], v[130:133], v[186:189], v[118:121]
	v_mfma_i32_16x16x64_i8 v[102:105], v[162:165], v[186:189], v[102:105]
	v_mfma_i32_16x16x64_i8 v[114:117], v[130:133], v[194:197], v[114:117]
	v_mfma_i32_16x16x64_i8 v[98:101], v[162:165], v[194:197], v[98:101]
	v_mfma_i32_16x16x64_i8 v[126:129], v[130:133], v[202:205], v[126:129]
	v_mfma_i32_16x16x64_i8 v[110:113], v[162:165], v[202:205], v[110:113]
	v_mfma_i32_16x16x64_i8 v[122:125], v[130:133], v[210:213], v[122:125]
	v_mfma_i32_16x16x64_i8 v[106:109], v[162:165], v[210:213], v[106:109]
	v_mfma_i32_16x16x64_i8 v[118:121], v[134:137], v[190:193], v[118:121]
	v_mfma_i32_16x16x64_i8 v[102:105], v[166:169], v[190:193], v[102:105]
	v_mfma_i32_16x16x64_i8 v[114:117], v[134:137], v[198:201], v[114:117]
	v_mfma_i32_16x16x64_i8 v[98:101], v[166:169], v[198:201], v[98:101]
	v_mfma_i32_16x16x64_i8 v[126:129], v[134:137], v[206:209], v[126:129]
	v_mfma_i32_16x16x64_i8 v[110:113], v[166:169], v[206:209], v[110:113]
	v_mfma_i32_16x16x64_i8 v[122:125], v[134:137], v[214:217], v[122:125]
	v_mfma_i32_16x16x64_i8 v[106:109], v[166:169], v[214:217], v[106:109]
	v_mfma_i32_16x16x64_i8 v[86:89], v[170:173], v[186:189], v[86:89]
	v_mfma_i32_16x16x64_i8 v[70:73], v[178:181], v[186:189], v[70:73]
	v_mfma_i32_16x16x64_i8 v[82:85], v[170:173], v[194:197], v[82:85]
	v_mfma_i32_16x16x64_i8 v[66:69], v[178:181], v[194:197], v[66:69]
	v_mfma_i32_16x16x64_i8 v[94:97], v[170:173], v[202:205], v[94:97]
	v_mfma_i32_16x16x64_i8 v[78:81], v[178:181], v[202:205], v[78:81]
	v_mfma_i32_16x16x64_i8 v[90:93], v[170:173], v[210:213], v[90:93]
	v_mfma_i32_16x16x64_i8 v[74:77], v[178:181], v[210:213], v[74:77]
	v_mfma_i32_16x16x64_i8 v[86:89], v[174:177], v[190:193], v[86:89]
	v_mfma_i32_16x16x64_i8 v[70:73], v[182:185], v[190:193], v[70:73]
	v_mfma_i32_16x16x64_i8 v[82:85], v[174:177], v[198:201], v[82:85]
	v_mfma_i32_16x16x64_i8 v[66:69], v[182:185], v[198:201], v[66:69]
	v_mfma_i32_16x16x64_i8 v[94:97], v[174:177], v[206:209], v[94:97]
	v_mfma_i32_16x16x64_i8 v[78:81], v[182:185], v[206:209], v[78:81]
	v_mfma_i32_16x16x64_i8 v[90:93], v[174:177], v[214:217], v[90:93]
	s_setprio 3
	s_barrier
	v_mfma_i32_16x16x64_i8 v[74:77], v[182:185], v[214:217], v[74:77]
	s_setprio 0
	s_add_i32 s4, s97, s63
	v_lshl_add_u64 v[218:219], s[18:19], 0, v[144:145]
	s_mov_b32 m0, s4
	ds_read_b128 v[186:189], v236 offset:16384
	ds_read_b128 v[190:193], v236 offset:17408
	ds_read_b128 v[194:197], v236 offset:18432
	ds_read_b128 v[198:201], v236 offset:19456
	ds_read_b128 v[202:205], v236 offset:20480
	ds_read_b128 v[206:209], v236 offset:21504
	ds_read_b128 v[210:213], v236 offset:22528
	ds_read_b128 v[214:217], v236 offset:23552
	global_load_lds_dwordx4 v[218:219], off
	s_add_i32 m0, s4, 0x2000
	s_add_u32 s4, s18, 0x80000
	v_lshl_add_u64 v[220:221], s[18:19], 0, v[148:149]
	s_addc_u32 s5, s19, 0
	s_add_i32 s81, s0, s63
	global_load_lds_dwordx4 v[220:221], off
	v_lshl_add_u64 v[222:223], s[4:5], 0, v[144:145]
	s_mov_b32 m0, s81
	v_lshl_add_u64 v[224:225], s[56:57], 0, v[146:147]
	global_load_lds_dwordx4 v[222:223], off
	v_lshl_add_u64 v[222:223], s[4:5], 0, v[148:149]
	s_add_i32 m0, s81, 0x2000
	s_nop 0
	global_load_lds_dwordx4 v[222:223], off
	v_lshl_add_u64 v[222:223], s[56:57], 0, v[142:143]
	s_mov_b32 m0, s65
	s_nop 0
	global_load_lds_dwordx4 v[222:223], off
	s_mov_b32 m0, s66
	s_nop 0
	global_load_lds_dwordx4 v[224:225], off
	s_waitcnt vmcnt(8)
	s_waitcnt lgkmcnt(0)
	s_barrier
	s_waitcnt lgkmcnt(0)
	v_mfma_i32_16x16x64_i8 v[54:57], v[130:133], v[186:189], v[54:57]
	v_mfma_i32_16x16x64_i8 v[18:21], v[162:165], v[186:189], v[18:21]
	v_mfma_i32_16x16x64_i8 v[50:53], v[130:133], v[194:197], v[50:53]
	v_mfma_i32_16x16x64_i8 v[22:25], v[162:165], v[194:197], v[22:25]
	v_mfma_i32_16x16x64_i8 v[62:65], v[130:133], v[202:205], v[62:65]
	v_mfma_i32_16x16x64_i8 v[30:33], v[162:165], v[202:205], v[30:33]
	v_mfma_i32_16x16x64_i8 v[58:61], v[130:133], v[210:213], v[58:61]
	v_mfma_i32_16x16x64_i8 v[26:29], v[162:165], v[210:213], v[26:29]
	v_mfma_i32_16x16x64_i8 v[54:57], v[134:137], v[190:193], v[54:57]
	v_mfma_i32_16x16x64_i8 v[18:21], v[166:169], v[190:193], v[18:21]
	v_mfma_i32_16x16x64_i8 v[50:53], v[134:137], v[198:201], v[50:53]
	v_mfma_i32_16x16x64_i8 v[22:25], v[166:169], v[198:201], v[22:25]
	v_mfma_i32_16x16x64_i8 v[62:65], v[134:137], v[206:209], v[62:65]
	v_mfma_i32_16x16x64_i8 v[30:33], v[166:169], v[206:209], v[30:33]
	v_mfma_i32_16x16x64_i8 v[58:61], v[134:137], v[214:217], v[58:61]
	v_mfma_i32_16x16x64_i8 v[26:29], v[166:169], v[214:217], v[26:29]
	v_mfma_i32_16x16x64_i8 v[46:49], v[170:173], v[186:189], v[46:49]
	v_mfma_i32_16x16x64_i8 v[14:17], v[178:181], v[186:189], v[14:17]
	v_mfma_i32_16x16x64_i8 v[42:45], v[170:173], v[194:197], v[42:45]
	v_mfma_i32_16x16x64_i8 v[10:13], v[178:181], v[194:197], v[10:13]
	v_mfma_i32_16x16x64_i8 v[38:41], v[170:173], v[202:205], v[38:41]
	v_mfma_i32_16x16x64_i8 v[6:9], v[178:181], v[202:205], v[6:9]
	v_mfma_i32_16x16x64_i8 v[34:37], v[170:173], v[210:213], v[34:37]
	v_mfma_i32_16x16x64_i8 v[2:5], v[178:181], v[210:213], v[2:5]
	v_mfma_i32_16x16x64_i8 v[46:49], v[174:177], v[190:193], v[46:49]
	v_mfma_i32_16x16x64_i8 v[14:17], v[182:185], v[190:193], v[14:17]
	v_mfma_i32_16x16x64_i8 v[42:45], v[174:177], v[198:201], v[42:45]
	v_mfma_i32_16x16x64_i8 v[10:13], v[182:185], v[198:201], v[10:13]
	v_mfma_i32_16x16x64_i8 v[38:41], v[174:177], v[206:209], v[38:41]
	v_mfma_i32_16x16x64_i8 v[6:9], v[182:185], v[206:209], v[6:9]
	v_mfma_i32_16x16x64_i8 v[34:37], v[174:177], v[214:217], v[34:37]
	s_setprio 3
	s_barrier
	v_mfma_i32_16x16x64_i8 v[2:5], v[182:185], v[214:217], v[2:5]
	s_setprio 0
	s_add_i32 s81, 0, 0x18000
	s_add_i32 s82, 0, 0x1c000
	v_add_u32_e32 v166, s81, v232
	v_add_u32_e32 v182, s82, v232
	ds_read_b128 v[130:133], v166
	ds_read_b128 v[134:137], v166 offset:1024
	ds_read_b128 v[162:165], v166 offset:2048
	ds_read_b128 v[166:169], v166 offset:3072
	ds_read_b128 v[170:173], v182
	ds_read_b128 v[174:177], v182 offset:1024
	ds_read_b128 v[178:181], v182 offset:2048
	ds_read_b128 v[182:185], v182 offset:3072
	s_add_u32 s4, s56, 0x80000
	s_addc_u32 s5, s57, 0
	s_mov_b32 m0, s67
	v_lshl_add_u64 v[226:227], s[4:5], 0, v[142:143]
	ds_read_b128 v[186:189], v236 offset:32768
	ds_read_b128 v[190:193], v236 offset:33792
	ds_read_b128 v[194:197], v236 offset:34816
	ds_read_b128 v[198:201], v236 offset:35840
	ds_read_b128 v[202:205], v236 offset:36864
	ds_read_b128 v[206:209], v236 offset:37888
	ds_read_b128 v[210:213], v236 offset:38912
	ds_read_b128 v[214:217], v236 offset:39936
	global_load_lds_dwordx4 v[226:227], off
	v_lshl_add_u64 v[226:227], s[4:5], 0, v[146:147]
	s_mov_b32 m0, s68
	s_nop 0
	global_load_lds_dwordx4 v[226:227], off
	s_waitcnt vmcnt(8)
	s_waitcnt lgkmcnt(0)
	s_barrier
	s_waitcnt lgkmcnt(0)
	v_mfma_i32_16x16x64_i8 v[118:121], v[130:133], v[186:189], v[118:121]
	v_mfma_i32_16x16x64_i8 v[102:105], v[162:165], v[186:189], v[102:105]
	v_mfma_i32_16x16x64_i8 v[114:117], v[130:133], v[194:197], v[114:117]
	v_mfma_i32_16x16x64_i8 v[98:101], v[162:165], v[194:197], v[98:101]
	v_mfma_i32_16x16x64_i8 v[126:129], v[130:133], v[202:205], v[126:129]
	v_mfma_i32_16x16x64_i8 v[110:113], v[162:165], v[202:205], v[110:113]
	v_mfma_i32_16x16x64_i8 v[122:125], v[130:133], v[210:213], v[122:125]
	v_mfma_i32_16x16x64_i8 v[106:109], v[162:165], v[210:213], v[106:109]
	v_mfma_i32_16x16x64_i8 v[118:121], v[134:137], v[190:193], v[118:121]
	v_mfma_i32_16x16x64_i8 v[102:105], v[166:169], v[190:193], v[102:105]
	v_mfma_i32_16x16x64_i8 v[114:117], v[134:137], v[198:201], v[114:117]
	v_mfma_i32_16x16x64_i8 v[98:101], v[166:169], v[198:201], v[98:101]
	v_mfma_i32_16x16x64_i8 v[126:129], v[134:137], v[206:209], v[126:129]
	v_mfma_i32_16x16x64_i8 v[110:113], v[166:169], v[206:209], v[110:113]
	v_mfma_i32_16x16x64_i8 v[122:125], v[134:137], v[214:217], v[122:125]
	v_mfma_i32_16x16x64_i8 v[106:109], v[166:169], v[214:217], v[106:109]
	v_mfma_i32_16x16x64_i8 v[86:89], v[170:173], v[186:189], v[86:89]
	v_mfma_i32_16x16x64_i8 v[70:73], v[178:181], v[186:189], v[70:73]
	v_mfma_i32_16x16x64_i8 v[82:85], v[170:173], v[194:197], v[82:85]
	v_mfma_i32_16x16x64_i8 v[66:69], v[178:181], v[194:197], v[66:69]
	v_mfma_i32_16x16x64_i8 v[94:97], v[170:173], v[202:205], v[94:97]
	v_mfma_i32_16x16x64_i8 v[78:81], v[178:181], v[202:205], v[78:81]
	v_mfma_i32_16x16x64_i8 v[90:93], v[170:173], v[210:213], v[90:93]
	v_mfma_i32_16x16x64_i8 v[74:77], v[178:181], v[210:213], v[74:77]
	v_mfma_i32_16x16x64_i8 v[86:89], v[174:177], v[190:193], v[86:89]
	v_mfma_i32_16x16x64_i8 v[70:73], v[182:185], v[190:193], v[70:73]
	v_mfma_i32_16x16x64_i8 v[82:85], v[174:177], v[198:201], v[82:85]
	v_mfma_i32_16x16x64_i8 v[66:69], v[182:185], v[198:201], v[66:69]
	v_mfma_i32_16x16x64_i8 v[94:97], v[174:177], v[206:209], v[94:97]
	v_mfma_i32_16x16x64_i8 v[78:81], v[182:185], v[206:209], v[78:81]
	v_mfma_i32_16x16x64_i8 v[90:93], v[174:177], v[214:217], v[90:93]
	s_setprio 3
	s_barrier
	v_mfma_i32_16x16x64_i8 v[74:77], v[182:185], v[214:217], v[74:77]
	s_setprio 0
	s_add_i32 s4, s81, s63
	v_lshl_add_u64 v[218:219], v[218:219], 0, s[22:23]
	s_mov_b32 m0, s4
	ds_read_b128 v[186:189], v236 offset:49152
	ds_read_b128 v[190:193], v236 offset:50176
	ds_read_b128 v[194:197], v236 offset:51200
	ds_read_b128 v[198:201], v236 offset:52224
	ds_read_b128 v[202:205], v236 offset:53248
	ds_read_b128 v[206:209], v236 offset:54272
	ds_read_b128 v[210:213], v236 offset:55296
	ds_read_b128 v[214:217], v236 offset:56320
	global_load_lds_dwordx4 v[218:219], off
	s_add_i32 m0, s4, 0x2000
	s_add_u32 s4, s18, 0x80080
	v_lshl_add_u64 v[218:219], v[220:221], 0, s[22:23]
	s_addc_u32 s5, s19, 0
	s_add_i32 s18, s82, s63
	global_load_lds_dwordx4 v[218:219], off
	v_lshl_add_u64 v[218:219], s[4:5], 0, v[144:145]
	s_mov_b32 m0, s18
	s_nop 0
	global_load_lds_dwordx4 v[218:219], off
	v_lshl_add_u64 v[218:219], s[4:5], 0, v[148:149]
	s_add_i32 m0, s18, 0x2000
	s_nop 0
	global_load_lds_dwordx4 v[218:219], off
	v_lshl_add_u64 v[218:219], v[222:223], 0, s[22:23]
	s_mov_b32 m0, s77
	s_nop 0
	global_load_lds_dwordx4 v[218:219], off
	v_lshl_add_u64 v[218:219], v[224:225], 0, s[22:23]
	s_mov_b32 m0, s78
	s_nop 0
	global_load_lds_dwordx4 v[218:219], off
	s_waitcnt vmcnt(8)
	s_waitcnt lgkmcnt(0)
	s_barrier
	s_waitcnt lgkmcnt(0)
	v_mfma_i32_16x16x64_i8 v[54:57], v[130:133], v[186:189], v[54:57]
	v_mfma_i32_16x16x64_i8 v[18:21], v[162:165], v[186:189], v[18:21]
	v_mfma_i32_16x16x64_i8 v[50:53], v[130:133], v[194:197], v[50:53]
	v_mfma_i32_16x16x64_i8 v[22:25], v[162:165], v[194:197], v[22:25]
	v_mfma_i32_16x16x64_i8 v[62:65], v[130:133], v[202:205], v[62:65]
	v_mfma_i32_16x16x64_i8 v[30:33], v[162:165], v[202:205], v[30:33]
	v_mfma_i32_16x16x64_i8 v[58:61], v[130:133], v[210:213], v[58:61]
	v_mfma_i32_16x16x64_i8 v[26:29], v[162:165], v[210:213], v[26:29]
	v_mfma_i32_16x16x64_i8 v[54:57], v[134:137], v[190:193], v[54:57]
	v_mfma_i32_16x16x64_i8 v[18:21], v[166:169], v[190:193], v[18:21]
	v_mfma_i32_16x16x64_i8 v[50:53], v[134:137], v[198:201], v[50:53]
	v_mfma_i32_16x16x64_i8 v[22:25], v[166:169], v[198:201], v[22:25]
	v_mfma_i32_16x16x64_i8 v[62:65], v[134:137], v[206:209], v[62:65]
	v_mfma_i32_16x16x64_i8 v[30:33], v[166:169], v[206:209], v[30:33]
	v_mfma_i32_16x16x64_i8 v[58:61], v[134:137], v[214:217], v[58:61]
	v_mfma_i32_16x16x64_i8 v[26:29], v[166:169], v[214:217], v[26:29]
	v_mfma_i32_16x16x64_i8 v[46:49], v[170:173], v[186:189], v[46:49]
	v_mfma_i32_16x16x64_i8 v[14:17], v[178:181], v[186:189], v[14:17]
	v_mfma_i32_16x16x64_i8 v[42:45], v[170:173], v[194:197], v[42:45]
	v_mfma_i32_16x16x64_i8 v[10:13], v[178:181], v[194:197], v[10:13]
	v_mfma_i32_16x16x64_i8 v[38:41], v[170:173], v[202:205], v[38:41]
	v_mfma_i32_16x16x64_i8 v[6:9], v[178:181], v[202:205], v[6:9]
	v_mfma_i32_16x16x64_i8 v[34:37], v[170:173], v[210:213], v[34:37]
	v_mfma_i32_16x16x64_i8 v[2:5], v[178:181], v[210:213], v[2:5]
	v_mfma_i32_16x16x64_i8 v[46:49], v[174:177], v[190:193], v[46:49]
	v_mfma_i32_16x16x64_i8 v[14:17], v[182:185], v[190:193], v[14:17]
	v_mfma_i32_16x16x64_i8 v[42:45], v[174:177], v[198:201], v[42:45]
	v_mfma_i32_16x16x64_i8 v[10:13], v[182:185], v[198:201], v[10:13]
	v_mfma_i32_16x16x64_i8 v[38:41], v[174:177], v[206:209], v[38:41]
	v_mfma_i32_16x16x64_i8 v[6:9], v[182:185], v[206:209], v[6:9]
	v_mfma_i32_16x16x64_i8 v[34:37], v[174:177], v[214:217], v[34:37]
	s_setprio 3
	s_barrier
	v_mfma_i32_16x16x64_i8 v[2:5], v[182:185], v[214:217], v[2:5]
	s_setprio 0
	s_add_i32 s80, s80, 2
	s_add_u32 vcc_hi, vcc_hi, 0x100
	s_addc_u32 s79, s79, 0
	s_cmp_gt_u32 s80, 29
	s_mov_b64 s[4:5], s[6:7]
	s_cbranch_scc0 .LBB0_1367
	s_and_b64 vcc, exec, s[10:11]
	s_cbranch_vccz .LBB0_1370
	s_barrier

.LBB0_1553:
	s_add_u32 s64, s26, 0x100
	s_addc_u32 s65, s27, 0
	s_mov_b32 s66, -2
	s_waitcnt lgkmcnt(0)
	ds_read_b128 v[114:117], v247
	ds_read_b128 v[118:121], v247 offset:1024
	ds_read_b128 v[126:129], v247 offset:2048
	ds_read_b128 v[134:137], v247 offset:3072
	ds_read_b128 v[138:141], v248
	ds_read_b128 v[142:145], v248 offset:1024
	ds_read_b128 v[154:157], v248 offset:2048
	ds_read_b128 v[158:161], v248 offset:3072
	s_add_u32 s4, s18, 0x100
	s_addc_u32 s5, s19, 0
	s_cmpk_eq_i32 s66, 0xdc
	s_cselect_b32 s29, s23, s5
	s_cselect_b32 s28, s22, s4
	s_cselect_b32 s27, s25, s65
	s_cselect_b32 s26, s24, s64
	v_lshl_add_u64 v[210:211], s[18:19], 0, v[202:203]
	s_add_i32 m0, s17, 0xc000
	ds_read_b128 v[162:165], v249
	ds_read_b128 v[166:169], v249 offset:1024
	ds_read_b128 v[170:173], v249 offset:2048
	ds_read_b128 v[174:177], v249 offset:3072
	ds_read_b128 v[178:181], v249 offset:4096
	ds_read_b128 v[182:185], v249 offset:5120
	ds_read_b128 v[186:189], v249 offset:6144
	ds_read_b128 v[190:193], v249 offset:7168
	global_load_lds_dwordx4 v[210:211], off
	v_lshl_add_u64 v[210:211], s[18:19], 0, v[204:205]
	s_add_i32 m0, s17, 0xe000
	s_nop 0
	global_load_lds_dwordx4 v[210:211], off
	s_waitcnt vmcnt(8)
	s_waitcnt lgkmcnt(0)
	s_barrier
	s_waitcnt lgkmcnt(0)
	v_mfma_f32_16x16x32_bf16 v[150:153], v[114:117], v[162:165], 0
	v_mfma_f32_16x16x32_bf16 v[146:149], v[126:129], v[162:165], 0
	v_mfma_f32_16x16x32_bf16 v[110:113], v[114:117], v[170:173], 0
	v_mfma_f32_16x16x32_bf16 v[106:109], v[126:129], v[170:173], 0
	v_mfma_f32_16x16x32_bf16 v[94:97], v[114:117], v[178:181], 0
	v_mfma_f32_16x16x32_bf16 v[90:93], v[126:129], v[178:181], 0
	v_mfma_f32_16x16x32_bf16 v[78:81], v[114:117], v[186:189], 0
	v_mfma_f32_16x16x32_bf16 v[74:77], v[126:129], v[186:189], 0
	v_mfma_f32_16x16x32_bf16 v[150:153], v[118:121], v[166:169], v[150:153]
	v_mfma_f32_16x16x32_bf16 v[146:149], v[134:137], v[166:169], v[146:149]
	v_mfma_f32_16x16x32_bf16 v[110:113], v[118:121], v[174:177], v[110:113]
	v_mfma_f32_16x16x32_bf16 v[106:109], v[134:137], v[174:177], v[106:109]
	v_mfma_f32_16x16x32_bf16 v[94:97], v[118:121], v[182:185], v[94:97]
	v_mfma_f32_16x16x32_bf16 v[90:93], v[134:137], v[182:185], v[90:93]
	v_mfma_f32_16x16x32_bf16 v[78:81], v[118:121], v[190:193], v[78:81]
	v_mfma_f32_16x16x32_bf16 v[74:77], v[134:137], v[190:193], v[74:77]
	v_mfma_f32_16x16x32_bf16 v[130:133], v[138:141], v[162:165], 0
	v_mfma_f32_16x16x32_bf16 v[122:125], v[154:157], v[162:165], 0
	v_mfma_f32_16x16x32_bf16 v[102:105], v[138:141], v[170:173], 0
	v_mfma_f32_16x16x32_bf16 v[98:101], v[154:157], v[170:173], 0
	v_mfma_f32_16x16x32_bf16 v[86:89], v[138:141], v[178:181], 0
	v_mfma_f32_16x16x32_bf16 v[82:85], v[154:157], v[178:181], 0
	v_mfma_f32_16x16x32_bf16 v[70:73], v[138:141], v[186:189], 0
	v_mfma_f32_16x16x32_bf16 v[66:69], v[154:157], v[186:189], 0
	v_mfma_f32_16x16x32_bf16 v[130:133], v[142:145], v[166:169], v[130:133]
	v_mfma_f32_16x16x32_bf16 v[122:125], v[158:161], v[166:169], v[122:125]
	v_mfma_f32_16x16x32_bf16 v[102:105], v[142:145], v[174:177], v[102:105]
	v_mfma_f32_16x16x32_bf16 v[98:101], v[158:161], v[174:177], v[98:101]
	v_mfma_f32_16x16x32_bf16 v[86:89], v[142:145], v[182:185], v[86:89]
	v_mfma_f32_16x16x32_bf16 v[82:85], v[158:161], v[182:185], v[82:85]
	v_mfma_f32_16x16x32_bf16 v[70:73], v[142:145], v[190:193], v[70:73]
	s_setprio 3
	s_barrier
	v_mfma_f32_16x16x32_bf16 v[66:69], v[158:161], v[190:193], v[66:69]
	s_setprio 0
	s_add_i32 s18, s42, s16
	v_lshl_add_u64 v[210:211], s[26:27], 0, v[196:197]
	s_mov_b32 m0, s18
	ds_read_b128 v[162:165], v249 offset:16384
	ds_read_b128 v[166:169], v249 offset:17408
	ds_read_b128 v[170:173], v249 offset:18432
	ds_read_b128 v[174:177], v249 offset:19456
	ds_read_b128 v[178:181], v249 offset:20480
	ds_read_b128 v[182:185], v249 offset:21504
	ds_read_b128 v[186:189], v249 offset:22528
	ds_read_b128 v[190:193], v249 offset:23552
	global_load_lds_dwordx4 v[210:211], off
	s_add_i32 m0, s18, 0x2000
	s_add_u32 s18, s26, 0x380000
	v_lshl_add_u64 v[212:213], s[26:27], 0, v[200:201]
	s_addc_u32 s19, s27, 0
	s_add_i32 s67, s43, s16
	global_load_lds_dwordx4 v[212:213], off
	v_lshl_add_u64 v[214:215], s[18:19], 0, v[196:197]
	s_mov_b32 m0, s67
	v_lshl_add_u64 v[216:217], s[28:29], 0, v[198:199]
	global_load_lds_dwordx4 v[214:215], off
	v_lshl_add_u64 v[214:215], s[18:19], 0, v[200:201]
	s_add_i32 m0, s67, 0x2000
	s_nop 0
	global_load_lds_dwordx4 v[214:215], off
	v_lshl_add_u64 v[214:215], s[28:29], 0, v[194:195]
	s_mov_b32 m0, s17
	s_nop 0
	global_load_lds_dwordx4 v[214:215], off
	s_mov_b32 m0, s30
	s_nop 0
	global_load_lds_dwordx4 v[216:217], off
	s_waitcnt vmcnt(8)
	s_waitcnt lgkmcnt(0)
	s_barrier
	s_waitcnt lgkmcnt(0)
	v_mfma_f32_16x16x32_bf16 v[62:65], v[114:117], v[162:165], 0
	v_mfma_f32_16x16x32_bf16 v[58:61], v[126:129], v[162:165], 0
	v_mfma_f32_16x16x32_bf16 v[46:49], v[114:117], v[170:173], 0
	v_mfma_f32_16x16x32_bf16 v[42:45], v[126:129], v[170:173], 0
	v_mfma_f32_16x16x32_bf16 v[30:33], v[114:117], v[178:181], 0
	v_mfma_f32_16x16x32_bf16 v[26:29], v[126:129], v[178:181], 0
	v_mfma_f32_16x16x32_bf16 v[14:17], v[114:117], v[186:189], 0
	v_mfma_f32_16x16x32_bf16 v[10:13], v[126:129], v[186:189], 0
	v_mfma_f32_16x16x32_bf16 v[62:65], v[118:121], v[166:169], v[62:65]
	v_mfma_f32_16x16x32_bf16 v[58:61], v[134:137], v[166:169], v[58:61]
	v_mfma_f32_16x16x32_bf16 v[46:49], v[118:121], v[174:177], v[46:49]
	v_mfma_f32_16x16x32_bf16 v[42:45], v[134:137], v[174:177], v[42:45]
	v_mfma_f32_16x16x32_bf16 v[30:33], v[118:121], v[182:185], v[30:33]
	v_mfma_f32_16x16x32_bf16 v[26:29], v[134:137], v[182:185], v[26:29]
	v_mfma_f32_16x16x32_bf16 v[14:17], v[118:121], v[190:193], v[14:17]
	v_mfma_f32_16x16x32_bf16 v[10:13], v[134:137], v[190:193], v[10:13]
	v_mfma_f32_16x16x32_bf16 v[54:57], v[138:141], v[162:165], 0
	v_mfma_f32_16x16x32_bf16 v[50:53], v[154:157], v[162:165], 0
	v_mfma_f32_16x16x32_bf16 v[38:41], v[138:141], v[170:173], 0
	v_mfma_f32_16x16x32_bf16 v[34:37], v[154:157], v[170:173], 0
	v_mfma_f32_16x16x32_bf16 v[22:25], v[138:141], v[178:181], 0
	v_mfma_f32_16x16x32_bf16 v[18:21], v[154:157], v[178:181], 0
	v_mfma_f32_16x16x32_bf16 v[6:9], v[138:141], v[186:189], 0
	v_mfma_f32_16x16x32_bf16 v[2:5], v[154:157], v[186:189], 0
	v_mfma_f32_16x16x32_bf16 v[54:57], v[142:145], v[166:169], v[54:57]
	v_mfma_f32_16x16x32_bf16 v[50:53], v[158:161], v[166:169], v[50:53]
	v_mfma_f32_16x16x32_bf16 v[38:41], v[142:145], v[174:177], v[38:41]
	v_mfma_f32_16x16x32_bf16 v[34:37], v[158:161], v[174:177], v[34:37]
	v_mfma_f32_16x16x32_bf16 v[22:25], v[142:145], v[182:185], v[22:25]
	v_mfma_f32_16x16x32_bf16 v[18:21], v[158:161], v[182:185], v[18:21]
	v_mfma_f32_16x16x32_bf16 v[6:9], v[142:145], v[190:193], v[6:9]
	s_setprio 3
	s_barrier
	v_mfma_f32_16x16x32_bf16 v[2:5], v[158:161], v[190:193], v[2:5]
	s_setprio 0
	s_add_i32 s67, 0, 0x18000
	s_add_i32 s68, 0, 0x1c000
	v_add_u32_e32 v134, s67, v244
	v_add_u32_e32 v158, s68, v244
	ds_read_b128 v[114:117], v134
	ds_read_b128 v[118:121], v134 offset:1024
	ds_read_b128 v[126:129], v134 offset:2048
	ds_read_b128 v[134:137], v134 offset:3072
	ds_read_b128 v[138:141], v158
	ds_read_b128 v[142:145], v158 offset:1024
	ds_read_b128 v[154:157], v158 offset:2048
	ds_read_b128 v[158:161], v158 offset:3072
	s_add_u32 s18, s28, 0x380000
	s_addc_u32 s19, s29, 0
	s_mov_b32 m0, s31
	v_lshl_add_u64 v[218:219], s[18:19], 0, v[194:195]
	ds_read_b128 v[162:165], v249 offset:32768
	ds_read_b128 v[166:169], v249 offset:33792
	ds_read_b128 v[170:173], v249 offset:34816
	ds_read_b128 v[174:177], v249 offset:35840
	ds_read_b128 v[178:181], v249 offset:36864
	ds_read_b128 v[182:185], v249 offset:37888
	ds_read_b128 v[186:189], v249 offset:38912
	ds_read_b128 v[190:193], v249 offset:39936
	global_load_lds_dwordx4 v[218:219], off
	v_lshl_add_u64 v[218:219], s[18:19], 0, v[198:199]
	s_mov_b32 m0, s34
	s_nop 0
	global_load_lds_dwordx4 v[218:219], off
	s_waitcnt vmcnt(8)
	s_waitcnt lgkmcnt(0)
	s_barrier
	s_waitcnt lgkmcnt(0)
	v_mfma_f32_16x16x32_bf16 v[150:153], v[114:117], v[162:165], v[150:153]
	v_mfma_f32_16x16x32_bf16 v[146:149], v[126:129], v[162:165], v[146:149]
	v_mfma_f32_16x16x32_bf16 v[110:113], v[114:117], v[170:173], v[110:113]
	v_mfma_f32_16x16x32_bf16 v[106:109], v[126:129], v[170:173], v[106:109]
	v_mfma_f32_16x16x32_bf16 v[94:97], v[114:117], v[178:181], v[94:97]
	v_mfma_f32_16x16x32_bf16 v[90:93], v[126:129], v[178:181], v[90:93]
	v_mfma_f32_16x16x32_bf16 v[78:81], v[114:117], v[186:189], v[78:81]
	v_mfma_f32_16x16x32_bf16 v[74:77], v[126:129], v[186:189], v[74:77]
	v_mfma_f32_16x16x32_bf16 v[150:153], v[118:121], v[166:169], v[150:153]
	v_mfma_f32_16x16x32_bf16 v[146:149], v[134:137], v[166:169], v[146:149]
	v_mfma_f32_16x16x32_bf16 v[110:113], v[118:121], v[174:177], v[110:113]
	v_mfma_f32_16x16x32_bf16 v[106:109], v[134:137], v[174:177], v[106:109]
	v_mfma_f32_16x16x32_bf16 v[94:97], v[118:121], v[182:185], v[94:97]
	v_mfma_f32_16x16x32_bf16 v[90:93], v[134:137], v[182:185], v[90:93]
	v_mfma_f32_16x16x32_bf16 v[78:81], v[118:121], v[190:193], v[78:81]
	v_mfma_f32_16x16x32_bf16 v[74:77], v[134:137], v[190:193], v[74:77]
	v_mfma_f32_16x16x32_bf16 v[130:133], v[138:141], v[162:165], v[130:133]
	v_mfma_f32_16x16x32_bf16 v[122:125], v[154:157], v[162:165], v[122:125]
	v_mfma_f32_16x16x32_bf16 v[102:105], v[138:141], v[170:173], v[102:105]
	v_mfma_f32_16x16x32_bf16 v[98:101], v[154:157], v[170:173], v[98:101]
	v_mfma_f32_16x16x32_bf16 v[86:89], v[138:141], v[178:181], v[86:89]
	v_mfma_f32_16x16x32_bf16 v[82:85], v[154:157], v[178:181], v[82:85]
	v_mfma_f32_16x16x32_bf16 v[70:73], v[138:141], v[186:189], v[70:73]
	v_mfma_f32_16x16x32_bf16 v[66:69], v[154:157], v[186:189], v[66:69]
	v_mfma_f32_16x16x32_bf16 v[130:133], v[142:145], v[166:169], v[130:133]
	v_mfma_f32_16x16x32_bf16 v[122:125], v[158:161], v[166:169], v[122:125]
	v_mfma_f32_16x16x32_bf16 v[102:105], v[142:145], v[174:177], v[102:105]
	v_mfma_f32_16x16x32_bf16 v[98:101], v[158:161], v[174:177], v[98:101]
	v_mfma_f32_16x16x32_bf16 v[86:89], v[142:145], v[182:185], v[86:89]
	v_mfma_f32_16x16x32_bf16 v[82:85], v[158:161], v[182:185], v[82:85]
	v_mfma_f32_16x16x32_bf16 v[70:73], v[142:145], v[190:193], v[70:73]
	s_setprio 3
	s_barrier
	v_mfma_f32_16x16x32_bf16 v[66:69], v[158:161], v[190:193], v[66:69]
	s_setprio 0
	s_add_i32 s18, s67, s16
	v_lshl_add_u64 v[210:211], v[210:211], 0, s[12:13]
	s_mov_b32 m0, s18
	ds_read_b128 v[162:165], v249 offset:49152
	ds_read_b128 v[166:169], v249 offset:50176
	ds_read_b128 v[170:173], v249 offset:51200
	ds_read_b128 v[174:177], v249 offset:52224
	ds_read_b128 v[178:181], v249 offset:53248
	ds_read_b128 v[182:185], v249 offset:54272
	ds_read_b128 v[186:189], v249 offset:55296
	ds_read_b128 v[190:193], v249 offset:56320
	global_load_lds_dwordx4 v[210:211], off
	s_add_i32 m0, s18, 0x2000
	s_add_u32 s18, s26, 0x380080
	v_lshl_add_u64 v[210:211], v[212:213], 0, s[12:13]
	s_addc_u32 s19, s27, 0
	s_add_i32 s26, s68, s16
	global_load_lds_dwordx4 v[210:211], off
	v_lshl_add_u64 v[210:211], s[18:19], 0, v[196:197]
	s_mov_b32 m0, s26
	s_nop 0
	global_load_lds_dwordx4 v[210:211], off
	v_lshl_add_u64 v[210:211], s[18:19], 0, v[200:201]
	s_add_i32 m0, s26, 0x2000
	s_nop 0
	global_load_lds_dwordx4 v[210:211], off
	v_lshl_add_u64 v[210:211], v[214:215], 0, s[12:13]
	s_mov_b32 m0, s38
	s_nop 0
	global_load_lds_dwordx4 v[210:211], off
	v_lshl_add_u64 v[210:211], v[216:217], 0, s[12:13]
	s_mov_b32 m0, s39
	s_nop 0
	global_load_lds_dwordx4 v[210:211], off
	s_waitcnt vmcnt(8)
	s_waitcnt lgkmcnt(0)
	s_barrier
	s_waitcnt lgkmcnt(0)
	v_mfma_f32_16x16x32_bf16 v[62:65], v[114:117], v[162:165], v[62:65]
	v_mfma_f32_16x16x32_bf16 v[58:61], v[126:129], v[162:165], v[58:61]
	v_mfma_f32_16x16x32_bf16 v[46:49], v[114:117], v[170:173], v[46:49]
	v_mfma_f32_16x16x32_bf16 v[42:45], v[126:129], v[170:173], v[42:45]
	v_mfma_f32_16x16x32_bf16 v[30:33], v[114:117], v[178:181], v[30:33]
	v_mfma_f32_16x16x32_bf16 v[26:29], v[126:129], v[178:181], v[26:29]
	v_mfma_f32_16x16x32_bf16 v[14:17], v[114:117], v[186:189], v[14:17]
	v_mfma_f32_16x16x32_bf16 v[10:13], v[126:129], v[186:189], v[10:13]
	v_mfma_f32_16x16x32_bf16 v[62:65], v[118:121], v[166:169], v[62:65]
	v_mfma_f32_16x16x32_bf16 v[58:61], v[134:137], v[166:169], v[58:61]
	v_mfma_f32_16x16x32_bf16 v[46:49], v[118:121], v[174:177], v[46:49]
	v_mfma_f32_16x16x32_bf16 v[42:45], v[134:137], v[174:177], v[42:45]
	v_mfma_f32_16x16x32_bf16 v[30:33], v[118:121], v[182:185], v[30:33]
	v_mfma_f32_16x16x32_bf16 v[26:29], v[134:137], v[182:185], v[26:29]
	v_mfma_f32_16x16x32_bf16 v[14:17], v[118:121], v[190:193], v[14:17]
	v_mfma_f32_16x16x32_bf16 v[10:13], v[134:137], v[190:193], v[10:13]
	v_mfma_f32_16x16x32_bf16 v[54:57], v[138:141], v[162:165], v[54:57]
	v_mfma_f32_16x16x32_bf16 v[50:53], v[154:157], v[162:165], v[50:53]
	v_mfma_f32_16x16x32_bf16 v[38:41], v[138:141], v[170:173], v[38:41]
	v_mfma_f32_16x16x32_bf16 v[34:37], v[154:157], v[170:173], v[34:37]
	v_mfma_f32_16x16x32_bf16 v[22:25], v[138:141], v[178:181], v[22:25]
	v_mfma_f32_16x16x32_bf16 v[18:21], v[154:157], v[178:181], v[18:21]
	v_mfma_f32_16x16x32_bf16 v[6:9], v[138:141], v[186:189], v[6:9]
	v_mfma_f32_16x16x32_bf16 v[2:5], v[154:157], v[186:189], v[2:5]
	v_mfma_f32_16x16x32_bf16 v[54:57], v[142:145], v[166:169], v[54:57]
	v_mfma_f32_16x16x32_bf16 v[50:53], v[158:161], v[166:169], v[50:53]
	v_mfma_f32_16x16x32_bf16 v[38:41], v[142:145], v[174:177], v[38:41]
	v_mfma_f32_16x16x32_bf16 v[34:37], v[158:161], v[174:177], v[34:37]
	v_mfma_f32_16x16x32_bf16 v[22:25], v[142:145], v[182:185], v[22:25]
	v_mfma_f32_16x16x32_bf16 v[18:21], v[158:161], v[182:185], v[18:21]
	v_mfma_f32_16x16x32_bf16 v[6:9], v[142:145], v[190:193], v[6:9]
	s_setprio 3
	s_barrier
	v_mfma_f32_16x16x32_bf16 v[2:5], v[158:161], v[190:193], v[2:5]
	s_setprio 0
	s_add_i32 s66, s66, 2
	s_add_u32 s64, s64, 0x100
	s_addc_u32 s65, s65, 0
	s_cmpk_gt_u32 s66, 0xdd
	s_mov_b64 s[18:19], s[4:5]
.LBB0_1554:
	ds_read_b128 v[114:117], v247
	ds_read_b128 v[118:121], v247 offset:1024
	ds_read_b128 v[126:129], v247 offset:2048
	ds_read_b128 v[134:137], v247 offset:3072
	ds_read_b128 v[138:141], v248
	ds_read_b128 v[142:145], v248 offset:1024
	ds_read_b128 v[154:157], v248 offset:2048
	ds_read_b128 v[158:161], v248 offset:3072
	s_add_u32 s4, s18, 0x100
	s_addc_u32 s5, s19, 0
	s_cmpk_eq_i32 s66, 0xdc
	s_cselect_b32 s29, s23, s5
	s_cselect_b32 s28, s22, s4
	s_cselect_b32 s27, s25, s65
	s_cselect_b32 s26, s24, s64
	v_lshl_add_u64 v[210:211], s[18:19], 0, v[202:203]
	s_add_i32 m0, s17, 0xc000
	ds_read_b128 v[162:165], v249
	ds_read_b128 v[166:169], v249 offset:1024
	ds_read_b128 v[170:173], v249 offset:2048
	ds_read_b128 v[174:177], v249 offset:3072
	ds_read_b128 v[178:181], v249 offset:4096
	ds_read_b128 v[182:185], v249 offset:5120
	ds_read_b128 v[186:189], v249 offset:6144
	ds_read_b128 v[190:193], v249 offset:7168
	global_load_lds_dwordx4 v[210:211], off
	v_lshl_add_u64 v[210:211], s[18:19], 0, v[204:205]
	s_add_i32 m0, s17, 0xe000
	s_nop 0
	global_load_lds_dwordx4 v[210:211], off
	s_waitcnt vmcnt(8)
	s_waitcnt lgkmcnt(0)
	s_barrier
	s_waitcnt lgkmcnt(0)
	v_mfma_f32_16x16x32_bf16 v[150:153], v[114:117], v[162:165], v[150:153]
	v_mfma_f32_16x16x32_bf16 v[146:149], v[126:129], v[162:165], v[146:149]
	v_mfma_f32_16x16x32_bf16 v[110:113], v[114:117], v[170:173], v[110:113]
	v_mfma_f32_16x16x32_bf16 v[106:109], v[126:129], v[170:173], v[106:109]
	v_mfma_f32_16x16x32_bf16 v[94:97], v[114:117], v[178:181], v[94:97]
	v_mfma_f32_16x16x32_bf16 v[90:93], v[126:129], v[178:181], v[90:93]
	v_mfma_f32_16x16x32_bf16 v[78:81], v[114:117], v[186:189], v[78:81]
	v_mfma_f32_16x16x32_bf16 v[74:77], v[126:129], v[186:189], v[74:77]
	v_mfma_f32_16x16x32_bf16 v[150:153], v[118:121], v[166:169], v[150:153]
	v_mfma_f32_16x16x32_bf16 v[146:149], v[134:137], v[166:169], v[146:149]
	v_mfma_f32_16x16x32_bf16 v[110:113], v[118:121], v[174:177], v[110:113]
	v_mfma_f32_16x16x32_bf16 v[106:109], v[134:137], v[174:177], v[106:109]
	v_mfma_f32_16x16x32_bf16 v[94:97], v[118:121], v[182:185], v[94:97]
	v_mfma_f32_16x16x32_bf16 v[90:93], v[134:137], v[182:185], v[90:93]
	v_mfma_f32_16x16x32_bf16 v[78:81], v[118:121], v[190:193], v[78:81]
	v_mfma_f32_16x16x32_bf16 v[74:77], v[134:137], v[190:193], v[74:77]
	v_mfma_f32_16x16x32_bf16 v[130:133], v[138:141], v[162:165], v[130:133]
	v_mfma_f32_16x16x32_bf16 v[122:125], v[154:157], v[162:165], v[122:125]
	v_mfma_f32_16x16x32_bf16 v[102:105], v[138:141], v[170:173], v[102:105]
	v_mfma_f32_16x16x32_bf16 v[98:101], v[154:157], v[170:173], v[98:101]
	v_mfma_f32_16x16x32_bf16 v[86:89], v[138:141], v[178:181], v[86:89]
	v_mfma_f32_16x16x32_bf16 v[82:85], v[154:157], v[178:181], v[82:85]
	v_mfma_f32_16x16x32_bf16 v[70:73], v[138:141], v[186:189], v[70:73]
	v_mfma_f32_16x16x32_bf16 v[66:69], v[154:157], v[186:189], v[66:69]
	v_mfma_f32_16x16x32_bf16 v[130:133], v[142:145], v[166:169], v[130:133]
	v_mfma_f32_16x16x32_bf16 v[122:125], v[158:161], v[166:169], v[122:125]
	v_mfma_f32_16x16x32_bf16 v[102:105], v[142:145], v[174:177], v[102:105]
	v_mfma_f32_16x16x32_bf16 v[98:101], v[158:161], v[174:177], v[98:101]
	v_mfma_f32_16x16x32_bf16 v[86:89], v[142:145], v[182:185], v[86:89]
	v_mfma_f32_16x16x32_bf16 v[82:85], v[158:161], v[182:185], v[82:85]
	v_mfma_f32_16x16x32_bf16 v[70:73], v[142:145], v[190:193], v[70:73]
	s_setprio 3
	s_barrier
	v_mfma_f32_16x16x32_bf16 v[66:69], v[158:161], v[190:193], v[66:69]
	s_setprio 0
	s_add_i32 s18, s42, s16
	v_lshl_add_u64 v[210:211], s[26:27], 0, v[196:197]
	s_mov_b32 m0, s18
	ds_read_b128 v[162:165], v249 offset:16384
	ds_read_b128 v[166:169], v249 offset:17408
	ds_read_b128 v[170:173], v249 offset:18432
	ds_read_b128 v[174:177], v249 offset:19456
	ds_read_b128 v[178:181], v249 offset:20480
	ds_read_b128 v[182:185], v249 offset:21504
	ds_read_b128 v[186:189], v249 offset:22528
	ds_read_b128 v[190:193], v249 offset:23552
	global_load_lds_dwordx4 v[210:211], off
	s_add_i32 m0, s18, 0x2000
	s_add_u32 s18, s26, 0x380000
	v_lshl_add_u64 v[212:213], s[26:27], 0, v[200:201]
	s_addc_u32 s19, s27, 0
	s_add_i32 s67, s43, s16
	global_load_lds_dwordx4 v[212:213], off
	v_lshl_add_u64 v[214:215], s[18:19], 0, v[196:197]
	s_mov_b32 m0, s67
	v_lshl_add_u64 v[216:217], s[28:29], 0, v[198:199]
	global_load_lds_dwordx4 v[214:215], off
	v_lshl_add_u64 v[214:215], s[18:19], 0, v[200:201]
	s_add_i32 m0, s67, 0x2000
	s_nop 0
	global_load_lds_dwordx4 v[214:215], off
	v_lshl_add_u64 v[214:215], s[28:29], 0, v[194:195]
	s_mov_b32 m0, s17
	s_nop 0
	global_load_lds_dwordx4 v[214:215], off
	s_mov_b32 m0, s30
	s_nop 0
	global_load_lds_dwordx4 v[216:217], off
	s_waitcnt vmcnt(8)
	s_waitcnt lgkmcnt(0)
	s_barrier
	s_waitcnt lgkmcnt(0)
	v_mfma_f32_16x16x32_bf16 v[62:65], v[114:117], v[162:165], v[62:65]
	v_mfma_f32_16x16x32_bf16 v[58:61], v[126:129], v[162:165], v[58:61]
	v_mfma_f32_16x16x32_bf16 v[46:49], v[114:117], v[170:173], v[46:49]
	v_mfma_f32_16x16x32_bf16 v[42:45], v[126:129], v[170:173], v[42:45]
	v_mfma_f32_16x16x32_bf16 v[30:33], v[114:117], v[178:181], v[30:33]
	v_mfma_f32_16x16x32_bf16 v[26:29], v[126:129], v[178:181], v[26:29]
	v_mfma_f32_16x16x32_bf16 v[14:17], v[114:117], v[186:189], v[14:17]
	v_mfma_f32_16x16x32_bf16 v[10:13], v[126:129], v[186:189], v[10:13]
	v_mfma_f32_16x16x32_bf16 v[62:65], v[118:121], v[166:169], v[62:65]
	v_mfma_f32_16x16x32_bf16 v[58:61], v[134:137], v[166:169], v[58:61]
	v_mfma_f32_16x16x32_bf16 v[46:49], v[118:121], v[174:177], v[46:49]
	v_mfma_f32_16x16x32_bf16 v[42:45], v[134:137], v[174:177], v[42:45]
	v_mfma_f32_16x16x32_bf16 v[30:33], v[118:121], v[182:185], v[30:33]
	v_mfma_f32_16x16x32_bf16 v[26:29], v[134:137], v[182:185], v[26:29]
	v_mfma_f32_16x16x32_bf16 v[14:17], v[118:121], v[190:193], v[14:17]
	v_mfma_f32_16x16x32_bf16 v[10:13], v[134:137], v[190:193], v[10:13]
	v_mfma_f32_16x16x32_bf16 v[54:57], v[138:141], v[162:165], v[54:57]
	v_mfma_f32_16x16x32_bf16 v[50:53], v[154:157], v[162:165], v[50:53]
	v_mfma_f32_16x16x32_bf16 v[38:41], v[138:141], v[170:173], v[38:41]
	v_mfma_f32_16x16x32_bf16 v[34:37], v[154:157], v[170:173], v[34:37]
	v_mfma_f32_16x16x32_bf16 v[22:25], v[138:141], v[178:181], v[22:25]
	v_mfma_f32_16x16x32_bf16 v[18:21], v[154:157], v[178:181], v[18:21]
	v_mfma_f32_16x16x32_bf16 v[6:9], v[138:141], v[186:189], v[6:9]
	v_mfma_f32_16x16x32_bf16 v[2:5], v[154:157], v[186:189], v[2:5]
	v_mfma_f32_16x16x32_bf16 v[54:57], v[142:145], v[166:169], v[54:57]
	v_mfma_f32_16x16x32_bf16 v[50:53], v[158:161], v[166:169], v[50:53]
	v_mfma_f32_16x16x32_bf16 v[38:41], v[142:145], v[174:177], v[38:41]
	v_mfma_f32_16x16x32_bf16 v[34:37], v[158:161], v[174:177], v[34:37]
	v_mfma_f32_16x16x32_bf16 v[22:25], v[142:145], v[182:185], v[22:25]
	v_mfma_f32_16x16x32_bf16 v[18:21], v[158:161], v[182:185], v[18:21]
	v_mfma_f32_16x16x32_bf16 v[6:9], v[142:145], v[190:193], v[6:9]
	s_setprio 3
	s_barrier
	v_mfma_f32_16x16x32_bf16 v[2:5], v[158:161], v[190:193], v[2:5]
	s_setprio 0
	s_add_i32 s67, 0, 0x18000
	s_add_i32 s68, 0, 0x1c000
	v_add_u32_e32 v134, s67, v244
	v_add_u32_e32 v158, s68, v244
	ds_read_b128 v[114:117], v134
	ds_read_b128 v[118:121], v134 offset:1024
	ds_read_b128 v[126:129], v134 offset:2048
	ds_read_b128 v[134:137], v134 offset:3072
	ds_read_b128 v[138:141], v158
	ds_read_b128 v[142:145], v158 offset:1024
	ds_read_b128 v[154:157], v158 offset:2048
	ds_read_b128 v[158:161], v158 offset:3072
	s_add_u32 s18, s28, 0x380000
	s_addc_u32 s19, s29, 0
	s_mov_b32 m0, s31
	v_lshl_add_u64 v[218:219], s[18:19], 0, v[194:195]
	ds_read_b128 v[162:165], v249 offset:32768
	ds_read_b128 v[166:169], v249 offset:33792
	ds_read_b128 v[170:173], v249 offset:34816
	ds_read_b128 v[174:177], v249 offset:35840
	ds_read_b128 v[178:181], v249 offset:36864
	ds_read_b128 v[182:185], v249 offset:37888
	ds_read_b128 v[186:189], v249 offset:38912
	ds_read_b128 v[190:193], v249 offset:39936
	global_load_lds_dwordx4 v[218:219], off
	v_lshl_add_u64 v[218:219], s[18:19], 0, v[198:199]
	s_mov_b32 m0, s34
	s_nop 0
	global_load_lds_dwordx4 v[218:219], off
	s_waitcnt vmcnt(8)
	s_waitcnt lgkmcnt(0)
	s_barrier
	s_waitcnt lgkmcnt(0)
	v_mfma_f32_16x16x32_bf16 v[150:153], v[114:117], v[162:165], v[150:153]
	v_mfma_f32_16x16x32_bf16 v[146:149], v[126:129], v[162:165], v[146:149]
	v_mfma_f32_16x16x32_bf16 v[110:113], v[114:117], v[170:173], v[110:113]
	v_mfma_f32_16x16x32_bf16 v[106:109], v[126:129], v[170:173], v[106:109]
	v_mfma_f32_16x16x32_bf16 v[94:97], v[114:117], v[178:181], v[94:97]
	v_mfma_f32_16x16x32_bf16 v[90:93], v[126:129], v[178:181], v[90:93]
	v_mfma_f32_16x16x32_bf16 v[78:81], v[114:117], v[186:189], v[78:81]
	v_mfma_f32_16x16x32_bf16 v[74:77], v[126:129], v[186:189], v[74:77]
	v_mfma_f32_16x16x32_bf16 v[150:153], v[118:121], v[166:169], v[150:153]
	v_mfma_f32_16x16x32_bf16 v[146:149], v[134:137], v[166:169], v[146:149]
	v_mfma_f32_16x16x32_bf16 v[110:113], v[118:121], v[174:177], v[110:113]
	v_mfma_f32_16x16x32_bf16 v[106:109], v[134:137], v[174:177], v[106:109]
	v_mfma_f32_16x16x32_bf16 v[94:97], v[118:121], v[182:185], v[94:97]
	v_mfma_f32_16x16x32_bf16 v[90:93], v[134:137], v[182:185], v[90:93]
	v_mfma_f32_16x16x32_bf16 v[78:81], v[118:121], v[190:193], v[78:81]
	v_mfma_f32_16x16x32_bf16 v[74:77], v[134:137], v[190:193], v[74:77]
	v_mfma_f32_16x16x32_bf16 v[130:133], v[138:141], v[162:165], v[130:133]
	v_mfma_f32_16x16x32_bf16 v[122:125], v[154:157], v[162:165], v[122:125]
	v_mfma_f32_16x16x32_bf16 v[102:105], v[138:141], v[170:173], v[102:105]
	v_mfma_f32_16x16x32_bf16 v[98:101], v[154:157], v[170:173], v[98:101]
	v_mfma_f32_16x16x32_bf16 v[86:89], v[138:141], v[178:181], v[86:89]
	v_mfma_f32_16x16x32_bf16 v[82:85], v[154:157], v[178:181], v[82:85]
	v_mfma_f32_16x16x32_bf16 v[70:73], v[138:141], v[186:189], v[70:73]
	v_mfma_f32_16x16x32_bf16 v[66:69], v[154:157], v[186:189], v[66:69]
	v_mfma_f32_16x16x32_bf16 v[130:133], v[142:145], v[166:169], v[130:133]
	v_mfma_f32_16x16x32_bf16 v[122:125], v[158:161], v[166:169], v[122:125]
	v_mfma_f32_16x16x32_bf16 v[102:105], v[142:145], v[174:177], v[102:105]
	v_mfma_f32_16x16x32_bf16 v[98:101], v[158:161], v[174:177], v[98:101]
	v_mfma_f32_16x16x32_bf16 v[86:89], v[142:145], v[182:185], v[86:89]
	v_mfma_f32_16x16x32_bf16 v[82:85], v[158:161], v[182:185], v[82:85]
	v_mfma_f32_16x16x32_bf16 v[70:73], v[142:145], v[190:193], v[70:73]
	s_setprio 3
	s_barrier
	v_mfma_f32_16x16x32_bf16 v[66:69], v[158:161], v[190:193], v[66:69]
	s_setprio 0
	s_add_i32 s18, s67, s16
	v_lshl_add_u64 v[210:211], v[210:211], 0, s[12:13]
	s_mov_b32 m0, s18
	ds_read_b128 v[162:165], v249 offset:49152
	ds_read_b128 v[166:169], v249 offset:50176
	ds_read_b128 v[170:173], v249 offset:51200
	ds_read_b128 v[174:177], v249 offset:52224
	ds_read_b128 v[178:181], v249 offset:53248
	ds_read_b128 v[182:185], v249 offset:54272
	ds_read_b128 v[186:189], v249 offset:55296
	ds_read_b128 v[190:193], v249 offset:56320
	global_load_lds_dwordx4 v[210:211], off
	s_add_i32 m0, s18, 0x2000
	s_add_u32 s18, s26, 0x380080
	v_lshl_add_u64 v[210:211], v[212:213], 0, s[12:13]
	s_addc_u32 s19, s27, 0
	s_add_i32 s26, s68, s16
	global_load_lds_dwordx4 v[210:211], off
	v_lshl_add_u64 v[210:211], s[18:19], 0, v[196:197]
	s_mov_b32 m0, s26
	s_nop 0
	global_load_lds_dwordx4 v[210:211], off
	v_lshl_add_u64 v[210:211], s[18:19], 0, v[200:201]
	s_add_i32 m0, s26, 0x2000
	s_nop 0
	global_load_lds_dwordx4 v[210:211], off
	v_lshl_add_u64 v[210:211], v[214:215], 0, s[12:13]
	s_mov_b32 m0, s38
	s_nop 0
	global_load_lds_dwordx4 v[210:211], off
	v_lshl_add_u64 v[210:211], v[216:217], 0, s[12:13]
	s_mov_b32 m0, s39
	s_nop 0
	global_load_lds_dwordx4 v[210:211], off
	s_waitcnt vmcnt(8)
	s_waitcnt lgkmcnt(0)
	s_barrier
	s_waitcnt lgkmcnt(0)
	v_mfma_f32_16x16x32_bf16 v[62:65], v[114:117], v[162:165], v[62:65]
	v_mfma_f32_16x16x32_bf16 v[58:61], v[126:129], v[162:165], v[58:61]
	v_mfma_f32_16x16x32_bf16 v[46:49], v[114:117], v[170:173], v[46:49]
	v_mfma_f32_16x16x32_bf16 v[42:45], v[126:129], v[170:173], v[42:45]
	v_mfma_f32_16x16x32_bf16 v[30:33], v[114:117], v[178:181], v[30:33]
	v_mfma_f32_16x16x32_bf16 v[26:29], v[126:129], v[178:181], v[26:29]
	v_mfma_f32_16x16x32_bf16 v[14:17], v[114:117], v[186:189], v[14:17]
	v_mfma_f32_16x16x32_bf16 v[10:13], v[126:129], v[186:189], v[10:13]
	v_mfma_f32_16x16x32_bf16 v[62:65], v[118:121], v[166:169], v[62:65]
	v_mfma_f32_16x16x32_bf16 v[58:61], v[134:137], v[166:169], v[58:61]
	v_mfma_f32_16x16x32_bf16 v[46:49], v[118:121], v[174:177], v[46:49]
	v_mfma_f32_16x16x32_bf16 v[42:45], v[134:137], v[174:177], v[42:45]
	v_mfma_f32_16x16x32_bf16 v[30:33], v[118:121], v[182:185], v[30:33]
	v_mfma_f32_16x16x32_bf16 v[26:29], v[134:137], v[182:185], v[26:29]
	v_mfma_f32_16x16x32_bf16 v[14:17], v[118:121], v[190:193], v[14:17]
	v_mfma_f32_16x16x32_bf16 v[10:13], v[134:137], v[190:193], v[10:13]
	v_mfma_f32_16x16x32_bf16 v[54:57], v[138:141], v[162:165], v[54:57]
	v_mfma_f32_16x16x32_bf16 v[50:53], v[154:157], v[162:165], v[50:53]
	v_mfma_f32_16x16x32_bf16 v[38:41], v[138:141], v[170:173], v[38:41]
	v_mfma_f32_16x16x32_bf16 v[34:37], v[154:157], v[170:173], v[34:37]
	v_mfma_f32_16x16x32_bf16 v[22:25], v[138:141], v[178:181], v[22:25]
	v_mfma_f32_16x16x32_bf16 v[18:21], v[154:157], v[178:181], v[18:21]
	v_mfma_f32_16x16x32_bf16 v[6:9], v[138:141], v[186:189], v[6:9]
	v_mfma_f32_16x16x32_bf16 v[2:5], v[154:157], v[186:189], v[2:5]
	v_mfma_f32_16x16x32_bf16 v[54:57], v[142:145], v[166:169], v[54:57]
	v_mfma_f32_16x16x32_bf16 v[50:53], v[158:161], v[166:169], v[50:53]
	v_mfma_f32_16x16x32_bf16 v[38:41], v[142:145], v[174:177], v[38:41]
	v_mfma_f32_16x16x32_bf16 v[34:37], v[158:161], v[174:177], v[34:37]
	v_mfma_f32_16x16x32_bf16 v[22:25], v[142:145], v[182:185], v[22:25]
	v_mfma_f32_16x16x32_bf16 v[18:21], v[158:161], v[182:185], v[18:21]
	v_mfma_f32_16x16x32_bf16 v[6:9], v[142:145], v[190:193], v[6:9]
	s_setprio 3
	s_barrier
	v_mfma_f32_16x16x32_bf16 v[2:5], v[158:161], v[190:193], v[2:5]
	s_setprio 0
	s_add_i32 s66, s66, 2
	s_add_u32 s64, s64, 0x100
	s_addc_u32 s65, s65, 0
	s_cmpk_gt_u32 s66, 0xdd
	s_mov_b64 s[18:19], s[4:5]
	s_cbranch_scc0 .LBB0_1554
	s_and_b64 vcc, exec, s[14:15]
	s_cbranch_vccz .LBB0_1557
	s_barrier

.LBB0_1646:
	s_ashr_i32 s63, s62, 31
	s_lshl_b64 s[0:1], s[62:63], 21
	s_add_u32 s64, s52, s0
	s_addc_u32 s65, s53, s1
	s_and_b64 s[0:1], s[4:5], exec
	s_cselect_b32 s0, s65, s11
	s_cselect_b32 s1, s64, s10
	s_ashr_i32 s61, s60, 31
	s_lshl_b64 s[16:17], s[60:61], 21
	s_add_u32 s66, s31, s16
	s_addc_u32 s67, s35, s17
	s_and_b64 s[16:17], s[4:5], exec
	s_cselect_b32 s7, s67, s19
	s_cselect_b32 s9, s66, s18
	s_add_u32 s10, s10, 0x100080
	s_addc_u32 s11, s11, 0
	s_add_u32 s16, s18, 0x100
	s_addc_u32 s17, s19, 0
	s_mov_b32 s61, -2
	s_waitcnt lgkmcnt(0)
	ds_read_b128 v[30:33], v200
	ds_read_b128 v[38:41], v200 offset:1024
	ds_read_b128 v[42:45], v200 offset:2048
	ds_read_b128 v[50:53], v200 offset:3072
	ds_read_b128 v[164:167], v201
	ds_read_b128 v[168:171], v201 offset:1024
	ds_read_b128 v[172:175], v201 offset:2048
	ds_read_b128 v[176:179], v201 offset:3072
	s_add_u32 s18, s10, 0xfff00080
	s_addc_u32 s19, s11, -1
	s_cmp_eq_u32 s61, 60
	s_cselect_b32 s69, s0, s19
	s_cselect_b32 s68, s1, s18
	s_cselect_b32 s19, s7, s17
	s_cselect_b32 s18, s9, s16
	v_lshl_add_u64 v[222:223], s[10:11], 0, v[156:157]
	s_add_i32 m0, s39, 0xc000
	ds_read_b128 v[180:183], v202
	ds_read_b128 v[184:187], v202 offset:1024
	ds_read_b128 v[188:191], v202 offset:2048
	ds_read_b128 v[192:195], v202 offset:3072
	ds_read_b128 v[206:209], v202 offset:4096
	ds_read_b128 v[210:213], v202 offset:5120
	ds_read_b128 v[214:217], v202 offset:6144
	ds_read_b128 v[218:221], v202 offset:7168
	global_load_lds_dwordx4 v[222:223], off
	v_lshl_add_u64 v[222:223], s[10:11], 0, v[158:159]
	s_add_i32 m0, s39, 0xe000
	s_nop 0
	global_load_lds_dwordx4 v[222:223], off
	s_waitcnt vmcnt(8)
	s_waitcnt lgkmcnt(0)
	s_barrier
	s_waitcnt lgkmcnt(0)
	v_mfma_f32_16x16x32_bf16 v[138:141], v[30:33], v[180:183], 0
	v_mfma_f32_16x16x32_bf16 v[142:145], v[42:45], v[180:183], 0
	v_mfma_f32_16x16x32_bf16 v[122:125], v[30:33], v[188:191], 0
	v_mfma_f32_16x16x32_bf16 v[126:129], v[42:45], v[188:191], 0
	v_mfma_f32_16x16x32_bf16 v[106:109], v[30:33], v[206:209], 0
	v_mfma_f32_16x16x32_bf16 v[110:113], v[42:45], v[206:209], 0
	v_mfma_f32_16x16x32_bf16 v[90:93], v[30:33], v[214:217], 0
	v_mfma_f32_16x16x32_bf16 v[94:97], v[42:45], v[214:217], 0
	v_mfma_f32_16x16x32_bf16 v[138:141], v[38:41], v[184:187], v[138:141]
	v_mfma_f32_16x16x32_bf16 v[142:145], v[50:53], v[184:187], v[142:145]
	v_mfma_f32_16x16x32_bf16 v[122:125], v[38:41], v[192:195], v[122:125]
	v_mfma_f32_16x16x32_bf16 v[126:129], v[50:53], v[192:195], v[126:129]
	v_mfma_f32_16x16x32_bf16 v[106:109], v[38:41], v[210:213], v[106:109]
	v_mfma_f32_16x16x32_bf16 v[110:113], v[50:53], v[210:213], v[110:113]
	v_mfma_f32_16x16x32_bf16 v[90:93], v[38:41], v[218:221], v[90:93]
	v_mfma_f32_16x16x32_bf16 v[94:97], v[50:53], v[218:221], v[94:97]
	v_mfma_f32_16x16x32_bf16 v[130:133], v[164:167], v[180:183], 0
	v_mfma_f32_16x16x32_bf16 v[134:137], v[172:175], v[180:183], 0
	v_mfma_f32_16x16x32_bf16 v[114:117], v[164:167], v[188:191], 0
	v_mfma_f32_16x16x32_bf16 v[118:121], v[172:175], v[188:191], 0
	v_mfma_f32_16x16x32_bf16 v[98:101], v[164:167], v[206:209], 0
	v_mfma_f32_16x16x32_bf16 v[102:105], v[172:175], v[206:209], 0
	v_mfma_f32_16x16x32_bf16 v[82:85], v[164:167], v[214:217], 0
	v_mfma_f32_16x16x32_bf16 v[86:89], v[172:175], v[214:217], 0
	v_mfma_f32_16x16x32_bf16 v[130:133], v[168:171], v[184:187], v[130:133]
	v_mfma_f32_16x16x32_bf16 v[134:137], v[176:179], v[184:187], v[134:137]
	v_mfma_f32_16x16x32_bf16 v[114:117], v[168:171], v[192:195], v[114:117]
	v_mfma_f32_16x16x32_bf16 v[118:121], v[176:179], v[192:195], v[118:121]
	v_mfma_f32_16x16x32_bf16 v[98:101], v[168:171], v[210:213], v[98:101]
	v_mfma_f32_16x16x32_bf16 v[102:105], v[176:179], v[210:213], v[102:105]
	v_mfma_f32_16x16x32_bf16 v[82:85], v[168:171], v[218:221], v[82:85]
	s_setprio 3
	s_barrier
	v_mfma_f32_16x16x32_bf16 v[86:89], v[176:179], v[218:221], v[86:89]
	s_setprio 0
	s_add_i32 s63, s77, s37
	v_lshl_add_u64 v[222:223], s[18:19], 0, v[148:149]
	s_mov_b32 m0, s63
	ds_read_b128 v[180:183], v202 offset:16384
	ds_read_b128 v[184:187], v202 offset:17408
	ds_read_b128 v[188:191], v202 offset:18432
	ds_read_b128 v[192:195], v202 offset:19456
	ds_read_b128 v[206:209], v202 offset:20480
	ds_read_b128 v[210:213], v202 offset:21504
	ds_read_b128 v[214:217], v202 offset:22528
	ds_read_b128 v[218:221], v202 offset:23552
	global_load_lds_dwordx4 v[222:223], off
	s_add_i32 m0, s63, 0x2000
	s_add_u32 s82, s18, 0x100000
	v_lshl_add_u64 v[224:225], s[18:19], 0, v[152:153]
	s_addc_u32 s83, s19, 0
	s_add_i32 s63, s78, s37
	global_load_lds_dwordx4 v[224:225], off
	v_lshl_add_u64 v[226:227], s[82:83], 0, v[148:149]
	s_mov_b32 m0, s63
	v_lshl_add_u64 v[228:229], s[68:69], 0, v[150:151]
	global_load_lds_dwordx4 v[226:227], off
	v_lshl_add_u64 v[226:227], s[82:83], 0, v[152:153]
	s_add_i32 m0, s63, 0x2000
	s_nop 0
	global_load_lds_dwordx4 v[226:227], off
	v_lshl_add_u64 v[226:227], s[68:69], 0, v[146:147]
	s_mov_b32 m0, s39
	s_nop 0
	global_load_lds_dwordx4 v[226:227], off
	s_mov_b32 m0, s41
	s_nop 0
	global_load_lds_dwordx4 v[228:229], off
	s_waitcnt vmcnt(8)
	s_waitcnt lgkmcnt(0)
	s_barrier
	s_waitcnt lgkmcnt(0)
	v_mfma_f32_16x16x32_bf16 v[74:77], v[30:33], v[180:183], 0
	v_mfma_f32_16x16x32_bf16 v[78:81], v[42:45], v[180:183], 0
	v_mfma_f32_16x16x32_bf16 v[58:61], v[30:33], v[188:191], 0
	v_mfma_f32_16x16x32_bf16 v[62:65], v[42:45], v[188:191], 0
	v_mfma_f32_16x16x32_bf16 v[26:29], v[30:33], v[206:209], 0
	v_mfma_f32_16x16x32_bf16 v[34:37], v[42:45], v[206:209], 0
	v_mfma_f32_16x16x32_bf16 v[10:13], v[30:33], v[214:217], 0
	v_mfma_f32_16x16x32_bf16 v[14:17], v[42:45], v[214:217], 0
	v_mfma_f32_16x16x32_bf16 v[74:77], v[38:41], v[184:187], v[74:77]
	v_mfma_f32_16x16x32_bf16 v[78:81], v[50:53], v[184:187], v[78:81]
	v_mfma_f32_16x16x32_bf16 v[58:61], v[38:41], v[192:195], v[58:61]
	v_mfma_f32_16x16x32_bf16 v[62:65], v[50:53], v[192:195], v[62:65]
	v_mfma_f32_16x16x32_bf16 v[26:29], v[38:41], v[210:213], v[26:29]
	v_mfma_f32_16x16x32_bf16 v[34:37], v[50:53], v[210:213], v[34:37]
	v_mfma_f32_16x16x32_bf16 v[10:13], v[38:41], v[218:221], v[10:13]
	v_mfma_f32_16x16x32_bf16 v[14:17], v[50:53], v[218:221], v[14:17]
	v_mfma_f32_16x16x32_bf16 v[18:21], v[164:167], v[206:209], 0
	v_mfma_f32_16x16x32_bf16 v[22:25], v[172:175], v[206:209], 0
	v_mfma_f32_16x16x32_bf16 v[2:5], v[164:167], v[214:217], 0
	v_mfma_f32_16x16x32_bf16 v[6:9], v[172:175], v[214:217], 0
	v_mfma_f32_16x16x32_bf16 v[30:33], v[164:167], v[180:183], 0
	v_mfma_f32_16x16x32_bf16 v[38:41], v[172:175], v[180:183], 0
	v_mfma_f32_16x16x32_bf16 v[42:45], v[164:167], v[188:191], 0
	v_mfma_f32_16x16x32_bf16 v[46:49], v[172:175], v[188:191], 0
	v_mfma_f32_16x16x32_bf16 v[18:21], v[168:171], v[210:213], v[18:21]
	v_mfma_f32_16x16x32_bf16 v[22:25], v[176:179], v[210:213], v[22:25]
	v_mfma_f32_16x16x32_bf16 v[2:5], v[168:171], v[218:221], v[2:5]
	v_mfma_f32_16x16x32_bf16 v[6:9], v[176:179], v[218:221], v[6:9]
	v_mfma_f32_16x16x32_bf16 v[30:33], v[168:171], v[184:187], v[30:33]
	v_mfma_f32_16x16x32_bf16 v[38:41], v[176:179], v[184:187], v[38:41]
	v_mfma_f32_16x16x32_bf16 v[42:45], v[168:171], v[192:195], v[42:45]
	s_setprio 3
	s_barrier
	v_mfma_f32_16x16x32_bf16 v[50:53], v[176:179], v[192:195], v[46:49]
	s_setprio 0
	s_add_i32 s63, 0, 0x18000
	s_add_i32 s82, 0, 0x1c000
	v_add_u32_e32 v70, s63, v196
	v_add_u32_e32 v155, s82, v196
	ds_read_b128 v[46:49], v70
	ds_read_b128 v[54:57], v70 offset:1024
	ds_read_b128 v[66:69], v70 offset:2048
	ds_read_b128 v[70:73], v70 offset:3072
	ds_read_b128 v[164:167], v155
	ds_read_b128 v[168:171], v155 offset:1024
	ds_read_b128 v[172:175], v155 offset:2048
	ds_read_b128 v[176:179], v155 offset:3072
	s_add_u32 s68, s68, 0x100000
	s_addc_u32 s69, s69, 0
	s_mov_b32 m0, s43
	v_lshl_add_u64 v[230:231], s[68:69], 0, v[146:147]
	ds_read_b128 v[180:183], v202 offset:32768
	ds_read_b128 v[184:187], v202 offset:33792
	ds_read_b128 v[188:191], v202 offset:34816
	ds_read_b128 v[192:195], v202 offset:35840
	ds_read_b128 v[206:209], v202 offset:36864
	ds_read_b128 v[210:213], v202 offset:37888
	ds_read_b128 v[214:217], v202 offset:38912
	ds_read_b128 v[218:221], v202 offset:39936
	global_load_lds_dwordx4 v[230:231], off
	v_lshl_add_u64 v[230:231], s[68:69], 0, v[150:151]
	s_mov_b32 m0, s57
	s_nop 0
	global_load_lds_dwordx4 v[230:231], off
	s_waitcnt vmcnt(8)
	s_waitcnt lgkmcnt(0)
	s_barrier
	s_waitcnt lgkmcnt(0)
	v_mfma_f32_16x16x32_bf16 v[138:141], v[46:49], v[180:183], v[138:141]
	v_mfma_f32_16x16x32_bf16 v[142:145], v[66:69], v[180:183], v[142:145]
	v_mfma_f32_16x16x32_bf16 v[122:125], v[46:49], v[188:191], v[122:125]
	v_mfma_f32_16x16x32_bf16 v[126:129], v[66:69], v[188:191], v[126:129]
	v_mfma_f32_16x16x32_bf16 v[106:109], v[46:49], v[206:209], v[106:109]
	v_mfma_f32_16x16x32_bf16 v[110:113], v[66:69], v[206:209], v[110:113]
	v_mfma_f32_16x16x32_bf16 v[90:93], v[46:49], v[214:217], v[90:93]
	v_mfma_f32_16x16x32_bf16 v[94:97], v[66:69], v[214:217], v[94:97]
	v_mfma_f32_16x16x32_bf16 v[138:141], v[54:57], v[184:187], v[138:141]
	v_mfma_f32_16x16x32_bf16 v[142:145], v[70:73], v[184:187], v[142:145]
	v_mfma_f32_16x16x32_bf16 v[122:125], v[54:57], v[192:195], v[122:125]
	v_mfma_f32_16x16x32_bf16 v[126:129], v[70:73], v[192:195], v[126:129]
	v_mfma_f32_16x16x32_bf16 v[106:109], v[54:57], v[210:213], v[106:109]
	v_mfma_f32_16x16x32_bf16 v[110:113], v[70:73], v[210:213], v[110:113]
	v_mfma_f32_16x16x32_bf16 v[90:93], v[54:57], v[218:221], v[90:93]
	v_mfma_f32_16x16x32_bf16 v[94:97], v[70:73], v[218:221], v[94:97]
	v_mfma_f32_16x16x32_bf16 v[130:133], v[164:167], v[180:183], v[130:133]
	v_mfma_f32_16x16x32_bf16 v[134:137], v[172:175], v[180:183], v[134:137]
	v_mfma_f32_16x16x32_bf16 v[114:117], v[164:167], v[188:191], v[114:117]
	v_mfma_f32_16x16x32_bf16 v[118:121], v[172:175], v[188:191], v[118:121]
	v_mfma_f32_16x16x32_bf16 v[98:101], v[164:167], v[206:209], v[98:101]
	v_mfma_f32_16x16x32_bf16 v[102:105], v[172:175], v[206:209], v[102:105]
	v_mfma_f32_16x16x32_bf16 v[82:85], v[164:167], v[214:217], v[82:85]
	v_mfma_f32_16x16x32_bf16 v[86:89], v[172:175], v[214:217], v[86:89]
	v_mfma_f32_16x16x32_bf16 v[130:133], v[168:171], v[184:187], v[130:133]
	v_mfma_f32_16x16x32_bf16 v[134:137], v[176:179], v[184:187], v[134:137]
	v_mfma_f32_16x16x32_bf16 v[114:117], v[168:171], v[192:195], v[114:117]
	v_mfma_f32_16x16x32_bf16 v[118:121], v[176:179], v[192:195], v[118:121]
	v_mfma_f32_16x16x32_bf16 v[98:101], v[168:171], v[210:213], v[98:101]
	v_mfma_f32_16x16x32_bf16 v[102:105], v[176:179], v[210:213], v[102:105]
	v_mfma_f32_16x16x32_bf16 v[82:85], v[168:171], v[218:221], v[82:85]
	s_setprio 3
	s_barrier
	v_mfma_f32_16x16x32_bf16 v[86:89], v[176:179], v[218:221], v[86:89]
	s_setprio 0
	s_add_i32 s63, s63, s37
	v_lshl_add_u64 v[222:223], v[222:223], 0, s[26:27]
	s_mov_b32 m0, s63
	ds_read_b128 v[180:183], v202 offset:49152
	ds_read_b128 v[184:187], v202 offset:50176
	ds_read_b128 v[188:191], v202 offset:51200
	ds_read_b128 v[192:195], v202 offset:52224
	ds_read_b128 v[206:209], v202 offset:53248
	ds_read_b128 v[210:213], v202 offset:54272
	ds_read_b128 v[214:217], v202 offset:55296
	ds_read_b128 v[218:221], v202 offset:56320
	global_load_lds_dwordx4 v[222:223], off
	s_add_i32 m0, s63, 0x2000
	s_add_u32 s18, s18, 0x100080
	v_lshl_add_u64 v[222:223], v[224:225], 0, s[26:27]
	s_addc_u32 s19, s19, 0
	s_add_i32 s63, s82, s37
	global_load_lds_dwordx4 v[222:223], off
	v_lshl_add_u64 v[222:223], s[18:19], 0, v[148:149]
	s_mov_b32 m0, s63
	s_nop 0
	global_load_lds_dwordx4 v[222:223], off
	v_lshl_add_u64 v[222:223], s[18:19], 0, v[152:153]
	s_add_i32 m0, s63, 0x2000
	s_nop 0
	global_load_lds_dwordx4 v[222:223], off
	v_lshl_add_u64 v[222:223], v[226:227], 0, s[26:27]
	s_mov_b32 m0, s71
	s_nop 0
	global_load_lds_dwordx4 v[222:223], off
	v_lshl_add_u64 v[222:223], v[228:229], 0, s[26:27]
	s_mov_b32 m0, s72
	s_nop 0
	global_load_lds_dwordx4 v[222:223], off
	s_waitcnt vmcnt(8)
	s_waitcnt lgkmcnt(0)
	s_barrier
	s_waitcnt lgkmcnt(0)
	v_mfma_f32_16x16x32_bf16 v[74:77], v[46:49], v[180:183], v[74:77]
	v_mfma_f32_16x16x32_bf16 v[78:81], v[66:69], v[180:183], v[78:81]
	v_mfma_f32_16x16x32_bf16 v[58:61], v[46:49], v[188:191], v[58:61]
	v_mfma_f32_16x16x32_bf16 v[62:65], v[66:69], v[188:191], v[62:65]
	v_mfma_f32_16x16x32_bf16 v[26:29], v[46:49], v[206:209], v[26:29]
	v_mfma_f32_16x16x32_bf16 v[34:37], v[66:69], v[206:209], v[34:37]
	v_mfma_f32_16x16x32_bf16 v[10:13], v[46:49], v[214:217], v[10:13]
	v_mfma_f32_16x16x32_bf16 v[14:17], v[66:69], v[214:217], v[14:17]
	v_mfma_f32_16x16x32_bf16 v[74:77], v[54:57], v[184:187], v[74:77]
	v_mfma_f32_16x16x32_bf16 v[78:81], v[70:73], v[184:187], v[78:81]
	v_mfma_f32_16x16x32_bf16 v[58:61], v[54:57], v[192:195], v[58:61]
	v_mfma_f32_16x16x32_bf16 v[62:65], v[70:73], v[192:195], v[62:65]
	v_mfma_f32_16x16x32_bf16 v[26:29], v[54:57], v[210:213], v[26:29]
	v_mfma_f32_16x16x32_bf16 v[34:37], v[70:73], v[210:213], v[34:37]
	v_mfma_f32_16x16x32_bf16 v[10:13], v[54:57], v[218:221], v[10:13]
	v_mfma_f32_16x16x32_bf16 v[14:17], v[70:73], v[218:221], v[14:17]
	v_mfma_f32_16x16x32_bf16 v[30:33], v[164:167], v[180:183], v[30:33]
	v_mfma_f32_16x16x32_bf16 v[66:69], v[168:171], v[184:187], v[30:33]
	v_mfma_f32_16x16x32_bf16 v[30:33], v[172:175], v[180:183], v[38:41]
	v_mfma_f32_16x16x32_bf16 v[70:73], v[176:179], v[184:187], v[30:33]
	v_mfma_f32_16x16x32_bf16 v[30:33], v[164:167], v[188:191], v[42:45]
	v_mfma_f32_16x16x32_bf16 v[46:49], v[168:171], v[192:195], v[30:33]
	v_mfma_f32_16x16x32_bf16 v[30:33], v[172:175], v[188:191], v[50:53]
	v_mfma_f32_16x16x32_bf16 v[18:21], v[164:167], v[206:209], v[18:21]
	v_mfma_f32_16x16x32_bf16 v[22:25], v[172:175], v[206:209], v[22:25]
	v_mfma_f32_16x16x32_bf16 v[2:5], v[164:167], v[214:217], v[2:5]
	v_mfma_f32_16x16x32_bf16 v[6:9], v[172:175], v[214:217], v[6:9]
	v_mfma_f32_16x16x32_bf16 v[54:57], v[176:179], v[192:195], v[30:33]
	v_mfma_f32_16x16x32_bf16 v[18:21], v[168:171], v[210:213], v[18:21]
	v_mfma_f32_16x16x32_bf16 v[22:25], v[176:179], v[210:213], v[22:25]
	v_mfma_f32_16x16x32_bf16 v[2:5], v[168:171], v[218:221], v[2:5]
	s_setprio 3
	s_barrier
	v_mfma_f32_16x16x32_bf16 v[6:9], v[176:179], v[218:221], v[6:9]
	s_setprio 0
	s_add_i32 s61, s61, 2
	s_add_u32 s10, s10, 0x100
	s_addc_u32 s11, s11, 0
	s_add_u32 s16, s16, 0x100
	s_addc_u32 s17, s17, 0
	s_cmp_gt_u32 s61, 61
.LBB0_1647:
	ds_read_b128 v[30:33], v200
	ds_read_b128 v[38:41], v200 offset:1024
	ds_read_b128 v[42:45], v200 offset:2048
	ds_read_b128 v[50:53], v200 offset:3072
	ds_read_b128 v[164:167], v201
	ds_read_b128 v[168:171], v201 offset:1024
	ds_read_b128 v[172:175], v201 offset:2048
	ds_read_b128 v[176:179], v201 offset:3072
	s_add_u32 s18, s10, 0xfff00080
	s_addc_u32 s19, s11, -1
	s_cmp_eq_u32 s61, 60
	s_cselect_b32 s69, s0, s19
	s_cselect_b32 s68, s1, s18
	s_cselect_b32 s19, s7, s17
	s_cselect_b32 s18, s9, s16
	v_lshl_add_u64 v[222:223], s[10:11], 0, v[156:157]
	s_add_i32 m0, s39, 0xc000
	ds_read_b128 v[180:183], v202
	ds_read_b128 v[184:187], v202 offset:1024
	ds_read_b128 v[188:191], v202 offset:2048
	ds_read_b128 v[192:195], v202 offset:3072
	ds_read_b128 v[206:209], v202 offset:4096
	ds_read_b128 v[210:213], v202 offset:5120
	ds_read_b128 v[214:217], v202 offset:6144
	ds_read_b128 v[218:221], v202 offset:7168
	global_load_lds_dwordx4 v[222:223], off
	v_lshl_add_u64 v[222:223], s[10:11], 0, v[158:159]
	s_add_i32 m0, s39, 0xe000
	s_nop 0
	global_load_lds_dwordx4 v[222:223], off
	s_waitcnt vmcnt(8)
	s_waitcnt lgkmcnt(0)
	s_barrier
	s_waitcnt lgkmcnt(0)
	v_mfma_f32_16x16x32_bf16 v[138:141], v[30:33], v[180:183], v[138:141]
	v_mfma_f32_16x16x32_bf16 v[142:145], v[42:45], v[180:183], v[142:145]
	v_mfma_f32_16x16x32_bf16 v[122:125], v[30:33], v[188:191], v[122:125]
	v_mfma_f32_16x16x32_bf16 v[126:129], v[42:45], v[188:191], v[126:129]
	v_mfma_f32_16x16x32_bf16 v[106:109], v[30:33], v[206:209], v[106:109]
	v_mfma_f32_16x16x32_bf16 v[110:113], v[42:45], v[206:209], v[110:113]
	v_mfma_f32_16x16x32_bf16 v[90:93], v[30:33], v[214:217], v[90:93]
	v_mfma_f32_16x16x32_bf16 v[94:97], v[42:45], v[214:217], v[94:97]
	v_mfma_f32_16x16x32_bf16 v[138:141], v[38:41], v[184:187], v[138:141]
	v_mfma_f32_16x16x32_bf16 v[142:145], v[50:53], v[184:187], v[142:145]
	v_mfma_f32_16x16x32_bf16 v[122:125], v[38:41], v[192:195], v[122:125]
	v_mfma_f32_16x16x32_bf16 v[126:129], v[50:53], v[192:195], v[126:129]
	v_mfma_f32_16x16x32_bf16 v[106:109], v[38:41], v[210:213], v[106:109]
	v_mfma_f32_16x16x32_bf16 v[110:113], v[50:53], v[210:213], v[110:113]
	v_mfma_f32_16x16x32_bf16 v[90:93], v[38:41], v[218:221], v[90:93]
	v_mfma_f32_16x16x32_bf16 v[94:97], v[50:53], v[218:221], v[94:97]
	v_mfma_f32_16x16x32_bf16 v[130:133], v[164:167], v[180:183], v[130:133]
	v_mfma_f32_16x16x32_bf16 v[134:137], v[172:175], v[180:183], v[134:137]
	v_mfma_f32_16x16x32_bf16 v[114:117], v[164:167], v[188:191], v[114:117]
	v_mfma_f32_16x16x32_bf16 v[118:121], v[172:175], v[188:191], v[118:121]
	v_mfma_f32_16x16x32_bf16 v[98:101], v[164:167], v[206:209], v[98:101]
	v_mfma_f32_16x16x32_bf16 v[102:105], v[172:175], v[206:209], v[102:105]
	v_mfma_f32_16x16x32_bf16 v[82:85], v[164:167], v[214:217], v[82:85]
	v_mfma_f32_16x16x32_bf16 v[86:89], v[172:175], v[214:217], v[86:89]
	v_mfma_f32_16x16x32_bf16 v[130:133], v[168:171], v[184:187], v[130:133]
	v_mfma_f32_16x16x32_bf16 v[134:137], v[176:179], v[184:187], v[134:137]
	v_mfma_f32_16x16x32_bf16 v[114:117], v[168:171], v[192:195], v[114:117]
	v_mfma_f32_16x16x32_bf16 v[118:121], v[176:179], v[192:195], v[118:121]
	v_mfma_f32_16x16x32_bf16 v[98:101], v[168:171], v[210:213], v[98:101]
	v_mfma_f32_16x16x32_bf16 v[102:105], v[176:179], v[210:213], v[102:105]
	v_mfma_f32_16x16x32_bf16 v[82:85], v[168:171], v[218:221], v[82:85]
	s_setprio 3
	s_barrier
	v_mfma_f32_16x16x32_bf16 v[86:89], v[176:179], v[218:221], v[86:89]
	s_setprio 0
	s_add_i32 s63, s77, s37
	v_lshl_add_u64 v[222:223], s[18:19], 0, v[148:149]
	s_mov_b32 m0, s63
	ds_read_b128 v[180:183], v202 offset:16384
	ds_read_b128 v[184:187], v202 offset:17408
	ds_read_b128 v[188:191], v202 offset:18432
	ds_read_b128 v[192:195], v202 offset:19456
	ds_read_b128 v[206:209], v202 offset:20480
	ds_read_b128 v[210:213], v202 offset:21504
	ds_read_b128 v[214:217], v202 offset:22528
	ds_read_b128 v[218:221], v202 offset:23552
	global_load_lds_dwordx4 v[222:223], off
	s_add_i32 m0, s63, 0x2000
	s_add_u32 s82, s18, 0x100000
	v_lshl_add_u64 v[224:225], s[18:19], 0, v[152:153]
	s_addc_u32 s83, s19, 0
	s_add_i32 s63, s78, s37
	global_load_lds_dwordx4 v[224:225], off
	v_lshl_add_u64 v[226:227], s[82:83], 0, v[148:149]
	s_mov_b32 m0, s63
	v_lshl_add_u64 v[228:229], s[68:69], 0, v[150:151]
	global_load_lds_dwordx4 v[226:227], off
	v_lshl_add_u64 v[226:227], s[82:83], 0, v[152:153]
	s_add_i32 m0, s63, 0x2000
	s_nop 0
	global_load_lds_dwordx4 v[226:227], off
	v_lshl_add_u64 v[226:227], s[68:69], 0, v[146:147]
	s_mov_b32 m0, s39
	s_nop 0
	global_load_lds_dwordx4 v[226:227], off
	s_mov_b32 m0, s41
	s_nop 0
	global_load_lds_dwordx4 v[228:229], off
	s_waitcnt vmcnt(8)
	s_waitcnt lgkmcnt(0)
	s_barrier
	s_waitcnt lgkmcnt(0)
	v_mfma_f32_16x16x32_bf16 v[74:77], v[30:33], v[180:183], v[74:77]
	v_mfma_f32_16x16x32_bf16 v[78:81], v[42:45], v[180:183], v[78:81]
	v_mfma_f32_16x16x32_bf16 v[58:61], v[30:33], v[188:191], v[58:61]
	v_mfma_f32_16x16x32_bf16 v[62:65], v[42:45], v[188:191], v[62:65]
	v_mfma_f32_16x16x32_bf16 v[26:29], v[30:33], v[206:209], v[26:29]
	v_mfma_f32_16x16x32_bf16 v[34:37], v[42:45], v[206:209], v[34:37]
	v_mfma_f32_16x16x32_bf16 v[10:13], v[30:33], v[214:217], v[10:13]
	v_mfma_f32_16x16x32_bf16 v[14:17], v[42:45], v[214:217], v[14:17]
	v_mfma_f32_16x16x32_bf16 v[74:77], v[38:41], v[184:187], v[74:77]
	v_mfma_f32_16x16x32_bf16 v[78:81], v[50:53], v[184:187], v[78:81]
	v_mfma_f32_16x16x32_bf16 v[58:61], v[38:41], v[192:195], v[58:61]
	v_mfma_f32_16x16x32_bf16 v[62:65], v[50:53], v[192:195], v[62:65]
	v_mfma_f32_16x16x32_bf16 v[26:29], v[38:41], v[210:213], v[26:29]
	v_mfma_f32_16x16x32_bf16 v[34:37], v[50:53], v[210:213], v[34:37]
	v_mfma_f32_16x16x32_bf16 v[10:13], v[38:41], v[218:221], v[10:13]
	v_mfma_f32_16x16x32_bf16 v[14:17], v[50:53], v[218:221], v[14:17]
	v_mfma_f32_16x16x32_bf16 v[18:21], v[164:167], v[206:209], v[18:21]
	v_mfma_f32_16x16x32_bf16 v[22:25], v[172:175], v[206:209], v[22:25]
	v_mfma_f32_16x16x32_bf16 v[2:5], v[164:167], v[214:217], v[2:5]
	v_mfma_f32_16x16x32_bf16 v[6:9], v[172:175], v[214:217], v[6:9]
	v_mfma_f32_16x16x32_bf16 v[30:33], v[164:167], v[180:183], v[66:69]
	v_mfma_f32_16x16x32_bf16 v[38:41], v[172:175], v[180:183], v[70:73]
	v_mfma_f32_16x16x32_bf16 v[42:45], v[164:167], v[188:191], v[46:49]
	v_mfma_f32_16x16x32_bf16 v[46:49], v[172:175], v[188:191], v[54:57]
	v_mfma_f32_16x16x32_bf16 v[18:21], v[168:171], v[210:213], v[18:21]
	v_mfma_f32_16x16x32_bf16 v[22:25], v[176:179], v[210:213], v[22:25]
	v_mfma_f32_16x16x32_bf16 v[2:5], v[168:171], v[218:221], v[2:5]
	v_mfma_f32_16x16x32_bf16 v[6:9], v[176:179], v[218:221], v[6:9]
	v_mfma_f32_16x16x32_bf16 v[30:33], v[168:171], v[184:187], v[30:33]
	v_mfma_f32_16x16x32_bf16 v[38:41], v[176:179], v[184:187], v[38:41]
	v_mfma_f32_16x16x32_bf16 v[42:45], v[168:171], v[192:195], v[42:45]
	s_setprio 3
	s_barrier
	v_mfma_f32_16x16x32_bf16 v[50:53], v[176:179], v[192:195], v[46:49]
	s_setprio 0
	s_add_i32 s63, 0, 0x18000
	s_add_i32 s82, 0, 0x1c000
	v_add_u32_e32 v70, s63, v196
	v_add_u32_e32 v155, s82, v196
	ds_read_b128 v[46:49], v70
	ds_read_b128 v[54:57], v70 offset:1024
	ds_read_b128 v[66:69], v70 offset:2048
	ds_read_b128 v[70:73], v70 offset:3072
	ds_read_b128 v[164:167], v155
	ds_read_b128 v[168:171], v155 offset:1024
	ds_read_b128 v[172:175], v155 offset:2048
	ds_read_b128 v[176:179], v155 offset:3072
	s_add_u32 s68, s68, 0x100000
	s_addc_u32 s69, s69, 0
	s_mov_b32 m0, s43
	v_lshl_add_u64 v[230:231], s[68:69], 0, v[146:147]
	ds_read_b128 v[180:183], v202 offset:32768
	ds_read_b128 v[184:187], v202 offset:33792
	ds_read_b128 v[188:191], v202 offset:34816
	ds_read_b128 v[192:195], v202 offset:35840
	ds_read_b128 v[206:209], v202 offset:36864
	ds_read_b128 v[210:213], v202 offset:37888
	ds_read_b128 v[214:217], v202 offset:38912
	ds_read_b128 v[218:221], v202 offset:39936
	global_load_lds_dwordx4 v[230:231], off
	v_lshl_add_u64 v[230:231], s[68:69], 0, v[150:151]
	s_mov_b32 m0, s57
	s_nop 0
	global_load_lds_dwordx4 v[230:231], off
	s_waitcnt vmcnt(8)
	s_waitcnt lgkmcnt(0)
	s_barrier
	s_waitcnt lgkmcnt(0)
	v_mfma_f32_16x16x32_bf16 v[138:141], v[46:49], v[180:183], v[138:141]
	v_mfma_f32_16x16x32_bf16 v[142:145], v[66:69], v[180:183], v[142:145]
	v_mfma_f32_16x16x32_bf16 v[122:125], v[46:49], v[188:191], v[122:125]
	v_mfma_f32_16x16x32_bf16 v[126:129], v[66:69], v[188:191], v[126:129]
	v_mfma_f32_16x16x32_bf16 v[106:109], v[46:49], v[206:209], v[106:109]
	v_mfma_f32_16x16x32_bf16 v[110:113], v[66:69], v[206:209], v[110:113]
	v_mfma_f32_16x16x32_bf16 v[90:93], v[46:49], v[214:217], v[90:93]
	v_mfma_f32_16x16x32_bf16 v[94:97], v[66:69], v[214:217], v[94:97]
	v_mfma_f32_16x16x32_bf16 v[138:141], v[54:57], v[184:187], v[138:141]
	v_mfma_f32_16x16x32_bf16 v[142:145], v[70:73], v[184:187], v[142:145]
	v_mfma_f32_16x16x32_bf16 v[122:125], v[54:57], v[192:195], v[122:125]
	v_mfma_f32_16x16x32_bf16 v[126:129], v[70:73], v[192:195], v[126:129]
	v_mfma_f32_16x16x32_bf16 v[106:109], v[54:57], v[210:213], v[106:109]
	v_mfma_f32_16x16x32_bf16 v[110:113], v[70:73], v[210:213], v[110:113]
	v_mfma_f32_16x16x32_bf16 v[90:93], v[54:57], v[218:221], v[90:93]
	v_mfma_f32_16x16x32_bf16 v[94:97], v[70:73], v[218:221], v[94:97]
	v_mfma_f32_16x16x32_bf16 v[130:133], v[164:167], v[180:183], v[130:133]
	v_mfma_f32_16x16x32_bf16 v[134:137], v[172:175], v[180:183], v[134:137]
	v_mfma_f32_16x16x32_bf16 v[114:117], v[164:167], v[188:191], v[114:117]
	v_mfma_f32_16x16x32_bf16 v[118:121], v[172:175], v[188:191], v[118:121]
	v_mfma_f32_16x16x32_bf16 v[98:101], v[164:167], v[206:209], v[98:101]
	v_mfma_f32_16x16x32_bf16 v[102:105], v[172:175], v[206:209], v[102:105]
	v_mfma_f32_16x16x32_bf16 v[82:85], v[164:167], v[214:217], v[82:85]
	v_mfma_f32_16x16x32_bf16 v[86:89], v[172:175], v[214:217], v[86:89]
	v_mfma_f32_16x16x32_bf16 v[130:133], v[168:171], v[184:187], v[130:133]
	v_mfma_f32_16x16x32_bf16 v[134:137], v[176:179], v[184:187], v[134:137]
	v_mfma_f32_16x16x32_bf16 v[114:117], v[168:171], v[192:195], v[114:117]
	v_mfma_f32_16x16x32_bf16 v[118:121], v[176:179], v[192:195], v[118:121]
	v_mfma_f32_16x16x32_bf16 v[98:101], v[168:171], v[210:213], v[98:101]
	v_mfma_f32_16x16x32_bf16 v[102:105], v[176:179], v[210:213], v[102:105]
	v_mfma_f32_16x16x32_bf16 v[82:85], v[168:171], v[218:221], v[82:85]
	s_setprio 3
	s_barrier
	v_mfma_f32_16x16x32_bf16 v[86:89], v[176:179], v[218:221], v[86:89]
	s_setprio 0
	s_add_i32 s63, s63, s37
	v_lshl_add_u64 v[222:223], v[222:223], 0, s[26:27]
	s_mov_b32 m0, s63
	ds_read_b128 v[180:183], v202 offset:49152
	ds_read_b128 v[184:187], v202 offset:50176
	ds_read_b128 v[188:191], v202 offset:51200
	ds_read_b128 v[192:195], v202 offset:52224
	ds_read_b128 v[206:209], v202 offset:53248
	ds_read_b128 v[210:213], v202 offset:54272
	ds_read_b128 v[214:217], v202 offset:55296
	ds_read_b128 v[218:221], v202 offset:56320
	global_load_lds_dwordx4 v[222:223], off
	s_add_i32 m0, s63, 0x2000
	s_add_u32 s18, s18, 0x100080
	v_lshl_add_u64 v[222:223], v[224:225], 0, s[26:27]
	s_addc_u32 s19, s19, 0
	s_add_i32 s63, s82, s37
	global_load_lds_dwordx4 v[222:223], off
	v_lshl_add_u64 v[222:223], s[18:19], 0, v[148:149]
	s_mov_b32 m0, s63
	s_nop 0
	global_load_lds_dwordx4 v[222:223], off
	v_lshl_add_u64 v[222:223], s[18:19], 0, v[152:153]
	s_add_i32 m0, s63, 0x2000
	s_nop 0
	global_load_lds_dwordx4 v[222:223], off
	v_lshl_add_u64 v[222:223], v[226:227], 0, s[26:27]
	s_mov_b32 m0, s71
	s_nop 0
	global_load_lds_dwordx4 v[222:223], off
	v_lshl_add_u64 v[222:223], v[228:229], 0, s[26:27]
	s_mov_b32 m0, s72
	s_nop 0
	global_load_lds_dwordx4 v[222:223], off
	s_waitcnt vmcnt(8)
	s_waitcnt lgkmcnt(0)
	s_barrier
	s_waitcnt lgkmcnt(0)
	v_mfma_f32_16x16x32_bf16 v[74:77], v[46:49], v[180:183], v[74:77]
	v_mfma_f32_16x16x32_bf16 v[78:81], v[66:69], v[180:183], v[78:81]
	v_mfma_f32_16x16x32_bf16 v[58:61], v[46:49], v[188:191], v[58:61]
	v_mfma_f32_16x16x32_bf16 v[62:65], v[66:69], v[188:191], v[62:65]
	v_mfma_f32_16x16x32_bf16 v[26:29], v[46:49], v[206:209], v[26:29]
	v_mfma_f32_16x16x32_bf16 v[34:37], v[66:69], v[206:209], v[34:37]
	v_mfma_f32_16x16x32_bf16 v[10:13], v[46:49], v[214:217], v[10:13]
	v_mfma_f32_16x16x32_bf16 v[14:17], v[66:69], v[214:217], v[14:17]
	v_mfma_f32_16x16x32_bf16 v[74:77], v[54:57], v[184:187], v[74:77]
	v_mfma_f32_16x16x32_bf16 v[78:81], v[70:73], v[184:187], v[78:81]
	v_mfma_f32_16x16x32_bf16 v[58:61], v[54:57], v[192:195], v[58:61]
	v_mfma_f32_16x16x32_bf16 v[62:65], v[70:73], v[192:195], v[62:65]
	v_mfma_f32_16x16x32_bf16 v[26:29], v[54:57], v[210:213], v[26:29]
	v_mfma_f32_16x16x32_bf16 v[34:37], v[70:73], v[210:213], v[34:37]
	v_mfma_f32_16x16x32_bf16 v[10:13], v[54:57], v[218:221], v[10:13]
	v_mfma_f32_16x16x32_bf16 v[14:17], v[70:73], v[218:221], v[14:17]
	v_mfma_f32_16x16x32_bf16 v[30:33], v[164:167], v[180:183], v[30:33]
	v_mfma_f32_16x16x32_bf16 v[66:69], v[168:171], v[184:187], v[30:33]
	v_mfma_f32_16x16x32_bf16 v[30:33], v[172:175], v[180:183], v[38:41]
	v_mfma_f32_16x16x32_bf16 v[70:73], v[176:179], v[184:187], v[30:33]
	v_mfma_f32_16x16x32_bf16 v[30:33], v[164:167], v[188:191], v[42:45]
	v_mfma_f32_16x16x32_bf16 v[46:49], v[168:171], v[192:195], v[30:33]
	v_mfma_f32_16x16x32_bf16 v[30:33], v[172:175], v[188:191], v[50:53]
	v_mfma_f32_16x16x32_bf16 v[18:21], v[164:167], v[206:209], v[18:21]
	v_mfma_f32_16x16x32_bf16 v[22:25], v[172:175], v[206:209], v[22:25]
	v_mfma_f32_16x16x32_bf16 v[2:5], v[164:167], v[214:217], v[2:5]
	v_mfma_f32_16x16x32_bf16 v[6:9], v[172:175], v[214:217], v[6:9]
	v_mfma_f32_16x16x32_bf16 v[54:57], v[176:179], v[192:195], v[30:33]
	v_mfma_f32_16x16x32_bf16 v[18:21], v[168:171], v[210:213], v[18:21]
	v_mfma_f32_16x16x32_bf16 v[22:25], v[176:179], v[210:213], v[22:25]
	v_mfma_f32_16x16x32_bf16 v[2:5], v[168:171], v[218:221], v[2:5]
	s_setprio 3
	s_barrier
	v_mfma_f32_16x16x32_bf16 v[6:9], v[176:179], v[218:221], v[6:9]
	s_setprio 0
	s_add_i32 s61, s61, 2
	s_add_u32 s10, s10, 0x100
	s_addc_u32 s11, s11, 0
	s_add_u32 s16, s16, 0x100
	s_addc_u32 s17, s17, 0
	s_cmp_gt_u32 s61, 61
	s_cbranch_scc0 .LBB0_1647
	s_and_b64 vcc, exec, s[28:29]
	s_cbranch_vccz .LBB0_1650
	s_barrier

.LBB0_1920:
	s_ashr_i32 s31, s30, 31
	s_lshl_b64 s[34:35], s[30:31], 21
	s_add_u32 s34, s54, s34
	s_addc_u32 s35, s55, s35
	s_and_b64 s[36:37], s[2:3], exec
	s_cselect_b32 s31, s35, s39
	s_cselect_b32 s69, s34, s38
	s_ashr_i32 s29, s28, 31
	s_lshl_b64 s[36:37], s[28:29], 21
	s_add_u32 s36, s1, s36
	s_addc_u32 s37, s16, s37
	s_and_b64 s[42:43], s[2:3], exec
	s_cselect_b32 s29, s37, s41
	s_cselect_b32 s70, s36, s40
	s_add_u32 s38, s38, 0x100080
	s_addc_u32 s39, s39, 0
	s_add_u32 s71, s40, 0x100
	s_addc_u32 s72, s41, 0
	s_mov_b32 s73, -2
	ds_read_b128 v[130:133], v212
	ds_read_b128 v[134:137], v212 offset:1024
	ds_read_b128 v[138:141], v212 offset:2048
	ds_read_b128 v[142:145], v212 offset:3072
	ds_read_b128 v[146:149], v213
	ds_read_b128 v[150:153], v213 offset:1024
	ds_read_b128 v[154:157], v213 offset:2048
	ds_read_b128 v[158:161], v213 offset:3072
	s_add_u32 s40, s38, 0xfff00080
	s_addc_u32 s41, s39, -1
	s_cmp_eq_u32 s73, 60
	s_cselect_b32 s43, s31, s41
	s_cselect_b32 s42, s69, s40
	s_cselect_b32 s41, s29, s72
	s_cselect_b32 s40, s70, s71
	v_lshl_add_u64 v[216:217], s[38:39], 0, v[178:179]
	s_add_i32 m0, s19, 0xc000
	ds_read_b128 v[162:165], v214
	ds_read_b128 v[166:169], v214 offset:1024
	ds_read_b128 v[186:189], v214 offset:2048
	ds_read_b128 v[190:193], v214 offset:3072
	ds_read_b128 v[194:197], v214 offset:4096
	ds_read_b128 v[198:201], v214 offset:5120
	ds_read_b128 v[202:205], v214 offset:6144
	ds_read_b128 v[206:209], v214 offset:7168
	global_load_lds_dwordx4 v[216:217], off
	v_lshl_add_u64 v[216:217], s[38:39], 0, v[180:181]
	s_add_i32 m0, s19, 0xe000
	s_nop 0
	global_load_lds_dwordx4 v[216:217], off
	s_waitcnt vmcnt(8)
	s_waitcnt lgkmcnt(0)
	s_barrier
	s_waitcnt lgkmcnt(0)
	v_mfma_f32_16x16x32_bf16 v[126:129], v[130:133], v[162:165], 0
	v_mfma_f32_16x16x32_bf16 v[122:125], v[138:141], v[162:165], 0
	v_mfma_f32_16x16x32_bf16 v[110:113], v[130:133], v[186:189], 0
	v_mfma_f32_16x16x32_bf16 v[106:109], v[138:141], v[186:189], 0
	v_mfma_f32_16x16x32_bf16 v[94:97], v[130:133], v[194:197], 0
	v_mfma_f32_16x16x32_bf16 v[90:93], v[138:141], v[194:197], 0
	v_mfma_f32_16x16x32_bf16 v[78:81], v[130:133], v[202:205], 0
	v_mfma_f32_16x16x32_bf16 v[74:77], v[138:141], v[202:205], 0
	v_mfma_f32_16x16x32_bf16 v[126:129], v[134:137], v[166:169], v[126:129]
	v_mfma_f32_16x16x32_bf16 v[122:125], v[142:145], v[166:169], v[122:125]
	v_mfma_f32_16x16x32_bf16 v[110:113], v[134:137], v[190:193], v[110:113]
	v_mfma_f32_16x16x32_bf16 v[106:109], v[142:145], v[190:193], v[106:109]
	v_mfma_f32_16x16x32_bf16 v[94:97], v[134:137], v[198:201], v[94:97]
	v_mfma_f32_16x16x32_bf16 v[90:93], v[142:145], v[198:201], v[90:93]
	v_mfma_f32_16x16x32_bf16 v[78:81], v[134:137], v[206:209], v[78:81]
	v_mfma_f32_16x16x32_bf16 v[74:77], v[142:145], v[206:209], v[74:77]
	v_mfma_f32_16x16x32_bf16 v[118:121], v[146:149], v[162:165], 0
	v_mfma_f32_16x16x32_bf16 v[114:117], v[154:157], v[162:165], 0
	v_mfma_f32_16x16x32_bf16 v[102:105], v[146:149], v[186:189], 0
	v_mfma_f32_16x16x32_bf16 v[98:101], v[154:157], v[186:189], 0
	v_mfma_f32_16x16x32_bf16 v[86:89], v[146:149], v[194:197], 0
	v_mfma_f32_16x16x32_bf16 v[82:85], v[154:157], v[194:197], 0
	v_mfma_f32_16x16x32_bf16 v[70:73], v[146:149], v[202:205], 0
	v_mfma_f32_16x16x32_bf16 v[66:69], v[154:157], v[202:205], 0
	v_mfma_f32_16x16x32_bf16 v[118:121], v[150:153], v[166:169], v[118:121]
	v_mfma_f32_16x16x32_bf16 v[114:117], v[158:161], v[166:169], v[114:117]
	v_mfma_f32_16x16x32_bf16 v[102:105], v[150:153], v[190:193], v[102:105]
	v_mfma_f32_16x16x32_bf16 v[98:101], v[158:161], v[190:193], v[98:101]
	v_mfma_f32_16x16x32_bf16 v[86:89], v[150:153], v[198:201], v[86:89]
	v_mfma_f32_16x16x32_bf16 v[82:85], v[158:161], v[198:201], v[82:85]
	v_mfma_f32_16x16x32_bf16 v[70:73], v[150:153], v[206:209], v[70:73]
	s_setprio 3
	s_barrier
	v_mfma_f32_16x16x32_bf16 v[66:69], v[158:161], v[206:209], v[66:69]
	s_setprio 0
	s_add_i32 s76, s57, s17
	v_lshl_add_u64 v[216:217], s[40:41], 0, v[172:173]
	s_mov_b32 m0, s76
	ds_read_b128 v[162:165], v214 offset:16384
	ds_read_b128 v[166:169], v214 offset:17408
	ds_read_b128 v[186:189], v214 offset:18432
	ds_read_b128 v[190:193], v214 offset:19456
	ds_read_b128 v[194:197], v214 offset:20480
	ds_read_b128 v[198:201], v214 offset:21504
	ds_read_b128 v[202:205], v214 offset:22528
	ds_read_b128 v[206:209], v214 offset:23552
	global_load_lds_dwordx4 v[216:217], off
	s_add_i32 m0, s76, 0x2000
	s_add_u32 s76, s40, 0x100000
	v_lshl_add_u64 v[218:219], s[40:41], 0, v[176:177]
	s_addc_u32 s77, s41, 0
	s_add_i32 s78, s60, s17
	global_load_lds_dwordx4 v[218:219], off
	v_lshl_add_u64 v[220:221], s[76:77], 0, v[172:173]
	s_mov_b32 m0, s78
	v_lshl_add_u64 v[222:223], s[42:43], 0, v[174:175]
	global_load_lds_dwordx4 v[220:221], off
	v_lshl_add_u64 v[220:221], s[76:77], 0, v[176:177]
	s_add_i32 m0, s78, 0x2000
	s_nop 0
	global_load_lds_dwordx4 v[220:221], off
	v_lshl_add_u64 v[220:221], s[42:43], 0, v[170:171]
	s_mov_b32 m0, s19
	s_nop 0
	global_load_lds_dwordx4 v[220:221], off
	s_mov_b32 m0, s44
	s_nop 0
	global_load_lds_dwordx4 v[222:223], off
	s_waitcnt vmcnt(8)
	s_waitcnt lgkmcnt(0)
	s_barrier
	s_waitcnt lgkmcnt(0)
	v_mfma_f32_16x16x32_bf16 v[62:65], v[130:133], v[162:165], 0
	v_mfma_f32_16x16x32_bf16 v[58:61], v[138:141], v[162:165], 0
	v_mfma_f32_16x16x32_bf16 v[46:49], v[130:133], v[186:189], 0
	v_mfma_f32_16x16x32_bf16 v[42:45], v[138:141], v[186:189], 0
	v_mfma_f32_16x16x32_bf16 v[30:33], v[130:133], v[194:197], 0
	v_mfma_f32_16x16x32_bf16 v[26:29], v[138:141], v[194:197], 0
	v_mfma_f32_16x16x32_bf16 v[14:17], v[130:133], v[202:205], 0
	v_mfma_f32_16x16x32_bf16 v[10:13], v[138:141], v[202:205], 0
	v_mfma_f32_16x16x32_bf16 v[62:65], v[134:137], v[166:169], v[62:65]
	v_mfma_f32_16x16x32_bf16 v[58:61], v[142:145], v[166:169], v[58:61]
	v_mfma_f32_16x16x32_bf16 v[46:49], v[134:137], v[190:193], v[46:49]
	v_mfma_f32_16x16x32_bf16 v[42:45], v[142:145], v[190:193], v[42:45]
	v_mfma_f32_16x16x32_bf16 v[30:33], v[134:137], v[198:201], v[30:33]
	v_mfma_f32_16x16x32_bf16 v[26:29], v[142:145], v[198:201], v[26:29]
	v_mfma_f32_16x16x32_bf16 v[14:17], v[134:137], v[206:209], v[14:17]
	v_mfma_f32_16x16x32_bf16 v[10:13], v[142:145], v[206:209], v[10:13]
	v_mfma_f32_16x16x32_bf16 v[54:57], v[146:149], v[162:165], 0
	v_mfma_f32_16x16x32_bf16 v[50:53], v[154:157], v[162:165], 0
	v_mfma_f32_16x16x32_bf16 v[38:41], v[146:149], v[186:189], 0
	v_mfma_f32_16x16x32_bf16 v[34:37], v[154:157], v[186:189], 0
	v_mfma_f32_16x16x32_bf16 v[22:25], v[146:149], v[194:197], 0
	v_mfma_f32_16x16x32_bf16 v[18:21], v[154:157], v[194:197], 0
	v_mfma_f32_16x16x32_bf16 v[6:9], v[146:149], v[202:205], 0
	v_mfma_f32_16x16x32_bf16 v[2:5], v[154:157], v[202:205], 0
	v_mfma_f32_16x16x32_bf16 v[54:57], v[150:153], v[166:169], v[54:57]
	v_mfma_f32_16x16x32_bf16 v[50:53], v[158:161], v[166:169], v[50:53]
	v_mfma_f32_16x16x32_bf16 v[38:41], v[150:153], v[190:193], v[38:41]
	v_mfma_f32_16x16x32_bf16 v[34:37], v[158:161], v[190:193], v[34:37]
	v_mfma_f32_16x16x32_bf16 v[22:25], v[150:153], v[198:201], v[22:25]
	v_mfma_f32_16x16x32_bf16 v[18:21], v[158:161], v[198:201], v[18:21]
	v_mfma_f32_16x16x32_bf16 v[6:9], v[150:153], v[206:209], v[6:9]
	s_setprio 3
	s_barrier
	v_mfma_f32_16x16x32_bf16 v[2:5], v[158:161], v[206:209], v[2:5]
	s_setprio 0
	s_add_i32 s76, 0, 0x18000
	s_add_i32 s77, 0, 0x1c000
	v_add_u32_e32 v142, s76, v211
	v_add_u32_e32 v158, s77, v211
	ds_read_b128 v[130:133], v142
	ds_read_b128 v[134:137], v142 offset:1024
	ds_read_b128 v[138:141], v142 offset:2048
	ds_read_b128 v[142:145], v142 offset:3072
	ds_read_b128 v[146:149], v158
	ds_read_b128 v[150:153], v158 offset:1024
	ds_read_b128 v[154:157], v158 offset:2048
	ds_read_b128 v[158:161], v158 offset:3072
	s_add_u32 s42, s42, 0x100000
	s_addc_u32 s43, s43, 0
	s_mov_b32 m0, s45
	v_lshl_add_u64 v[224:225], s[42:43], 0, v[170:171]
	ds_read_b128 v[162:165], v214 offset:32768
	ds_read_b128 v[166:169], v214 offset:33792
	ds_read_b128 v[186:189], v214 offset:34816
	ds_read_b128 v[190:193], v214 offset:35840
	ds_read_b128 v[194:197], v214 offset:36864
	ds_read_b128 v[198:201], v214 offset:37888
	ds_read_b128 v[202:205], v214 offset:38912
	ds_read_b128 v[206:209], v214 offset:39936
	global_load_lds_dwordx4 v[224:225], off
	v_lshl_add_u64 v[224:225], s[42:43], 0, v[174:175]
	s_mov_b32 m0, s46
	s_nop 0
	global_load_lds_dwordx4 v[224:225], off
	s_waitcnt vmcnt(8)
	s_waitcnt lgkmcnt(0)
	s_barrier
	s_waitcnt lgkmcnt(0)
	v_mfma_f32_16x16x32_bf16 v[126:129], v[130:133], v[162:165], v[126:129]
	v_mfma_f32_16x16x32_bf16 v[122:125], v[138:141], v[162:165], v[122:125]
	v_mfma_f32_16x16x32_bf16 v[110:113], v[130:133], v[186:189], v[110:113]
	v_mfma_f32_16x16x32_bf16 v[106:109], v[138:141], v[186:189], v[106:109]
	v_mfma_f32_16x16x32_bf16 v[94:97], v[130:133], v[194:197], v[94:97]
	v_mfma_f32_16x16x32_bf16 v[90:93], v[138:141], v[194:197], v[90:93]
	v_mfma_f32_16x16x32_bf16 v[78:81], v[130:133], v[202:205], v[78:81]
	v_mfma_f32_16x16x32_bf16 v[74:77], v[138:141], v[202:205], v[74:77]
	v_mfma_f32_16x16x32_bf16 v[126:129], v[134:137], v[166:169], v[126:129]
	v_mfma_f32_16x16x32_bf16 v[122:125], v[142:145], v[166:169], v[122:125]
	v_mfma_f32_16x16x32_bf16 v[110:113], v[134:137], v[190:193], v[110:113]
	v_mfma_f32_16x16x32_bf16 v[106:109], v[142:145], v[190:193], v[106:109]
	v_mfma_f32_16x16x32_bf16 v[94:97], v[134:137], v[198:201], v[94:97]
	v_mfma_f32_16x16x32_bf16 v[90:93], v[142:145], v[198:201], v[90:93]
	v_mfma_f32_16x16x32_bf16 v[78:81], v[134:137], v[206:209], v[78:81]
	v_mfma_f32_16x16x32_bf16 v[74:77], v[142:145], v[206:209], v[74:77]
	v_mfma_f32_16x16x32_bf16 v[118:121], v[146:149], v[162:165], v[118:121]
	v_mfma_f32_16x16x32_bf16 v[114:117], v[154:157], v[162:165], v[114:117]
	v_mfma_f32_16x16x32_bf16 v[102:105], v[146:149], v[186:189], v[102:105]
	v_mfma_f32_16x16x32_bf16 v[98:101], v[154:157], v[186:189], v[98:101]
	v_mfma_f32_16x16x32_bf16 v[86:89], v[146:149], v[194:197], v[86:89]
	v_mfma_f32_16x16x32_bf16 v[82:85], v[154:157], v[194:197], v[82:85]
	v_mfma_f32_16x16x32_bf16 v[70:73], v[146:149], v[202:205], v[70:73]
	v_mfma_f32_16x16x32_bf16 v[66:69], v[154:157], v[202:205], v[66:69]
	v_mfma_f32_16x16x32_bf16 v[118:121], v[150:153], v[166:169], v[118:121]
	v_mfma_f32_16x16x32_bf16 v[114:117], v[158:161], v[166:169], v[114:117]
	v_mfma_f32_16x16x32_bf16 v[102:105], v[150:153], v[190:193], v[102:105]
	v_mfma_f32_16x16x32_bf16 v[98:101], v[158:161], v[190:193], v[98:101]
	v_mfma_f32_16x16x32_bf16 v[86:89], v[150:153], v[198:201], v[86:89]
	v_mfma_f32_16x16x32_bf16 v[82:85], v[158:161], v[198:201], v[82:85]
	v_mfma_f32_16x16x32_bf16 v[70:73], v[150:153], v[206:209], v[70:73]
	s_setprio 3
	s_barrier
	v_mfma_f32_16x16x32_bf16 v[66:69], v[158:161], v[206:209], v[66:69]
	s_setprio 0
	s_add_i32 s42, s76, s17
	v_lshl_add_u64 v[216:217], v[216:217], 0, s[8:9]
	s_mov_b32 m0, s42
	ds_read_b128 v[162:165], v214 offset:49152
	ds_read_b128 v[166:169], v214 offset:50176
	ds_read_b128 v[186:189], v214 offset:51200
	ds_read_b128 v[190:193], v214 offset:52224
	ds_read_b128 v[194:197], v214 offset:53248
	ds_read_b128 v[198:201], v214 offset:54272
	ds_read_b128 v[202:205], v214 offset:55296
	ds_read_b128 v[206:209], v214 offset:56320
	global_load_lds_dwordx4 v[216:217], off
	s_add_i32 m0, s42, 0x2000
	s_add_u32 s40, s40, 0x100080
	v_lshl_add_u64 v[216:217], v[218:219], 0, s[8:9]
	s_addc_u32 s41, s41, 0
	s_add_i32 s42, s77, s17
	global_load_lds_dwordx4 v[216:217], off
	v_lshl_add_u64 v[216:217], s[40:41], 0, v[172:173]
	s_mov_b32 m0, s42
	s_nop 0
	global_load_lds_dwordx4 v[216:217], off
	v_lshl_add_u64 v[216:217], s[40:41], 0, v[176:177]
	s_add_i32 m0, s42, 0x2000
	s_nop 0
	global_load_lds_dwordx4 v[216:217], off
	v_lshl_add_u64 v[216:217], v[220:221], 0, s[8:9]
	s_mov_b32 m0, s50
	s_nop 0
	global_load_lds_dwordx4 v[216:217], off
	v_lshl_add_u64 v[216:217], v[222:223], 0, s[8:9]
	s_mov_b32 m0, s51
	s_nop 0
	global_load_lds_dwordx4 v[216:217], off
	s_waitcnt vmcnt(8)
	s_waitcnt lgkmcnt(0)
	s_barrier
	s_waitcnt lgkmcnt(0)
	v_mfma_f32_16x16x32_bf16 v[62:65], v[130:133], v[162:165], v[62:65]
	v_mfma_f32_16x16x32_bf16 v[58:61], v[138:141], v[162:165], v[58:61]
	v_mfma_f32_16x16x32_bf16 v[46:49], v[130:133], v[186:189], v[46:49]
	v_mfma_f32_16x16x32_bf16 v[42:45], v[138:141], v[186:189], v[42:45]
	v_mfma_f32_16x16x32_bf16 v[30:33], v[130:133], v[194:197], v[30:33]
	v_mfma_f32_16x16x32_bf16 v[26:29], v[138:141], v[194:197], v[26:29]
	v_mfma_f32_16x16x32_bf16 v[14:17], v[130:133], v[202:205], v[14:17]
	v_mfma_f32_16x16x32_bf16 v[10:13], v[138:141], v[202:205], v[10:13]
	v_mfma_f32_16x16x32_bf16 v[62:65], v[134:137], v[166:169], v[62:65]
	v_mfma_f32_16x16x32_bf16 v[58:61], v[142:145], v[166:169], v[58:61]
	v_mfma_f32_16x16x32_bf16 v[46:49], v[134:137], v[190:193], v[46:49]
	v_mfma_f32_16x16x32_bf16 v[42:45], v[142:145], v[190:193], v[42:45]
	v_mfma_f32_16x16x32_bf16 v[30:33], v[134:137], v[198:201], v[30:33]
	v_mfma_f32_16x16x32_bf16 v[26:29], v[142:145], v[198:201], v[26:29]
	v_mfma_f32_16x16x32_bf16 v[14:17], v[134:137], v[206:209], v[14:17]
	v_mfma_f32_16x16x32_bf16 v[10:13], v[142:145], v[206:209], v[10:13]
	v_mfma_f32_16x16x32_bf16 v[54:57], v[146:149], v[162:165], v[54:57]
	v_mfma_f32_16x16x32_bf16 v[50:53], v[154:157], v[162:165], v[50:53]
	v_mfma_f32_16x16x32_bf16 v[38:41], v[146:149], v[186:189], v[38:41]
	v_mfma_f32_16x16x32_bf16 v[34:37], v[154:157], v[186:189], v[34:37]
	v_mfma_f32_16x16x32_bf16 v[22:25], v[146:149], v[194:197], v[22:25]
	v_mfma_f32_16x16x32_bf16 v[18:21], v[154:157], v[194:197], v[18:21]
	v_mfma_f32_16x16x32_bf16 v[6:9], v[146:149], v[202:205], v[6:9]
	v_mfma_f32_16x16x32_bf16 v[2:5], v[154:157], v[202:205], v[2:5]
	v_mfma_f32_16x16x32_bf16 v[54:57], v[150:153], v[166:169], v[54:57]
	v_mfma_f32_16x16x32_bf16 v[50:53], v[158:161], v[166:169], v[50:53]
	v_mfma_f32_16x16x32_bf16 v[38:41], v[150:153], v[190:193], v[38:41]
	v_mfma_f32_16x16x32_bf16 v[34:37], v[158:161], v[190:193], v[34:37]
	v_mfma_f32_16x16x32_bf16 v[22:25], v[150:153], v[198:201], v[22:25]
	v_mfma_f32_16x16x32_bf16 v[18:21], v[158:161], v[198:201], v[18:21]
	v_mfma_f32_16x16x32_bf16 v[6:9], v[150:153], v[206:209], v[6:9]
	s_setprio 3
	s_barrier
	v_mfma_f32_16x16x32_bf16 v[2:5], v[158:161], v[206:209], v[2:5]
	s_setprio 0
	s_add_i32 s73, s73, 2
	s_add_u32 s38, s38, 0x100
	s_addc_u32 s39, s39, 0
	s_add_u32 s71, s71, 0x100
	s_addc_u32 s72, s72, 0
	s_cmp_gt_u32 s73, 61
.LBB0_1921:
	ds_read_b128 v[130:133], v212
	ds_read_b128 v[134:137], v212 offset:1024
	ds_read_b128 v[138:141], v212 offset:2048
	ds_read_b128 v[142:145], v212 offset:3072
	ds_read_b128 v[146:149], v213
	ds_read_b128 v[150:153], v213 offset:1024
	ds_read_b128 v[154:157], v213 offset:2048
	ds_read_b128 v[158:161], v213 offset:3072
	s_add_u32 s40, s38, 0xfff00080
	s_addc_u32 s41, s39, -1
	s_cmp_eq_u32 s73, 60
	s_cselect_b32 s43, s31, s41
	s_cselect_b32 s42, s69, s40
	s_cselect_b32 s41, s29, s72
	s_cselect_b32 s40, s70, s71
	v_lshl_add_u64 v[216:217], s[38:39], 0, v[178:179]
	s_add_i32 m0, s19, 0xc000
	ds_read_b128 v[162:165], v214
	ds_read_b128 v[166:169], v214 offset:1024
	ds_read_b128 v[186:189], v214 offset:2048
	ds_read_b128 v[190:193], v214 offset:3072
	ds_read_b128 v[194:197], v214 offset:4096
	ds_read_b128 v[198:201], v214 offset:5120
	ds_read_b128 v[202:205], v214 offset:6144
	ds_read_b128 v[206:209], v214 offset:7168
	global_load_lds_dwordx4 v[216:217], off
	v_lshl_add_u64 v[216:217], s[38:39], 0, v[180:181]
	s_add_i32 m0, s19, 0xe000
	s_nop 0
	global_load_lds_dwordx4 v[216:217], off
	s_waitcnt vmcnt(8)
	s_waitcnt lgkmcnt(0)
	s_barrier
	s_waitcnt lgkmcnt(0)
	v_mfma_f32_16x16x32_bf16 v[126:129], v[130:133], v[162:165], v[126:129]
	v_mfma_f32_16x16x32_bf16 v[122:125], v[138:141], v[162:165], v[122:125]
	v_mfma_f32_16x16x32_bf16 v[110:113], v[130:133], v[186:189], v[110:113]
	v_mfma_f32_16x16x32_bf16 v[106:109], v[138:141], v[186:189], v[106:109]
	v_mfma_f32_16x16x32_bf16 v[94:97], v[130:133], v[194:197], v[94:97]
	v_mfma_f32_16x16x32_bf16 v[90:93], v[138:141], v[194:197], v[90:93]
	v_mfma_f32_16x16x32_bf16 v[78:81], v[130:133], v[202:205], v[78:81]
	v_mfma_f32_16x16x32_bf16 v[74:77], v[138:141], v[202:205], v[74:77]
	v_mfma_f32_16x16x32_bf16 v[126:129], v[134:137], v[166:169], v[126:129]
	v_mfma_f32_16x16x32_bf16 v[122:125], v[142:145], v[166:169], v[122:125]
	v_mfma_f32_16x16x32_bf16 v[110:113], v[134:137], v[190:193], v[110:113]
	v_mfma_f32_16x16x32_bf16 v[106:109], v[142:145], v[190:193], v[106:109]
	v_mfma_f32_16x16x32_bf16 v[94:97], v[134:137], v[198:201], v[94:97]
	v_mfma_f32_16x16x32_bf16 v[90:93], v[142:145], v[198:201], v[90:93]
	v_mfma_f32_16x16x32_bf16 v[78:81], v[134:137], v[206:209], v[78:81]
	v_mfma_f32_16x16x32_bf16 v[74:77], v[142:145], v[206:209], v[74:77]
	v_mfma_f32_16x16x32_bf16 v[118:121], v[146:149], v[162:165], v[118:121]
	v_mfma_f32_16x16x32_bf16 v[114:117], v[154:157], v[162:165], v[114:117]
	v_mfma_f32_16x16x32_bf16 v[102:105], v[146:149], v[186:189], v[102:105]
	v_mfma_f32_16x16x32_bf16 v[98:101], v[154:157], v[186:189], v[98:101]
	v_mfma_f32_16x16x32_bf16 v[86:89], v[146:149], v[194:197], v[86:89]
	v_mfma_f32_16x16x32_bf16 v[82:85], v[154:157], v[194:197], v[82:85]
	v_mfma_f32_16x16x32_bf16 v[70:73], v[146:149], v[202:205], v[70:73]
	v_mfma_f32_16x16x32_bf16 v[66:69], v[154:157], v[202:205], v[66:69]
	v_mfma_f32_16x16x32_bf16 v[118:121], v[150:153], v[166:169], v[118:121]
	v_mfma_f32_16x16x32_bf16 v[114:117], v[158:161], v[166:169], v[114:117]
	v_mfma_f32_16x16x32_bf16 v[102:105], v[150:153], v[190:193], v[102:105]
	v_mfma_f32_16x16x32_bf16 v[98:101], v[158:161], v[190:193], v[98:101]
	v_mfma_f32_16x16x32_bf16 v[86:89], v[150:153], v[198:201], v[86:89]
	v_mfma_f32_16x16x32_bf16 v[82:85], v[158:161], v[198:201], v[82:85]
	v_mfma_f32_16x16x32_bf16 v[70:73], v[150:153], v[206:209], v[70:73]
	s_setprio 3
	s_barrier
	v_mfma_f32_16x16x32_bf16 v[66:69], v[158:161], v[206:209], v[66:69]
	s_setprio 0
	s_add_i32 s76, s57, s17
	v_lshl_add_u64 v[216:217], s[40:41], 0, v[172:173]
	s_mov_b32 m0, s76
	ds_read_b128 v[162:165], v214 offset:16384
	ds_read_b128 v[166:169], v214 offset:17408
	ds_read_b128 v[186:189], v214 offset:18432
	ds_read_b128 v[190:193], v214 offset:19456
	ds_read_b128 v[194:197], v214 offset:20480
	ds_read_b128 v[198:201], v214 offset:21504
	ds_read_b128 v[202:205], v214 offset:22528
	ds_read_b128 v[206:209], v214 offset:23552
	global_load_lds_dwordx4 v[216:217], off
	s_add_i32 m0, s76, 0x2000
	s_add_u32 s76, s40, 0x100000
	v_lshl_add_u64 v[218:219], s[40:41], 0, v[176:177]
	s_addc_u32 s77, s41, 0
	s_add_i32 s78, s60, s17
	global_load_lds_dwordx4 v[218:219], off
	v_lshl_add_u64 v[220:221], s[76:77], 0, v[172:173]
	s_mov_b32 m0, s78
	v_lshl_add_u64 v[222:223], s[42:43], 0, v[174:175]
	global_load_lds_dwordx4 v[220:221], off
	v_lshl_add_u64 v[220:221], s[76:77], 0, v[176:177]
	s_add_i32 m0, s78, 0x2000
	s_nop 0
	global_load_lds_dwordx4 v[220:221], off
	v_lshl_add_u64 v[220:221], s[42:43], 0, v[170:171]
	s_mov_b32 m0, s19
	s_nop 0
	global_load_lds_dwordx4 v[220:221], off
	s_mov_b32 m0, s44
	s_nop 0
	global_load_lds_dwordx4 v[222:223], off
	s_waitcnt vmcnt(8)
	s_waitcnt lgkmcnt(0)
	s_barrier
	s_waitcnt lgkmcnt(0)
	v_mfma_f32_16x16x32_bf16 v[62:65], v[130:133], v[162:165], v[62:65]
	v_mfma_f32_16x16x32_bf16 v[58:61], v[138:141], v[162:165], v[58:61]
	v_mfma_f32_16x16x32_bf16 v[46:49], v[130:133], v[186:189], v[46:49]
	v_mfma_f32_16x16x32_bf16 v[42:45], v[138:141], v[186:189], v[42:45]
	v_mfma_f32_16x16x32_bf16 v[30:33], v[130:133], v[194:197], v[30:33]
	v_mfma_f32_16x16x32_bf16 v[26:29], v[138:141], v[194:197], v[26:29]
	v_mfma_f32_16x16x32_bf16 v[14:17], v[130:133], v[202:205], v[14:17]
	v_mfma_f32_16x16x32_bf16 v[10:13], v[138:141], v[202:205], v[10:13]
	v_mfma_f32_16x16x32_bf16 v[62:65], v[134:137], v[166:169], v[62:65]
	v_mfma_f32_16x16x32_bf16 v[58:61], v[142:145], v[166:169], v[58:61]
	v_mfma_f32_16x16x32_bf16 v[46:49], v[134:137], v[190:193], v[46:49]
	v_mfma_f32_16x16x32_bf16 v[42:45], v[142:145], v[190:193], v[42:45]
	v_mfma_f32_16x16x32_bf16 v[30:33], v[134:137], v[198:201], v[30:33]
	v_mfma_f32_16x16x32_bf16 v[26:29], v[142:145], v[198:201], v[26:29]
	v_mfma_f32_16x16x32_bf16 v[14:17], v[134:137], v[206:209], v[14:17]
	v_mfma_f32_16x16x32_bf16 v[10:13], v[142:145], v[206:209], v[10:13]
	v_mfma_f32_16x16x32_bf16 v[54:57], v[146:149], v[162:165], v[54:57]
	v_mfma_f32_16x16x32_bf16 v[50:53], v[154:157], v[162:165], v[50:53]
	v_mfma_f32_16x16x32_bf16 v[38:41], v[146:149], v[186:189], v[38:41]
	v_mfma_f32_16x16x32_bf16 v[34:37], v[154:157], v[186:189], v[34:37]
	v_mfma_f32_16x16x32_bf16 v[22:25], v[146:149], v[194:197], v[22:25]
	v_mfma_f32_16x16x32_bf16 v[18:21], v[154:157], v[194:197], v[18:21]
	v_mfma_f32_16x16x32_bf16 v[6:9], v[146:149], v[202:205], v[6:9]
	v_mfma_f32_16x16x32_bf16 v[2:5], v[154:157], v[202:205], v[2:5]
	v_mfma_f32_16x16x32_bf16 v[54:57], v[150:153], v[166:169], v[54:57]
	v_mfma_f32_16x16x32_bf16 v[50:53], v[158:161], v[166:169], v[50:53]
	v_mfma_f32_16x16x32_bf16 v[38:41], v[150:153], v[190:193], v[38:41]
	v_mfma_f32_16x16x32_bf16 v[34:37], v[158:161], v[190:193], v[34:37]
	v_mfma_f32_16x16x32_bf16 v[22:25], v[150:153], v[198:201], v[22:25]
	v_mfma_f32_16x16x32_bf16 v[18:21], v[158:161], v[198:201], v[18:21]
	v_mfma_f32_16x16x32_bf16 v[6:9], v[150:153], v[206:209], v[6:9]
	s_setprio 3
	s_barrier
	v_mfma_f32_16x16x32_bf16 v[2:5], v[158:161], v[206:209], v[2:5]
	s_setprio 0
	s_add_i32 s76, 0, 0x18000
	s_add_i32 s77, 0, 0x1c000
	v_add_u32_e32 v142, s76, v211
	v_add_u32_e32 v158, s77, v211
	ds_read_b128 v[130:133], v142
	ds_read_b128 v[134:137], v142 offset:1024
	ds_read_b128 v[138:141], v142 offset:2048
	ds_read_b128 v[142:145], v142 offset:3072
	ds_read_b128 v[146:149], v158
	ds_read_b128 v[150:153], v158 offset:1024
	ds_read_b128 v[154:157], v158 offset:2048
	ds_read_b128 v[158:161], v158 offset:3072
	s_add_u32 s42, s42, 0x100000
	s_addc_u32 s43, s43, 0
	s_mov_b32 m0, s45
	v_lshl_add_u64 v[224:225], s[42:43], 0, v[170:171]
	ds_read_b128 v[162:165], v214 offset:32768
	ds_read_b128 v[166:169], v214 offset:33792
	ds_read_b128 v[186:189], v214 offset:34816
	ds_read_b128 v[190:193], v214 offset:35840
	ds_read_b128 v[194:197], v214 offset:36864
	ds_read_b128 v[198:201], v214 offset:37888
	ds_read_b128 v[202:205], v214 offset:38912
	ds_read_b128 v[206:209], v214 offset:39936
	global_load_lds_dwordx4 v[224:225], off
	v_lshl_add_u64 v[224:225], s[42:43], 0, v[174:175]
	s_mov_b32 m0, s46
	s_nop 0
	global_load_lds_dwordx4 v[224:225], off
	s_waitcnt vmcnt(8)
	s_waitcnt lgkmcnt(0)
	s_barrier
	s_waitcnt lgkmcnt(0)
	v_mfma_f32_16x16x32_bf16 v[126:129], v[130:133], v[162:165], v[126:129]
	v_mfma_f32_16x16x32_bf16 v[122:125], v[138:141], v[162:165], v[122:125]
	v_mfma_f32_16x16x32_bf16 v[110:113], v[130:133], v[186:189], v[110:113]
	v_mfma_f32_16x16x32_bf16 v[106:109], v[138:141], v[186:189], v[106:109]
	v_mfma_f32_16x16x32_bf16 v[94:97], v[130:133], v[194:197], v[94:97]
	v_mfma_f32_16x16x32_bf16 v[90:93], v[138:141], v[194:197], v[90:93]
	v_mfma_f32_16x16x32_bf16 v[78:81], v[130:133], v[202:205], v[78:81]
	v_mfma_f32_16x16x32_bf16 v[74:77], v[138:141], v[202:205], v[74:77]
	v_mfma_f32_16x16x32_bf16 v[126:129], v[134:137], v[166:169], v[126:129]
	v_mfma_f32_16x16x32_bf16 v[122:125], v[142:145], v[166:169], v[122:125]
	v_mfma_f32_16x16x32_bf16 v[110:113], v[134:137], v[190:193], v[110:113]
	v_mfma_f32_16x16x32_bf16 v[106:109], v[142:145], v[190:193], v[106:109]
	v_mfma_f32_16x16x32_bf16 v[94:97], v[134:137], v[198:201], v[94:97]
	v_mfma_f32_16x16x32_bf16 v[90:93], v[142:145], v[198:201], v[90:93]
	v_mfma_f32_16x16x32_bf16 v[78:81], v[134:137], v[206:209], v[78:81]
	v_mfma_f32_16x16x32_bf16 v[74:77], v[142:145], v[206:209], v[74:77]
	v_mfma_f32_16x16x32_bf16 v[118:121], v[146:149], v[162:165], v[118:121]
	v_mfma_f32_16x16x32_bf16 v[114:117], v[154:157], v[162:165], v[114:117]
	v_mfma_f32_16x16x32_bf16 v[102:105], v[146:149], v[186:189], v[102:105]
	v_mfma_f32_16x16x32_bf16 v[98:101], v[154:157], v[186:189], v[98:101]
	v_mfma_f32_16x16x32_bf16 v[86:89], v[146:149], v[194:197], v[86:89]
	v_mfma_f32_16x16x32_bf16 v[82:85], v[154:157], v[194:197], v[82:85]
	v_mfma_f32_16x16x32_bf16 v[70:73], v[146:149], v[202:205], v[70:73]
	v_mfma_f32_16x16x32_bf16 v[66:69], v[154:157], v[202:205], v[66:69]
	v_mfma_f32_16x16x32_bf16 v[118:121], v[150:153], v[166:169], v[118:121]
	v_mfma_f32_16x16x32_bf16 v[114:117], v[158:161], v[166:169], v[114:117]
	v_mfma_f32_16x16x32_bf16 v[102:105], v[150:153], v[190:193], v[102:105]
	v_mfma_f32_16x16x32_bf16 v[98:101], v[158:161], v[190:193], v[98:101]
	v_mfma_f32_16x16x32_bf16 v[86:89], v[150:153], v[198:201], v[86:89]
	v_mfma_f32_16x16x32_bf16 v[82:85], v[158:161], v[198:201], v[82:85]
	v_mfma_f32_16x16x32_bf16 v[70:73], v[150:153], v[206:209], v[70:73]
	s_setprio 3
	s_barrier
	v_mfma_f32_16x16x32_bf16 v[66:69], v[158:161], v[206:209], v[66:69]
	s_setprio 0
	s_add_i32 s42, s76, s17
	v_lshl_add_u64 v[216:217], v[216:217], 0, s[8:9]
	s_mov_b32 m0, s42
	ds_read_b128 v[162:165], v214 offset:49152
	ds_read_b128 v[166:169], v214 offset:50176
	ds_read_b128 v[186:189], v214 offset:51200
	ds_read_b128 v[190:193], v214 offset:52224
	ds_read_b128 v[194:197], v214 offset:53248
	ds_read_b128 v[198:201], v214 offset:54272
	ds_read_b128 v[202:205], v214 offset:55296
	ds_read_b128 v[206:209], v214 offset:56320
	global_load_lds_dwordx4 v[216:217], off
	s_add_i32 m0, s42, 0x2000
	s_add_u32 s40, s40, 0x100080
	v_lshl_add_u64 v[216:217], v[218:219], 0, s[8:9]
	s_addc_u32 s41, s41, 0
	s_add_i32 s42, s77, s17
	global_load_lds_dwordx4 v[216:217], off
	v_lshl_add_u64 v[216:217], s[40:41], 0, v[172:173]
	s_mov_b32 m0, s42
	s_nop 0
	global_load_lds_dwordx4 v[216:217], off
	v_lshl_add_u64 v[216:217], s[40:41], 0, v[176:177]
	s_add_i32 m0, s42, 0x2000
	s_nop 0
	global_load_lds_dwordx4 v[216:217], off
	v_lshl_add_u64 v[216:217], v[220:221], 0, s[8:9]
	s_mov_b32 m0, s50
	s_nop 0
	global_load_lds_dwordx4 v[216:217], off
	v_lshl_add_u64 v[216:217], v[222:223], 0, s[8:9]
	s_mov_b32 m0, s51
	s_nop 0
	global_load_lds_dwordx4 v[216:217], off
	s_waitcnt vmcnt(8)
	s_waitcnt lgkmcnt(0)
	s_barrier
	s_waitcnt lgkmcnt(0)
	v_mfma_f32_16x16x32_bf16 v[62:65], v[130:133], v[162:165], v[62:65]
	v_mfma_f32_16x16x32_bf16 v[58:61], v[138:141], v[162:165], v[58:61]
	v_mfma_f32_16x16x32_bf16 v[46:49], v[130:133], v[186:189], v[46:49]
	v_mfma_f32_16x16x32_bf16 v[42:45], v[138:141], v[186:189], v[42:45]
	v_mfma_f32_16x16x32_bf16 v[30:33], v[130:133], v[194:197], v[30:33]
	v_mfma_f32_16x16x32_bf16 v[26:29], v[138:141], v[194:197], v[26:29]
	v_mfma_f32_16x16x32_bf16 v[14:17], v[130:133], v[202:205], v[14:17]
	v_mfma_f32_16x16x32_bf16 v[10:13], v[138:141], v[202:205], v[10:13]
	v_mfma_f32_16x16x32_bf16 v[62:65], v[134:137], v[166:169], v[62:65]
	v_mfma_f32_16x16x32_bf16 v[58:61], v[142:145], v[166:169], v[58:61]
	v_mfma_f32_16x16x32_bf16 v[46:49], v[134:137], v[190:193], v[46:49]
	v_mfma_f32_16x16x32_bf16 v[42:45], v[142:145], v[190:193], v[42:45]
	v_mfma_f32_16x16x32_bf16 v[30:33], v[134:137], v[198:201], v[30:33]
	v_mfma_f32_16x16x32_bf16 v[26:29], v[142:145], v[198:201], v[26:29]
	v_mfma_f32_16x16x32_bf16 v[14:17], v[134:137], v[206:209], v[14:17]
	v_mfma_f32_16x16x32_bf16 v[10:13], v[142:145], v[206:209], v[10:13]
	v_mfma_f32_16x16x32_bf16 v[54:57], v[146:149], v[162:165], v[54:57]
	v_mfma_f32_16x16x32_bf16 v[50:53], v[154:157], v[162:165], v[50:53]
	v_mfma_f32_16x16x32_bf16 v[38:41], v[146:149], v[186:189], v[38:41]
	v_mfma_f32_16x16x32_bf16 v[34:37], v[154:157], v[186:189], v[34:37]
	v_mfma_f32_16x16x32_bf16 v[22:25], v[146:149], v[194:197], v[22:25]
	v_mfma_f32_16x16x32_bf16 v[18:21], v[154:157], v[194:197], v[18:21]
	v_mfma_f32_16x16x32_bf16 v[6:9], v[146:149], v[202:205], v[6:9]
	v_mfma_f32_16x16x32_bf16 v[2:5], v[154:157], v[202:205], v[2:5]
	v_mfma_f32_16x16x32_bf16 v[54:57], v[150:153], v[166:169], v[54:57]
	v_mfma_f32_16x16x32_bf16 v[50:53], v[158:161], v[166:169], v[50:53]
	v_mfma_f32_16x16x32_bf16 v[38:41], v[150:153], v[190:193], v[38:41]
	v_mfma_f32_16x16x32_bf16 v[34:37], v[158:161], v[190:193], v[34:37]
	v_mfma_f32_16x16x32_bf16 v[22:25], v[150:153], v[198:201], v[22:25]
	v_mfma_f32_16x16x32_bf16 v[18:21], v[158:161], v[198:201], v[18:21]
	v_mfma_f32_16x16x32_bf16 v[6:9], v[150:153], v[206:209], v[6:9]
	s_setprio 3
	s_barrier
	v_mfma_f32_16x16x32_bf16 v[2:5], v[158:161], v[206:209], v[2:5]
	s_setprio 0
	s_add_i32 s73, s73, 2
	s_add_u32 s38, s38, 0x100
	s_addc_u32 s39, s39, 0
	s_add_u32 s71, s71, 0x100
	s_addc_u32 s72, s72, 0
	s_cmp_gt_u32 s73, 61
	s_cbranch_scc0 .LBB0_1921
	s_and_b64 vcc, exec, s[10:11]
	s_cbranch_vccz .LBB0_1924
	s_barrier

.LBB0_2055:
	s_ashr_i32 s31, s30, 31
	s_lshl_b64 s[18:19], s[30:31], 20
	s_add_u32 s34, s27, s18
	s_addc_u32 s35, s44, s19
	s_and_b64 s[18:19], s[0:1], exec
	s_cselect_b32 s31, s35, s3
	s_cselect_b32 s87, s34, s2
	s_ashr_i32 s29, s28, 31
	s_lshl_b64 s[18:19], s[28:29], 20
	s_add_u32 s36, s45, s18
	s_addc_u32 s37, s46, s19
	s_and_b64 s[18:19], s[0:1], exec
	s_cselect_b32 s29, s37, s5
	s_cselect_b32 s90, s36, s4
	s_add_u32 s91, s4, 0x100
	s_addc_u32 s92, s5, 0
	s_mov_b32 s93, -2
	ds_read_b128 v[130:133], v234
	ds_read_b128 v[134:137], v234 offset:1024
	ds_read_b128 v[162:165], v234 offset:2048
	ds_read_b128 v[166:169], v234 offset:3072
	ds_read_b128 v[170:173], v235
	ds_read_b128 v[174:177], v235 offset:1024
	ds_read_b128 v[178:181], v235 offset:2048
	ds_read_b128 v[182:185], v235 offset:3072
	s_add_u32 s4, s2, 0x100
	s_addc_u32 s5, s3, 0
	s_cmp_eq_u32 s93, 28
	s_cselect_b32 s43, s31, s5
	s_cselect_b32 s42, s87, s4
	s_cselect_b32 s19, s29, s92
	s_cselect_b32 s18, s90, s91
	v_lshl_add_u64 v[218:219], s[2:3], 0, v[154:155]
	s_add_i32 m0, s49, 0xc000
	ds_read_b128 v[186:189], v236
	ds_read_b128 v[190:193], v236 offset:1024
	ds_read_b128 v[194:197], v236 offset:2048
	ds_read_b128 v[198:201], v236 offset:3072
	ds_read_b128 v[202:205], v236 offset:4096
	ds_read_b128 v[206:209], v236 offset:5120
	ds_read_b128 v[210:213], v236 offset:6144
	ds_read_b128 v[214:217], v236 offset:7168
	global_load_lds_dwordx4 v[218:219], off
	v_lshl_add_u64 v[218:219], s[2:3], 0, v[156:157]
	s_add_i32 m0, s49, 0xe000
	s_nop 0
	global_load_lds_dwordx4 v[218:219], off
	s_waitcnt vmcnt(8)
	s_waitcnt lgkmcnt(0)
	s_barrier
	s_waitcnt lgkmcnt(0)
	v_mfma_i32_16x16x64_i8 v[118:121], v[130:133], v[186:189], 0
	v_mfma_i32_16x16x64_i8 v[102:105], v[162:165], v[186:189], 0
	v_mfma_i32_16x16x64_i8 v[114:117], v[130:133], v[194:197], 0
	v_mfma_i32_16x16x64_i8 v[98:101], v[162:165], v[194:197], 0
	v_mfma_i32_16x16x64_i8 v[126:129], v[130:133], v[202:205], 0
	v_mfma_i32_16x16x64_i8 v[110:113], v[162:165], v[202:205], 0
	v_mfma_i32_16x16x64_i8 v[122:125], v[130:133], v[210:213], 0
	v_mfma_i32_16x16x64_i8 v[106:109], v[162:165], v[210:213], 0
	v_mfma_i32_16x16x64_i8 v[118:121], v[134:137], v[190:193], v[118:121]
	v_mfma_i32_16x16x64_i8 v[102:105], v[166:169], v[190:193], v[102:105]
	v_mfma_i32_16x16x64_i8 v[114:117], v[134:137], v[198:201], v[114:117]
	v_mfma_i32_16x16x64_i8 v[98:101], v[166:169], v[198:201], v[98:101]
	v_mfma_i32_16x16x64_i8 v[126:129], v[134:137], v[206:209], v[126:129]
	v_mfma_i32_16x16x64_i8 v[110:113], v[166:169], v[206:209], v[110:113]
	v_mfma_i32_16x16x64_i8 v[122:125], v[134:137], v[214:217], v[122:125]
	v_mfma_i32_16x16x64_i8 v[106:109], v[166:169], v[214:217], v[106:109]
	v_mfma_i32_16x16x64_i8 v[86:89], v[170:173], v[186:189], 0
	v_mfma_i32_16x16x64_i8 v[70:73], v[178:181], v[186:189], 0
	v_mfma_i32_16x16x64_i8 v[82:85], v[170:173], v[194:197], 0
	v_mfma_i32_16x16x64_i8 v[66:69], v[178:181], v[194:197], 0
	v_mfma_i32_16x16x64_i8 v[94:97], v[170:173], v[202:205], 0
	v_mfma_i32_16x16x64_i8 v[78:81], v[178:181], v[202:205], 0
	v_mfma_i32_16x16x64_i8 v[90:93], v[170:173], v[210:213], 0
	v_mfma_i32_16x16x64_i8 v[74:77], v[178:181], v[210:213], 0
	v_mfma_i32_16x16x64_i8 v[86:89], v[174:177], v[190:193], v[86:89]
	v_mfma_i32_16x16x64_i8 v[70:73], v[182:185], v[190:193], v[70:73]
	v_mfma_i32_16x16x64_i8 v[82:85], v[174:177], v[198:201], v[82:85]
	v_mfma_i32_16x16x64_i8 v[66:69], v[182:185], v[198:201], v[66:69]
	v_mfma_i32_16x16x64_i8 v[94:97], v[174:177], v[206:209], v[94:97]
	v_mfma_i32_16x16x64_i8 v[78:81], v[182:185], v[206:209], v[78:81]
	v_mfma_i32_16x16x64_i8 v[90:93], v[174:177], v[214:217], v[90:93]
	s_setprio 3
	s_barrier
	v_mfma_i32_16x16x64_i8 v[74:77], v[182:185], v[214:217], v[74:77]
	s_setprio 0
	s_add_i32 s2, s82, s47
	v_lshl_add_u64 v[218:219], s[18:19], 0, v[144:145]
	s_mov_b32 m0, s2
	ds_read_b128 v[186:189], v236 offset:16384
	ds_read_b128 v[190:193], v236 offset:17408
	ds_read_b128 v[194:197], v236 offset:18432
	ds_read_b128 v[198:201], v236 offset:19456
	ds_read_b128 v[202:205], v236 offset:20480
	ds_read_b128 v[206:209], v236 offset:21504
	ds_read_b128 v[210:213], v236 offset:22528
	ds_read_b128 v[214:217], v236 offset:23552
	global_load_lds_dwordx4 v[218:219], off
	s_add_i32 m0, s2, 0x2000
	s_add_u32 s2, s18, 0x80000
	v_lshl_add_u64 v[220:221], s[18:19], 0, v[148:149]
	s_addc_u32 s3, s19, 0
	s_add_i32 s94, s16, s47
	global_load_lds_dwordx4 v[220:221], off
	v_lshl_add_u64 v[222:223], s[2:3], 0, v[144:145]
	s_mov_b32 m0, s94
	v_lshl_add_u64 v[224:225], s[42:43], 0, v[146:147]
	global_load_lds_dwordx4 v[222:223], off
	v_lshl_add_u64 v[222:223], s[2:3], 0, v[148:149]
	s_add_i32 m0, s94, 0x2000
	s_nop 0
	global_load_lds_dwordx4 v[222:223], off
	v_lshl_add_u64 v[222:223], s[42:43], 0, v[142:143]
	s_mov_b32 m0, s49
	s_nop 0
	global_load_lds_dwordx4 v[222:223], off
	s_mov_b32 m0, s50
	s_nop 0
	global_load_lds_dwordx4 v[224:225], off
	s_waitcnt vmcnt(8)
	s_waitcnt lgkmcnt(0)
	s_barrier
	s_waitcnt lgkmcnt(0)
	v_mfma_i32_16x16x64_i8 v[54:57], v[130:133], v[186:189], 0
	v_mfma_i32_16x16x64_i8 v[18:21], v[162:165], v[186:189], 0
	v_mfma_i32_16x16x64_i8 v[50:53], v[130:133], v[194:197], 0
	v_mfma_i32_16x16x64_i8 v[22:25], v[162:165], v[194:197], 0
	v_mfma_i32_16x16x64_i8 v[62:65], v[130:133], v[202:205], 0
	v_mfma_i32_16x16x64_i8 v[30:33], v[162:165], v[202:205], 0
	v_mfma_i32_16x16x64_i8 v[58:61], v[130:133], v[210:213], 0
	v_mfma_i32_16x16x64_i8 v[26:29], v[162:165], v[210:213], 0
	v_mfma_i32_16x16x64_i8 v[54:57], v[134:137], v[190:193], v[54:57]
	v_mfma_i32_16x16x64_i8 v[18:21], v[166:169], v[190:193], v[18:21]
	v_mfma_i32_16x16x64_i8 v[50:53], v[134:137], v[198:201], v[50:53]
	v_mfma_i32_16x16x64_i8 v[22:25], v[166:169], v[198:201], v[22:25]
	v_mfma_i32_16x16x64_i8 v[62:65], v[134:137], v[206:209], v[62:65]
	v_mfma_i32_16x16x64_i8 v[30:33], v[166:169], v[206:209], v[30:33]
	v_mfma_i32_16x16x64_i8 v[58:61], v[134:137], v[214:217], v[58:61]
	v_mfma_i32_16x16x64_i8 v[26:29], v[166:169], v[214:217], v[26:29]
	v_mfma_i32_16x16x64_i8 v[46:49], v[170:173], v[186:189], 0
	v_mfma_i32_16x16x64_i8 v[14:17], v[178:181], v[186:189], 0
	v_mfma_i32_16x16x64_i8 v[42:45], v[170:173], v[194:197], 0
	v_mfma_i32_16x16x64_i8 v[10:13], v[178:181], v[194:197], 0
	v_mfma_i32_16x16x64_i8 v[38:41], v[170:173], v[202:205], 0
	v_mfma_i32_16x16x64_i8 v[6:9], v[178:181], v[202:205], 0
	v_mfma_i32_16x16x64_i8 v[34:37], v[170:173], v[210:213], 0
	v_mfma_i32_16x16x64_i8 v[2:5], v[178:181], v[210:213], 0
	v_mfma_i32_16x16x64_i8 v[46:49], v[174:177], v[190:193], v[46:49]
	v_mfma_i32_16x16x64_i8 v[14:17], v[182:185], v[190:193], v[14:17]
	v_mfma_i32_16x16x64_i8 v[42:45], v[174:177], v[198:201], v[42:45]
	v_mfma_i32_16x16x64_i8 v[10:13], v[182:185], v[198:201], v[10:13]
	v_mfma_i32_16x16x64_i8 v[38:41], v[174:177], v[206:209], v[38:41]
	v_mfma_i32_16x16x64_i8 v[6:9], v[182:185], v[206:209], v[6:9]
	v_mfma_i32_16x16x64_i8 v[34:37], v[174:177], v[214:217], v[34:37]
	s_setprio 3
	s_barrier
	v_mfma_i32_16x16x64_i8 v[2:5], v[182:185], v[214:217], v[2:5]
	s_setprio 0
	s_add_i32 s94, 0, 0x18000
	s_add_i32 s95, 0, 0x1c000
	v_add_u32_e32 v166, s94, v232
	v_add_u32_e32 v182, s95, v232
	ds_read_b128 v[130:133], v166
	ds_read_b128 v[134:137], v166 offset:1024
	ds_read_b128 v[162:165], v166 offset:2048
	ds_read_b128 v[166:169], v166 offset:3072
	ds_read_b128 v[170:173], v182
	ds_read_b128 v[174:177], v182 offset:1024
	ds_read_b128 v[178:181], v182 offset:2048
	ds_read_b128 v[182:185], v182 offset:3072
	s_add_u32 s2, s42, 0x80000
	s_addc_u32 s3, s43, 0
	s_mov_b32 m0, s51
	v_lshl_add_u64 v[226:227], s[2:3], 0, v[142:143]
	ds_read_b128 v[186:189], v236 offset:32768
	ds_read_b128 v[190:193], v236 offset:33792
	ds_read_b128 v[194:197], v236 offset:34816
	ds_read_b128 v[198:201], v236 offset:35840
	ds_read_b128 v[202:205], v236 offset:36864
	ds_read_b128 v[206:209], v236 offset:37888
	ds_read_b128 v[210:213], v236 offset:38912
	ds_read_b128 v[214:217], v236 offset:39936
	global_load_lds_dwordx4 v[226:227], off
	v_lshl_add_u64 v[226:227], s[2:3], 0, v[146:147]
	s_mov_b32 m0, s54
	s_nop 0
	global_load_lds_dwordx4 v[226:227], off
	s_waitcnt vmcnt(8)
	s_waitcnt lgkmcnt(0)
	s_barrier
	s_waitcnt lgkmcnt(0)
	v_mfma_i32_16x16x64_i8 v[118:121], v[130:133], v[186:189], v[118:121]
	v_mfma_i32_16x16x64_i8 v[102:105], v[162:165], v[186:189], v[102:105]
	v_mfma_i32_16x16x64_i8 v[114:117], v[130:133], v[194:197], v[114:117]
	v_mfma_i32_16x16x64_i8 v[98:101], v[162:165], v[194:197], v[98:101]
	v_mfma_i32_16x16x64_i8 v[126:129], v[130:133], v[202:205], v[126:129]
	v_mfma_i32_16x16x64_i8 v[110:113], v[162:165], v[202:205], v[110:113]
	v_mfma_i32_16x16x64_i8 v[122:125], v[130:133], v[210:213], v[122:125]
	v_mfma_i32_16x16x64_i8 v[106:109], v[162:165], v[210:213], v[106:109]
	v_mfma_i32_16x16x64_i8 v[118:121], v[134:137], v[190:193], v[118:121]
	v_mfma_i32_16x16x64_i8 v[102:105], v[166:169], v[190:193], v[102:105]
	v_mfma_i32_16x16x64_i8 v[114:117], v[134:137], v[198:201], v[114:117]
	v_mfma_i32_16x16x64_i8 v[98:101], v[166:169], v[198:201], v[98:101]
	v_mfma_i32_16x16x64_i8 v[126:129], v[134:137], v[206:209], v[126:129]
	v_mfma_i32_16x16x64_i8 v[110:113], v[166:169], v[206:209], v[110:113]
	v_mfma_i32_16x16x64_i8 v[122:125], v[134:137], v[214:217], v[122:125]
	v_mfma_i32_16x16x64_i8 v[106:109], v[166:169], v[214:217], v[106:109]
	v_mfma_i32_16x16x64_i8 v[86:89], v[170:173], v[186:189], v[86:89]
	v_mfma_i32_16x16x64_i8 v[70:73], v[178:181], v[186:189], v[70:73]
	v_mfma_i32_16x16x64_i8 v[82:85], v[170:173], v[194:197], v[82:85]
	v_mfma_i32_16x16x64_i8 v[66:69], v[178:181], v[194:197], v[66:69]
	v_mfma_i32_16x16x64_i8 v[94:97], v[170:173], v[202:205], v[94:97]
	v_mfma_i32_16x16x64_i8 v[78:81], v[178:181], v[202:205], v[78:81]
	v_mfma_i32_16x16x64_i8 v[90:93], v[170:173], v[210:213], v[90:93]
	v_mfma_i32_16x16x64_i8 v[74:77], v[178:181], v[210:213], v[74:77]
	v_mfma_i32_16x16x64_i8 v[86:89], v[174:177], v[190:193], v[86:89]
	v_mfma_i32_16x16x64_i8 v[70:73], v[182:185], v[190:193], v[70:73]
	v_mfma_i32_16x16x64_i8 v[82:85], v[174:177], v[198:201], v[82:85]
	v_mfma_i32_16x16x64_i8 v[66:69], v[182:185], v[198:201], v[66:69]
	v_mfma_i32_16x16x64_i8 v[94:97], v[174:177], v[206:209], v[94:97]
	v_mfma_i32_16x16x64_i8 v[78:81], v[182:185], v[206:209], v[78:81]
	v_mfma_i32_16x16x64_i8 v[90:93], v[174:177], v[214:217], v[90:93]
	s_setprio 3
	s_barrier
	v_mfma_i32_16x16x64_i8 v[74:77], v[182:185], v[214:217], v[74:77]
	s_setprio 0
	s_add_i32 s2, s94, s47
	v_lshl_add_u64 v[218:219], v[218:219], 0, s[14:15]
	s_mov_b32 m0, s2
	ds_read_b128 v[186:189], v236 offset:49152
	ds_read_b128 v[190:193], v236 offset:50176
	ds_read_b128 v[194:197], v236 offset:51200
	ds_read_b128 v[198:201], v236 offset:52224
	ds_read_b128 v[202:205], v236 offset:53248
	ds_read_b128 v[206:209], v236 offset:54272
	ds_read_b128 v[210:213], v236 offset:55296
	ds_read_b128 v[214:217], v236 offset:56320
	global_load_lds_dwordx4 v[218:219], off
	s_add_i32 m0, s2, 0x2000
	s_add_u32 s2, s18, 0x80080
	v_lshl_add_u64 v[218:219], v[220:221], 0, s[14:15]
	s_addc_u32 s3, s19, 0
	s_add_i32 s18, s95, s47
	global_load_lds_dwordx4 v[218:219], off
	v_lshl_add_u64 v[218:219], s[2:3], 0, v[144:145]
	s_mov_b32 m0, s18
	s_nop 0
	global_load_lds_dwordx4 v[218:219], off
	v_lshl_add_u64 v[218:219], s[2:3], 0, v[148:149]
	s_add_i32 m0, s18, 0x2000
	s_nop 0
	global_load_lds_dwordx4 v[218:219], off
	v_lshl_add_u64 v[218:219], v[222:223], 0, s[14:15]
	s_mov_b32 m0, s63
	s_nop 0
	global_load_lds_dwordx4 v[218:219], off
	v_lshl_add_u64 v[218:219], v[224:225], 0, s[14:15]
	s_mov_b32 m0, s64
	s_nop 0
	global_load_lds_dwordx4 v[218:219], off
	s_waitcnt vmcnt(8)
	s_waitcnt lgkmcnt(0)
	s_barrier
	s_waitcnt lgkmcnt(0)
	v_mfma_i32_16x16x64_i8 v[54:57], v[130:133], v[186:189], v[54:57]
	v_mfma_i32_16x16x64_i8 v[18:21], v[162:165], v[186:189], v[18:21]
	v_mfma_i32_16x16x64_i8 v[50:53], v[130:133], v[194:197], v[50:53]
	v_mfma_i32_16x16x64_i8 v[22:25], v[162:165], v[194:197], v[22:25]
	v_mfma_i32_16x16x64_i8 v[62:65], v[130:133], v[202:205], v[62:65]
	v_mfma_i32_16x16x64_i8 v[30:33], v[162:165], v[202:205], v[30:33]
	v_mfma_i32_16x16x64_i8 v[58:61], v[130:133], v[210:213], v[58:61]
	v_mfma_i32_16x16x64_i8 v[26:29], v[162:165], v[210:213], v[26:29]
	v_mfma_i32_16x16x64_i8 v[54:57], v[134:137], v[190:193], v[54:57]
	v_mfma_i32_16x16x64_i8 v[18:21], v[166:169], v[190:193], v[18:21]
	v_mfma_i32_16x16x64_i8 v[50:53], v[134:137], v[198:201], v[50:53]
	v_mfma_i32_16x16x64_i8 v[22:25], v[166:169], v[198:201], v[22:25]
	v_mfma_i32_16x16x64_i8 v[62:65], v[134:137], v[206:209], v[62:65]
	v_mfma_i32_16x16x64_i8 v[30:33], v[166:169], v[206:209], v[30:33]
	v_mfma_i32_16x16x64_i8 v[58:61], v[134:137], v[214:217], v[58:61]
	v_mfma_i32_16x16x64_i8 v[26:29], v[166:169], v[214:217], v[26:29]
	v_mfma_i32_16x16x64_i8 v[46:49], v[170:173], v[186:189], v[46:49]
	v_mfma_i32_16x16x64_i8 v[14:17], v[178:181], v[186:189], v[14:17]
	v_mfma_i32_16x16x64_i8 v[42:45], v[170:173], v[194:197], v[42:45]
	v_mfma_i32_16x16x64_i8 v[10:13], v[178:181], v[194:197], v[10:13]
	v_mfma_i32_16x16x64_i8 v[38:41], v[170:173], v[202:205], v[38:41]
	v_mfma_i32_16x16x64_i8 v[6:9], v[178:181], v[202:205], v[6:9]
	v_mfma_i32_16x16x64_i8 v[34:37], v[170:173], v[210:213], v[34:37]
	v_mfma_i32_16x16x64_i8 v[2:5], v[178:181], v[210:213], v[2:5]
	v_mfma_i32_16x16x64_i8 v[46:49], v[174:177], v[190:193], v[46:49]
	v_mfma_i32_16x16x64_i8 v[14:17], v[182:185], v[190:193], v[14:17]
	v_mfma_i32_16x16x64_i8 v[42:45], v[174:177], v[198:201], v[42:45]
	v_mfma_i32_16x16x64_i8 v[10:13], v[182:185], v[198:201], v[10:13]
	v_mfma_i32_16x16x64_i8 v[38:41], v[174:177], v[206:209], v[38:41]
	v_mfma_i32_16x16x64_i8 v[6:9], v[182:185], v[206:209], v[6:9]
	v_mfma_i32_16x16x64_i8 v[34:37], v[174:177], v[214:217], v[34:37]
	s_setprio 3
	s_barrier
	v_mfma_i32_16x16x64_i8 v[2:5], v[182:185], v[214:217], v[2:5]
	s_setprio 0
	s_add_i32 s93, s93, 2
	s_add_u32 s91, s91, 0x100
	s_addc_u32 s92, s92, 0
	s_cmp_gt_u32 s93, 29
	s_mov_b64 s[2:3], s[4:5]
.LBB0_2056:
	ds_read_b128 v[130:133], v234
	ds_read_b128 v[134:137], v234 offset:1024
	ds_read_b128 v[162:165], v234 offset:2048
	ds_read_b128 v[166:169], v234 offset:3072
	ds_read_b128 v[170:173], v235
	ds_read_b128 v[174:177], v235 offset:1024
	ds_read_b128 v[178:181], v235 offset:2048
	ds_read_b128 v[182:185], v235 offset:3072
	s_add_u32 s4, s2, 0x100
	s_addc_u32 s5, s3, 0
	s_cmp_eq_u32 s93, 28
	s_cselect_b32 s43, s31, s5
	s_cselect_b32 s42, s87, s4
	s_cselect_b32 s19, s29, s92
	s_cselect_b32 s18, s90, s91
	v_lshl_add_u64 v[218:219], s[2:3], 0, v[154:155]
	s_add_i32 m0, s49, 0xc000
	ds_read_b128 v[186:189], v236
	ds_read_b128 v[190:193], v236 offset:1024
	ds_read_b128 v[194:197], v236 offset:2048
	ds_read_b128 v[198:201], v236 offset:3072
	ds_read_b128 v[202:205], v236 offset:4096
	ds_read_b128 v[206:209], v236 offset:5120
	ds_read_b128 v[210:213], v236 offset:6144
	ds_read_b128 v[214:217], v236 offset:7168
	global_load_lds_dwordx4 v[218:219], off
	v_lshl_add_u64 v[218:219], s[2:3], 0, v[156:157]
	s_add_i32 m0, s49, 0xe000
	s_nop 0
	global_load_lds_dwordx4 v[218:219], off
	s_waitcnt vmcnt(8)
	s_waitcnt lgkmcnt(0)
	s_barrier
	s_waitcnt lgkmcnt(0)
	v_mfma_i32_16x16x64_i8 v[118:121], v[130:133], v[186:189], v[118:121]
	v_mfma_i32_16x16x64_i8 v[102:105], v[162:165], v[186:189], v[102:105]
	v_mfma_i32_16x16x64_i8 v[114:117], v[130:133], v[194:197], v[114:117]
	v_mfma_i32_16x16x64_i8 v[98:101], v[162:165], v[194:197], v[98:101]
	v_mfma_i32_16x16x64_i8 v[126:129], v[130:133], v[202:205], v[126:129]
	v_mfma_i32_16x16x64_i8 v[110:113], v[162:165], v[202:205], v[110:113]
	v_mfma_i32_16x16x64_i8 v[122:125], v[130:133], v[210:213], v[122:125]
	v_mfma_i32_16x16x64_i8 v[106:109], v[162:165], v[210:213], v[106:109]
	v_mfma_i32_16x16x64_i8 v[118:121], v[134:137], v[190:193], v[118:121]
	v_mfma_i32_16x16x64_i8 v[102:105], v[166:169], v[190:193], v[102:105]
	v_mfma_i32_16x16x64_i8 v[114:117], v[134:137], v[198:201], v[114:117]
	v_mfma_i32_16x16x64_i8 v[98:101], v[166:169], v[198:201], v[98:101]
	v_mfma_i32_16x16x64_i8 v[126:129], v[134:137], v[206:209], v[126:129]
	v_mfma_i32_16x16x64_i8 v[110:113], v[166:169], v[206:209], v[110:113]
	v_mfma_i32_16x16x64_i8 v[122:125], v[134:137], v[214:217], v[122:125]
	v_mfma_i32_16x16x64_i8 v[106:109], v[166:169], v[214:217], v[106:109]
	v_mfma_i32_16x16x64_i8 v[86:89], v[170:173], v[186:189], v[86:89]
	v_mfma_i32_16x16x64_i8 v[70:73], v[178:181], v[186:189], v[70:73]
	v_mfma_i32_16x16x64_i8 v[82:85], v[170:173], v[194:197], v[82:85]
	v_mfma_i32_16x16x64_i8 v[66:69], v[178:181], v[194:197], v[66:69]
	v_mfma_i32_16x16x64_i8 v[94:97], v[170:173], v[202:205], v[94:97]
	v_mfma_i32_16x16x64_i8 v[78:81], v[178:181], v[202:205], v[78:81]
	v_mfma_i32_16x16x64_i8 v[90:93], v[170:173], v[210:213], v[90:93]
	v_mfma_i32_16x16x64_i8 v[74:77], v[178:181], v[210:213], v[74:77]
	v_mfma_i32_16x16x64_i8 v[86:89], v[174:177], v[190:193], v[86:89]
	v_mfma_i32_16x16x64_i8 v[70:73], v[182:185], v[190:193], v[70:73]
	v_mfma_i32_16x16x64_i8 v[82:85], v[174:177], v[198:201], v[82:85]
	v_mfma_i32_16x16x64_i8 v[66:69], v[182:185], v[198:201], v[66:69]
	v_mfma_i32_16x16x64_i8 v[94:97], v[174:177], v[206:209], v[94:97]
	v_mfma_i32_16x16x64_i8 v[78:81], v[182:185], v[206:209], v[78:81]
	v_mfma_i32_16x16x64_i8 v[90:93], v[174:177], v[214:217], v[90:93]
	s_setprio 3
	s_barrier
	v_mfma_i32_16x16x64_i8 v[74:77], v[182:185], v[214:217], v[74:77]
	s_setprio 0
	s_add_i32 s2, s82, s47
	v_lshl_add_u64 v[218:219], s[18:19], 0, v[144:145]
	s_mov_b32 m0, s2
	ds_read_b128 v[186:189], v236 offset:16384
	ds_read_b128 v[190:193], v236 offset:17408
	ds_read_b128 v[194:197], v236 offset:18432
	ds_read_b128 v[198:201], v236 offset:19456
	ds_read_b128 v[202:205], v236 offset:20480
	ds_read_b128 v[206:209], v236 offset:21504
	ds_read_b128 v[210:213], v236 offset:22528
	ds_read_b128 v[214:217], v236 offset:23552
	global_load_lds_dwordx4 v[218:219], off
	s_add_i32 m0, s2, 0x2000
	s_add_u32 s2, s18, 0x80000
	v_lshl_add_u64 v[220:221], s[18:19], 0, v[148:149]
	s_addc_u32 s3, s19, 0
	s_add_i32 s94, s16, s47
	global_load_lds_dwordx4 v[220:221], off
	v_lshl_add_u64 v[222:223], s[2:3], 0, v[144:145]
	s_mov_b32 m0, s94
	v_lshl_add_u64 v[224:225], s[42:43], 0, v[146:147]
	global_load_lds_dwordx4 v[222:223], off
	v_lshl_add_u64 v[222:223], s[2:3], 0, v[148:149]
	s_add_i32 m0, s94, 0x2000
	s_nop 0
	global_load_lds_dwordx4 v[222:223], off
	v_lshl_add_u64 v[222:223], s[42:43], 0, v[142:143]
	s_mov_b32 m0, s49
	s_nop 0
	global_load_lds_dwordx4 v[222:223], off
	s_mov_b32 m0, s50
	s_nop 0
	global_load_lds_dwordx4 v[224:225], off
	s_waitcnt vmcnt(8)
	s_waitcnt lgkmcnt(0)
	s_barrier
	s_waitcnt lgkmcnt(0)
	v_mfma_i32_16x16x64_i8 v[54:57], v[130:133], v[186:189], v[54:57]
	v_mfma_i32_16x16x64_i8 v[18:21], v[162:165], v[186:189], v[18:21]
	v_mfma_i32_16x16x64_i8 v[50:53], v[130:133], v[194:197], v[50:53]
	v_mfma_i32_16x16x64_i8 v[22:25], v[162:165], v[194:197], v[22:25]
	v_mfma_i32_16x16x64_i8 v[62:65], v[130:133], v[202:205], v[62:65]
	v_mfma_i32_16x16x64_i8 v[30:33], v[162:165], v[202:205], v[30:33]
	v_mfma_i32_16x16x64_i8 v[58:61], v[130:133], v[210:213], v[58:61]
	v_mfma_i32_16x16x64_i8 v[26:29], v[162:165], v[210:213], v[26:29]
	v_mfma_i32_16x16x64_i8 v[54:57], v[134:137], v[190:193], v[54:57]
	v_mfma_i32_16x16x64_i8 v[18:21], v[166:169], v[190:193], v[18:21]
	v_mfma_i32_16x16x64_i8 v[50:53], v[134:137], v[198:201], v[50:53]
	v_mfma_i32_16x16x64_i8 v[22:25], v[166:169], v[198:201], v[22:25]
	v_mfma_i32_16x16x64_i8 v[62:65], v[134:137], v[206:209], v[62:65]
	v_mfma_i32_16x16x64_i8 v[30:33], v[166:169], v[206:209], v[30:33]
	v_mfma_i32_16x16x64_i8 v[58:61], v[134:137], v[214:217], v[58:61]
	v_mfma_i32_16x16x64_i8 v[26:29], v[166:169], v[214:217], v[26:29]
	v_mfma_i32_16x16x64_i8 v[46:49], v[170:173], v[186:189], v[46:49]
	v_mfma_i32_16x16x64_i8 v[14:17], v[178:181], v[186:189], v[14:17]
	v_mfma_i32_16x16x64_i8 v[42:45], v[170:173], v[194:197], v[42:45]
	v_mfma_i32_16x16x64_i8 v[10:13], v[178:181], v[194:197], v[10:13]
	v_mfma_i32_16x16x64_i8 v[38:41], v[170:173], v[202:205], v[38:41]
	v_mfma_i32_16x16x64_i8 v[6:9], v[178:181], v[202:205], v[6:9]
	v_mfma_i32_16x16x64_i8 v[34:37], v[170:173], v[210:213], v[34:37]
	v_mfma_i32_16x16x64_i8 v[2:5], v[178:181], v[210:213], v[2:5]
	v_mfma_i32_16x16x64_i8 v[46:49], v[174:177], v[190:193], v[46:49]
	v_mfma_i32_16x16x64_i8 v[14:17], v[182:185], v[190:193], v[14:17]
	v_mfma_i32_16x16x64_i8 v[42:45], v[174:177], v[198:201], v[42:45]
	v_mfma_i32_16x16x64_i8 v[10:13], v[182:185], v[198:201], v[10:13]
	v_mfma_i32_16x16x64_i8 v[38:41], v[174:177], v[206:209], v[38:41]
	v_mfma_i32_16x16x64_i8 v[6:9], v[182:185], v[206:209], v[6:9]
	v_mfma_i32_16x16x64_i8 v[34:37], v[174:177], v[214:217], v[34:37]
	s_setprio 3
	s_barrier
	v_mfma_i32_16x16x64_i8 v[2:5], v[182:185], v[214:217], v[2:5]
	s_setprio 0
	s_add_i32 s94, 0, 0x18000
	s_add_i32 s95, 0, 0x1c000
	v_add_u32_e32 v166, s94, v232
	v_add_u32_e32 v182, s95, v232
	ds_read_b128 v[130:133], v166
	ds_read_b128 v[134:137], v166 offset:1024
	ds_read_b128 v[162:165], v166 offset:2048
	ds_read_b128 v[166:169], v166 offset:3072
	ds_read_b128 v[170:173], v182
	ds_read_b128 v[174:177], v182 offset:1024
	ds_read_b128 v[178:181], v182 offset:2048
	ds_read_b128 v[182:185], v182 offset:3072
	s_add_u32 s2, s42, 0x80000
	s_addc_u32 s3, s43, 0
	s_mov_b32 m0, s51
	v_lshl_add_u64 v[226:227], s[2:3], 0, v[142:143]
	ds_read_b128 v[186:189], v236 offset:32768
	ds_read_b128 v[190:193], v236 offset:33792
	ds_read_b128 v[194:197], v236 offset:34816
	ds_read_b128 v[198:201], v236 offset:35840
	ds_read_b128 v[202:205], v236 offset:36864
	ds_read_b128 v[206:209], v236 offset:37888
	ds_read_b128 v[210:213], v236 offset:38912
	ds_read_b128 v[214:217], v236 offset:39936
	global_load_lds_dwordx4 v[226:227], off
	v_lshl_add_u64 v[226:227], s[2:3], 0, v[146:147]
	s_mov_b32 m0, s54
	s_nop 0
	global_load_lds_dwordx4 v[226:227], off
	s_waitcnt vmcnt(8)
	s_waitcnt lgkmcnt(0)
	s_barrier
	s_waitcnt lgkmcnt(0)
	v_mfma_i32_16x16x64_i8 v[118:121], v[130:133], v[186:189], v[118:121]
	v_mfma_i32_16x16x64_i8 v[102:105], v[162:165], v[186:189], v[102:105]
	v_mfma_i32_16x16x64_i8 v[114:117], v[130:133], v[194:197], v[114:117]
	v_mfma_i32_16x16x64_i8 v[98:101], v[162:165], v[194:197], v[98:101]
	v_mfma_i32_16x16x64_i8 v[126:129], v[130:133], v[202:205], v[126:129]
	v_mfma_i32_16x16x64_i8 v[110:113], v[162:165], v[202:205], v[110:113]
	v_mfma_i32_16x16x64_i8 v[122:125], v[130:133], v[210:213], v[122:125]
	v_mfma_i32_16x16x64_i8 v[106:109], v[162:165], v[210:213], v[106:109]
	v_mfma_i32_16x16x64_i8 v[118:121], v[134:137], v[190:193], v[118:121]
	v_mfma_i32_16x16x64_i8 v[102:105], v[166:169], v[190:193], v[102:105]
	v_mfma_i32_16x16x64_i8 v[114:117], v[134:137], v[198:201], v[114:117]
	v_mfma_i32_16x16x64_i8 v[98:101], v[166:169], v[198:201], v[98:101]
	v_mfma_i32_16x16x64_i8 v[126:129], v[134:137], v[206:209], v[126:129]
	v_mfma_i32_16x16x64_i8 v[110:113], v[166:169], v[206:209], v[110:113]
	v_mfma_i32_16x16x64_i8 v[122:125], v[134:137], v[214:217], v[122:125]
	v_mfma_i32_16x16x64_i8 v[106:109], v[166:169], v[214:217], v[106:109]
	v_mfma_i32_16x16x64_i8 v[86:89], v[170:173], v[186:189], v[86:89]
	v_mfma_i32_16x16x64_i8 v[70:73], v[178:181], v[186:189], v[70:73]
	v_mfma_i32_16x16x64_i8 v[82:85], v[170:173], v[194:197], v[82:85]
	v_mfma_i32_16x16x64_i8 v[66:69], v[178:181], v[194:197], v[66:69]
	v_mfma_i32_16x16x64_i8 v[94:97], v[170:173], v[202:205], v[94:97]
	v_mfma_i32_16x16x64_i8 v[78:81], v[178:181], v[202:205], v[78:81]
	v_mfma_i32_16x16x64_i8 v[90:93], v[170:173], v[210:213], v[90:93]
	v_mfma_i32_16x16x64_i8 v[74:77], v[178:181], v[210:213], v[74:77]
	v_mfma_i32_16x16x64_i8 v[86:89], v[174:177], v[190:193], v[86:89]
	v_mfma_i32_16x16x64_i8 v[70:73], v[182:185], v[190:193], v[70:73]
	v_mfma_i32_16x16x64_i8 v[82:85], v[174:177], v[198:201], v[82:85]
	v_mfma_i32_16x16x64_i8 v[66:69], v[182:185], v[198:201], v[66:69]
	v_mfma_i32_16x16x64_i8 v[94:97], v[174:177], v[206:209], v[94:97]
	v_mfma_i32_16x16x64_i8 v[78:81], v[182:185], v[206:209], v[78:81]
	v_mfma_i32_16x16x64_i8 v[90:93], v[174:177], v[214:217], v[90:93]
	s_setprio 3
	s_barrier
	v_mfma_i32_16x16x64_i8 v[74:77], v[182:185], v[214:217], v[74:77]
	s_setprio 0
	s_add_i32 s2, s94, s47
	v_lshl_add_u64 v[218:219], v[218:219], 0, s[14:15]
	s_mov_b32 m0, s2
	ds_read_b128 v[186:189], v236 offset:49152
	ds_read_b128 v[190:193], v236 offset:50176
	ds_read_b128 v[194:197], v236 offset:51200
	ds_read_b128 v[198:201], v236 offset:52224
	ds_read_b128 v[202:205], v236 offset:53248
	ds_read_b128 v[206:209], v236 offset:54272
	ds_read_b128 v[210:213], v236 offset:55296
	ds_read_b128 v[214:217], v236 offset:56320
	global_load_lds_dwordx4 v[218:219], off
	s_add_i32 m0, s2, 0x2000
	s_add_u32 s2, s18, 0x80080
	v_lshl_add_u64 v[218:219], v[220:221], 0, s[14:15]
	s_addc_u32 s3, s19, 0
	s_add_i32 s18, s95, s47
	global_load_lds_dwordx4 v[218:219], off
	v_lshl_add_u64 v[218:219], s[2:3], 0, v[144:145]
	s_mov_b32 m0, s18
	s_nop 0
	global_load_lds_dwordx4 v[218:219], off
	v_lshl_add_u64 v[218:219], s[2:3], 0, v[148:149]
	s_add_i32 m0, s18, 0x2000
	s_nop 0
	global_load_lds_dwordx4 v[218:219], off
	v_lshl_add_u64 v[218:219], v[222:223], 0, s[14:15]
	s_mov_b32 m0, s63
	s_nop 0
	global_load_lds_dwordx4 v[218:219], off
	v_lshl_add_u64 v[218:219], v[224:225], 0, s[14:15]
	s_mov_b32 m0, s64
	s_nop 0
	global_load_lds_dwordx4 v[218:219], off
	s_waitcnt vmcnt(8)
	s_waitcnt lgkmcnt(0)
	s_barrier
	s_waitcnt lgkmcnt(0)
	v_mfma_i32_16x16x64_i8 v[54:57], v[130:133], v[186:189], v[54:57]
	v_mfma_i32_16x16x64_i8 v[18:21], v[162:165], v[186:189], v[18:21]
	v_mfma_i32_16x16x64_i8 v[50:53], v[130:133], v[194:197], v[50:53]
	v_mfma_i32_16x16x64_i8 v[22:25], v[162:165], v[194:197], v[22:25]
	v_mfma_i32_16x16x64_i8 v[62:65], v[130:133], v[202:205], v[62:65]
	v_mfma_i32_16x16x64_i8 v[30:33], v[162:165], v[202:205], v[30:33]
	v_mfma_i32_16x16x64_i8 v[58:61], v[130:133], v[210:213], v[58:61]
	v_mfma_i32_16x16x64_i8 v[26:29], v[162:165], v[210:213], v[26:29]
	v_mfma_i32_16x16x64_i8 v[54:57], v[134:137], v[190:193], v[54:57]
	v_mfma_i32_16x16x64_i8 v[18:21], v[166:169], v[190:193], v[18:21]
	v_mfma_i32_16x16x64_i8 v[50:53], v[134:137], v[198:201], v[50:53]
	v_mfma_i32_16x16x64_i8 v[22:25], v[166:169], v[198:201], v[22:25]
	v_mfma_i32_16x16x64_i8 v[62:65], v[134:137], v[206:209], v[62:65]
	v_mfma_i32_16x16x64_i8 v[30:33], v[166:169], v[206:209], v[30:33]
	v_mfma_i32_16x16x64_i8 v[58:61], v[134:137], v[214:217], v[58:61]
	v_mfma_i32_16x16x64_i8 v[26:29], v[166:169], v[214:217], v[26:29]
	v_mfma_i32_16x16x64_i8 v[46:49], v[170:173], v[186:189], v[46:49]
	v_mfma_i32_16x16x64_i8 v[14:17], v[178:181], v[186:189], v[14:17]
	v_mfma_i32_16x16x64_i8 v[42:45], v[170:173], v[194:197], v[42:45]
	v_mfma_i32_16x16x64_i8 v[10:13], v[178:181], v[194:197], v[10:13]
	v_mfma_i32_16x16x64_i8 v[38:41], v[170:173], v[202:205], v[38:41]
	v_mfma_i32_16x16x64_i8 v[6:9], v[178:181], v[202:205], v[6:9]
	v_mfma_i32_16x16x64_i8 v[34:37], v[170:173], v[210:213], v[34:37]
	v_mfma_i32_16x16x64_i8 v[2:5], v[178:181], v[210:213], v[2:5]
	v_mfma_i32_16x16x64_i8 v[46:49], v[174:177], v[190:193], v[46:49]
	v_mfma_i32_16x16x64_i8 v[14:17], v[182:185], v[190:193], v[14:17]
	v_mfma_i32_16x16x64_i8 v[42:45], v[174:177], v[198:201], v[42:45]
	v_mfma_i32_16x16x64_i8 v[10:13], v[182:185], v[198:201], v[10:13]
	v_mfma_i32_16x16x64_i8 v[38:41], v[174:177], v[206:209], v[38:41]
	v_mfma_i32_16x16x64_i8 v[6:9], v[182:185], v[206:209], v[6:9]
	v_mfma_i32_16x16x64_i8 v[34:37], v[174:177], v[214:217], v[34:37]
	s_setprio 3
	s_barrier
	v_mfma_i32_16x16x64_i8 v[2:5], v[182:185], v[214:217], v[2:5]
	s_setprio 0
	s_add_i32 s93, s93, 2
	s_add_u32 s91, s91, 0x100
	s_addc_u32 s92, s92, 0
	s_cmp_gt_u32 s93, 29
	s_mov_b64 s[2:3], s[4:5]
	s_cbranch_scc0 .LBB0_2056
	s_and_b64 vcc, exec, s[8:9]
	s_cbranch_vccz .LBB0_2059
	s_barrier

.LBB0_2240:
	s_add_u32 s69, s36, 0x100
	s_addc_u32 s70, s37, 0
	s_mov_b32 s71, -2
	ds_read_b128 v[130:133], v212
	ds_read_b128 v[134:137], v212 offset:1024
	ds_read_b128 v[138:141], v212 offset:2048
	ds_read_b128 v[142:145], v212 offset:3072
	ds_read_b128 v[146:149], v213
	ds_read_b128 v[150:153], v213 offset:1024
	ds_read_b128 v[154:157], v213 offset:2048
	ds_read_b128 v[158:161], v213 offset:3072
	s_add_u32 s36, s18, 0x100
	s_addc_u32 s37, s19, 0
	s_cmpk_eq_i32 s71, 0xdc
	s_cselect_b32 s41, s3, s37
	s_cselect_b32 s40, s2, s36
	s_cselect_b32 s39, s35, s70
	s_cselect_b32 s38, s34, s69
	v_lshl_add_u64 v[216:217], s[18:19], 0, v[178:179]
	s_add_i32 m0, s44, 0xc000
	ds_read_b128 v[162:165], v214
	ds_read_b128 v[166:169], v214 offset:1024
	ds_read_b128 v[186:189], v214 offset:2048
	ds_read_b128 v[190:193], v214 offset:3072
	ds_read_b128 v[194:197], v214 offset:4096
	ds_read_b128 v[198:201], v214 offset:5120
	ds_read_b128 v[202:205], v214 offset:6144
	ds_read_b128 v[206:209], v214 offset:7168
	global_load_lds_dwordx4 v[216:217], off
	v_lshl_add_u64 v[216:217], s[18:19], 0, v[180:181]
	s_add_i32 m0, s44, 0xe000
	s_nop 0
	global_load_lds_dwordx4 v[216:217], off
	s_waitcnt vmcnt(8)
	s_waitcnt lgkmcnt(0)
	s_barrier
	s_waitcnt lgkmcnt(0)
	v_mfma_f32_16x16x32_bf16 v[126:129], v[130:133], v[162:165], 0
	v_mfma_f32_16x16x32_bf16 v[122:125], v[138:141], v[162:165], 0
	v_mfma_f32_16x16x32_bf16 v[110:113], v[130:133], v[186:189], 0
	v_mfma_f32_16x16x32_bf16 v[106:109], v[138:141], v[186:189], 0
	v_mfma_f32_16x16x32_bf16 v[94:97], v[130:133], v[194:197], 0
	v_mfma_f32_16x16x32_bf16 v[90:93], v[138:141], v[194:197], 0
	v_mfma_f32_16x16x32_bf16 v[78:81], v[130:133], v[202:205], 0
	v_mfma_f32_16x16x32_bf16 v[74:77], v[138:141], v[202:205], 0
	v_mfma_f32_16x16x32_bf16 v[126:129], v[134:137], v[166:169], v[126:129]
	v_mfma_f32_16x16x32_bf16 v[122:125], v[142:145], v[166:169], v[122:125]
	v_mfma_f32_16x16x32_bf16 v[110:113], v[134:137], v[190:193], v[110:113]
	v_mfma_f32_16x16x32_bf16 v[106:109], v[142:145], v[190:193], v[106:109]
	v_mfma_f32_16x16x32_bf16 v[94:97], v[134:137], v[198:201], v[94:97]
	v_mfma_f32_16x16x32_bf16 v[90:93], v[142:145], v[198:201], v[90:93]
	v_mfma_f32_16x16x32_bf16 v[78:81], v[134:137], v[206:209], v[78:81]
	v_mfma_f32_16x16x32_bf16 v[74:77], v[142:145], v[206:209], v[74:77]
	v_mfma_f32_16x16x32_bf16 v[118:121], v[146:149], v[162:165], 0
	v_mfma_f32_16x16x32_bf16 v[114:117], v[154:157], v[162:165], 0
	v_mfma_f32_16x16x32_bf16 v[102:105], v[146:149], v[186:189], 0
	v_mfma_f32_16x16x32_bf16 v[98:101], v[154:157], v[186:189], 0
	v_mfma_f32_16x16x32_bf16 v[86:89], v[146:149], v[194:197], 0
	v_mfma_f32_16x16x32_bf16 v[82:85], v[154:157], v[194:197], 0
	v_mfma_f32_16x16x32_bf16 v[70:73], v[146:149], v[202:205], 0
	v_mfma_f32_16x16x32_bf16 v[66:69], v[154:157], v[202:205], 0
	v_mfma_f32_16x16x32_bf16 v[118:121], v[150:153], v[166:169], v[118:121]
	v_mfma_f32_16x16x32_bf16 v[114:117], v[158:161], v[166:169], v[114:117]
	v_mfma_f32_16x16x32_bf16 v[102:105], v[150:153], v[190:193], v[102:105]
	v_mfma_f32_16x16x32_bf16 v[98:101], v[158:161], v[190:193], v[98:101]
	v_mfma_f32_16x16x32_bf16 v[86:89], v[150:153], v[198:201], v[86:89]
	v_mfma_f32_16x16x32_bf16 v[82:85], v[158:161], v[198:201], v[82:85]
	v_mfma_f32_16x16x32_bf16 v[70:73], v[150:153], v[206:209], v[70:73]
	s_setprio 3
	s_barrier
	v_mfma_f32_16x16x32_bf16 v[66:69], v[158:161], v[206:209], v[66:69]
	s_setprio 0
	s_add_i32 s18, s56, s43
	v_lshl_add_u64 v[216:217], s[38:39], 0, v[172:173]
	s_mov_b32 m0, s18
	ds_read_b128 v[162:165], v214 offset:16384
	ds_read_b128 v[166:169], v214 offset:17408
	ds_read_b128 v[186:189], v214 offset:18432
	ds_read_b128 v[190:193], v214 offset:19456
	ds_read_b128 v[194:197], v214 offset:20480
	ds_read_b128 v[198:201], v214 offset:21504
	ds_read_b128 v[202:205], v214 offset:22528
	ds_read_b128 v[206:209], v214 offset:23552
	global_load_lds_dwordx4 v[216:217], off
	s_add_i32 m0, s18, 0x2000
	s_add_u32 s18, s38, 0x380000
	v_lshl_add_u64 v[218:219], s[38:39], 0, v[176:177]
	s_addc_u32 s19, s39, 0
	s_add_i32 s72, s57, s43
	global_load_lds_dwordx4 v[218:219], off
	v_lshl_add_u64 v[220:221], s[18:19], 0, v[172:173]
	s_mov_b32 m0, s72
	v_lshl_add_u64 v[222:223], s[40:41], 0, v[174:175]
	global_load_lds_dwordx4 v[220:221], off
	v_lshl_add_u64 v[220:221], s[18:19], 0, v[176:177]
	s_add_i32 m0, s72, 0x2000
	s_nop 0
	global_load_lds_dwordx4 v[220:221], off
	v_lshl_add_u64 v[220:221], s[40:41], 0, v[170:171]
	s_mov_b32 m0, s44
	s_nop 0
	global_load_lds_dwordx4 v[220:221], off
	s_mov_b32 m0, s45
	s_nop 0
	global_load_lds_dwordx4 v[222:223], off
	s_waitcnt vmcnt(8)
	s_waitcnt lgkmcnt(0)
	s_barrier
	s_waitcnt lgkmcnt(0)
	v_mfma_f32_16x16x32_bf16 v[62:65], v[130:133], v[162:165], 0
	v_mfma_f32_16x16x32_bf16 v[58:61], v[138:141], v[162:165], 0
	v_mfma_f32_16x16x32_bf16 v[46:49], v[130:133], v[186:189], 0
	v_mfma_f32_16x16x32_bf16 v[42:45], v[138:141], v[186:189], 0
	v_mfma_f32_16x16x32_bf16 v[30:33], v[130:133], v[194:197], 0
	v_mfma_f32_16x16x32_bf16 v[26:29], v[138:141], v[194:197], 0
	v_mfma_f32_16x16x32_bf16 v[14:17], v[130:133], v[202:205], 0
	v_mfma_f32_16x16x32_bf16 v[10:13], v[138:141], v[202:205], 0
	v_mfma_f32_16x16x32_bf16 v[62:65], v[134:137], v[166:169], v[62:65]
	v_mfma_f32_16x16x32_bf16 v[58:61], v[142:145], v[166:169], v[58:61]
	v_mfma_f32_16x16x32_bf16 v[46:49], v[134:137], v[190:193], v[46:49]
	v_mfma_f32_16x16x32_bf16 v[42:45], v[142:145], v[190:193], v[42:45]
	v_mfma_f32_16x16x32_bf16 v[30:33], v[134:137], v[198:201], v[30:33]
	v_mfma_f32_16x16x32_bf16 v[26:29], v[142:145], v[198:201], v[26:29]
	v_mfma_f32_16x16x32_bf16 v[14:17], v[134:137], v[206:209], v[14:17]
	v_mfma_f32_16x16x32_bf16 v[10:13], v[142:145], v[206:209], v[10:13]
	v_mfma_f32_16x16x32_bf16 v[54:57], v[146:149], v[162:165], 0
	v_mfma_f32_16x16x32_bf16 v[50:53], v[154:157], v[162:165], 0
	v_mfma_f32_16x16x32_bf16 v[38:41], v[146:149], v[186:189], 0
	v_mfma_f32_16x16x32_bf16 v[34:37], v[154:157], v[186:189], 0
	v_mfma_f32_16x16x32_bf16 v[22:25], v[146:149], v[194:197], 0
	v_mfma_f32_16x16x32_bf16 v[18:21], v[154:157], v[194:197], 0
	v_mfma_f32_16x16x32_bf16 v[6:9], v[146:149], v[202:205], 0
	v_mfma_f32_16x16x32_bf16 v[2:5], v[154:157], v[202:205], 0
	v_mfma_f32_16x16x32_bf16 v[54:57], v[150:153], v[166:169], v[54:57]
	v_mfma_f32_16x16x32_bf16 v[50:53], v[158:161], v[166:169], v[50:53]
	v_mfma_f32_16x16x32_bf16 v[38:41], v[150:153], v[190:193], v[38:41]
	v_mfma_f32_16x16x32_bf16 v[34:37], v[158:161], v[190:193], v[34:37]
	v_mfma_f32_16x16x32_bf16 v[22:25], v[150:153], v[198:201], v[22:25]
	v_mfma_f32_16x16x32_bf16 v[18:21], v[158:161], v[198:201], v[18:21]
	v_mfma_f32_16x16x32_bf16 v[6:9], v[150:153], v[206:209], v[6:9]
	s_setprio 3
	s_barrier
	v_mfma_f32_16x16x32_bf16 v[2:5], v[158:161], v[206:209], v[2:5]
	s_setprio 0
	s_add_i32 s72, 0, 0x18000
	s_add_i32 s73, 0, 0x1c000
	v_add_u32_e32 v142, s72, v211
	v_add_u32_e32 v158, s73, v211
	ds_read_b128 v[130:133], v142
	ds_read_b128 v[134:137], v142 offset:1024
	ds_read_b128 v[138:141], v142 offset:2048
	ds_read_b128 v[142:145], v142 offset:3072
	ds_read_b128 v[146:149], v158
	ds_read_b128 v[150:153], v158 offset:1024
	ds_read_b128 v[154:157], v158 offset:2048
	ds_read_b128 v[158:161], v158 offset:3072
	s_add_u32 s18, s40, 0x380000
	s_addc_u32 s19, s41, 0
	s_mov_b32 m0, s46
	v_lshl_add_u64 v[224:225], s[18:19], 0, v[170:171]
	ds_read_b128 v[162:165], v214 offset:32768
	ds_read_b128 v[166:169], v214 offset:33792
	ds_read_b128 v[186:189], v214 offset:34816
	ds_read_b128 v[190:193], v214 offset:35840
	ds_read_b128 v[194:197], v214 offset:36864
	ds_read_b128 v[198:201], v214 offset:37888
	ds_read_b128 v[202:205], v214 offset:38912
	ds_read_b128 v[206:209], v214 offset:39936
	global_load_lds_dwordx4 v[224:225], off
	v_lshl_add_u64 v[224:225], s[18:19], 0, v[174:175]
	s_mov_b32 m0, s47
	s_nop 0
	global_load_lds_dwordx4 v[224:225], off
	s_waitcnt vmcnt(8)
	s_waitcnt lgkmcnt(0)
	s_barrier
	s_waitcnt lgkmcnt(0)
	v_mfma_f32_16x16x32_bf16 v[126:129], v[130:133], v[162:165], v[126:129]
	v_mfma_f32_16x16x32_bf16 v[122:125], v[138:141], v[162:165], v[122:125]
	v_mfma_f32_16x16x32_bf16 v[110:113], v[130:133], v[186:189], v[110:113]
	v_mfma_f32_16x16x32_bf16 v[106:109], v[138:141], v[186:189], v[106:109]
	v_mfma_f32_16x16x32_bf16 v[94:97], v[130:133], v[194:197], v[94:97]
	v_mfma_f32_16x16x32_bf16 v[90:93], v[138:141], v[194:197], v[90:93]
	v_mfma_f32_16x16x32_bf16 v[78:81], v[130:133], v[202:205], v[78:81]
	v_mfma_f32_16x16x32_bf16 v[74:77], v[138:141], v[202:205], v[74:77]
	v_mfma_f32_16x16x32_bf16 v[126:129], v[134:137], v[166:169], v[126:129]
	v_mfma_f32_16x16x32_bf16 v[122:125], v[142:145], v[166:169], v[122:125]
	v_mfma_f32_16x16x32_bf16 v[110:113], v[134:137], v[190:193], v[110:113]
	v_mfma_f32_16x16x32_bf16 v[106:109], v[142:145], v[190:193], v[106:109]
	v_mfma_f32_16x16x32_bf16 v[94:97], v[134:137], v[198:201], v[94:97]
	v_mfma_f32_16x16x32_bf16 v[90:93], v[142:145], v[198:201], v[90:93]
	v_mfma_f32_16x16x32_bf16 v[78:81], v[134:137], v[206:209], v[78:81]
	v_mfma_f32_16x16x32_bf16 v[74:77], v[142:145], v[206:209], v[74:77]
	v_mfma_f32_16x16x32_bf16 v[118:121], v[146:149], v[162:165], v[118:121]
	v_mfma_f32_16x16x32_bf16 v[114:117], v[154:157], v[162:165], v[114:117]
	v_mfma_f32_16x16x32_bf16 v[102:105], v[146:149], v[186:189], v[102:105]
	v_mfma_f32_16x16x32_bf16 v[98:101], v[154:157], v[186:189], v[98:101]
	v_mfma_f32_16x16x32_bf16 v[86:89], v[146:149], v[194:197], v[86:89]
	v_mfma_f32_16x16x32_bf16 v[82:85], v[154:157], v[194:197], v[82:85]
	v_mfma_f32_16x16x32_bf16 v[70:73], v[146:149], v[202:205], v[70:73]
	v_mfma_f32_16x16x32_bf16 v[66:69], v[154:157], v[202:205], v[66:69]
	v_mfma_f32_16x16x32_bf16 v[118:121], v[150:153], v[166:169], v[118:121]
	v_mfma_f32_16x16x32_bf16 v[114:117], v[158:161], v[166:169], v[114:117]
	v_mfma_f32_16x16x32_bf16 v[102:105], v[150:153], v[190:193], v[102:105]
	v_mfma_f32_16x16x32_bf16 v[98:101], v[158:161], v[190:193], v[98:101]
	v_mfma_f32_16x16x32_bf16 v[86:89], v[150:153], v[198:201], v[86:89]
	v_mfma_f32_16x16x32_bf16 v[82:85], v[158:161], v[198:201], v[82:85]
	v_mfma_f32_16x16x32_bf16 v[70:73], v[150:153], v[206:209], v[70:73]
	s_setprio 3
	s_barrier
	v_mfma_f32_16x16x32_bf16 v[66:69], v[158:161], v[206:209], v[66:69]
	s_setprio 0
	s_add_i32 s18, s72, s43
	v_lshl_add_u64 v[216:217], v[216:217], 0, s[8:9]
	s_mov_b32 m0, s18
	ds_read_b128 v[162:165], v214 offset:49152
	ds_read_b128 v[166:169], v214 offset:50176
	ds_read_b128 v[186:189], v214 offset:51200
	ds_read_b128 v[190:193], v214 offset:52224
	ds_read_b128 v[194:197], v214 offset:53248
	ds_read_b128 v[198:201], v214 offset:54272
	ds_read_b128 v[202:205], v214 offset:55296
	ds_read_b128 v[206:209], v214 offset:56320
	global_load_lds_dwordx4 v[216:217], off
	s_add_i32 m0, s18, 0x2000
	s_add_u32 s18, s38, 0x380080
	v_lshl_add_u64 v[216:217], v[218:219], 0, s[8:9]
	s_addc_u32 s19, s39, 0
	s_add_i32 s38, s73, s43
	global_load_lds_dwordx4 v[216:217], off
	v_lshl_add_u64 v[216:217], s[18:19], 0, v[172:173]
	s_mov_b32 m0, s38
	s_nop 0
	global_load_lds_dwordx4 v[216:217], off
	v_lshl_add_u64 v[216:217], s[18:19], 0, v[176:177]
	s_add_i32 m0, s38, 0x2000
	s_nop 0
	global_load_lds_dwordx4 v[216:217], off
	v_lshl_add_u64 v[216:217], v[220:221], 0, s[8:9]
	s_mov_b32 m0, s51
	s_nop 0
	global_load_lds_dwordx4 v[216:217], off
	v_lshl_add_u64 v[216:217], v[222:223], 0, s[8:9]
	s_mov_b32 m0, s54
	s_nop 0
	global_load_lds_dwordx4 v[216:217], off
	s_waitcnt vmcnt(8)
	s_waitcnt lgkmcnt(0)
	s_barrier
	s_waitcnt lgkmcnt(0)
	v_mfma_f32_16x16x32_bf16 v[62:65], v[130:133], v[162:165], v[62:65]
	v_mfma_f32_16x16x32_bf16 v[58:61], v[138:141], v[162:165], v[58:61]
	v_mfma_f32_16x16x32_bf16 v[46:49], v[130:133], v[186:189], v[46:49]
	v_mfma_f32_16x16x32_bf16 v[42:45], v[138:141], v[186:189], v[42:45]
	v_mfma_f32_16x16x32_bf16 v[30:33], v[130:133], v[194:197], v[30:33]
	v_mfma_f32_16x16x32_bf16 v[26:29], v[138:141], v[194:197], v[26:29]
	v_mfma_f32_16x16x32_bf16 v[14:17], v[130:133], v[202:205], v[14:17]
	v_mfma_f32_16x16x32_bf16 v[10:13], v[138:141], v[202:205], v[10:13]
	v_mfma_f32_16x16x32_bf16 v[62:65], v[134:137], v[166:169], v[62:65]
	v_mfma_f32_16x16x32_bf16 v[58:61], v[142:145], v[166:169], v[58:61]
	v_mfma_f32_16x16x32_bf16 v[46:49], v[134:137], v[190:193], v[46:49]
	v_mfma_f32_16x16x32_bf16 v[42:45], v[142:145], v[190:193], v[42:45]
	v_mfma_f32_16x16x32_bf16 v[30:33], v[134:137], v[198:201], v[30:33]
	v_mfma_f32_16x16x32_bf16 v[26:29], v[142:145], v[198:201], v[26:29]
	v_mfma_f32_16x16x32_bf16 v[14:17], v[134:137], v[206:209], v[14:17]
	v_mfma_f32_16x16x32_bf16 v[10:13], v[142:145], v[206:209], v[10:13]
	v_mfma_f32_16x16x32_bf16 v[54:57], v[146:149], v[162:165], v[54:57]
	v_mfma_f32_16x16x32_bf16 v[50:53], v[154:157], v[162:165], v[50:53]
	v_mfma_f32_16x16x32_bf16 v[38:41], v[146:149], v[186:189], v[38:41]
	v_mfma_f32_16x16x32_bf16 v[34:37], v[154:157], v[186:189], v[34:37]
	v_mfma_f32_16x16x32_bf16 v[22:25], v[146:149], v[194:197], v[22:25]
	v_mfma_f32_16x16x32_bf16 v[18:21], v[154:157], v[194:197], v[18:21]
	v_mfma_f32_16x16x32_bf16 v[6:9], v[146:149], v[202:205], v[6:9]
	v_mfma_f32_16x16x32_bf16 v[2:5], v[154:157], v[202:205], v[2:5]
	v_mfma_f32_16x16x32_bf16 v[54:57], v[150:153], v[166:169], v[54:57]
	v_mfma_f32_16x16x32_bf16 v[50:53], v[158:161], v[166:169], v[50:53]
	v_mfma_f32_16x16x32_bf16 v[38:41], v[150:153], v[190:193], v[38:41]
	v_mfma_f32_16x16x32_bf16 v[34:37], v[158:161], v[190:193], v[34:37]
	v_mfma_f32_16x16x32_bf16 v[22:25], v[150:153], v[198:201], v[22:25]
	v_mfma_f32_16x16x32_bf16 v[18:21], v[158:161], v[198:201], v[18:21]
	v_mfma_f32_16x16x32_bf16 v[6:9], v[150:153], v[206:209], v[6:9]
	s_setprio 3
	s_barrier
	v_mfma_f32_16x16x32_bf16 v[2:5], v[158:161], v[206:209], v[2:5]
	s_setprio 0
	s_add_i32 s71, s71, 2
	s_add_u32 s69, s69, 0x100
	s_addc_u32 s70, s70, 0
	s_cmpk_gt_u32 s71, 0xdd
	s_mov_b64 s[18:19], s[36:37]
.LBB0_2241:
	ds_read_b128 v[130:133], v212
	ds_read_b128 v[134:137], v212 offset:1024
	ds_read_b128 v[138:141], v212 offset:2048
	ds_read_b128 v[142:145], v212 offset:3072
	ds_read_b128 v[146:149], v213
	ds_read_b128 v[150:153], v213 offset:1024
	ds_read_b128 v[154:157], v213 offset:2048
	ds_read_b128 v[158:161], v213 offset:3072
	s_add_u32 s36, s18, 0x100
	s_addc_u32 s37, s19, 0
	s_cmpk_eq_i32 s71, 0xdc
	s_cselect_b32 s41, s3, s37
	s_cselect_b32 s40, s2, s36
	s_cselect_b32 s39, s35, s70
	s_cselect_b32 s38, s34, s69
	v_lshl_add_u64 v[216:217], s[18:19], 0, v[178:179]
	s_add_i32 m0, s44, 0xc000
	ds_read_b128 v[162:165], v214
	ds_read_b128 v[166:169], v214 offset:1024
	ds_read_b128 v[186:189], v214 offset:2048
	ds_read_b128 v[190:193], v214 offset:3072
	ds_read_b128 v[194:197], v214 offset:4096
	ds_read_b128 v[198:201], v214 offset:5120
	ds_read_b128 v[202:205], v214 offset:6144
	ds_read_b128 v[206:209], v214 offset:7168
	global_load_lds_dwordx4 v[216:217], off
	v_lshl_add_u64 v[216:217], s[18:19], 0, v[180:181]
	s_add_i32 m0, s44, 0xe000
	s_nop 0
	global_load_lds_dwordx4 v[216:217], off
	s_waitcnt vmcnt(8)
	s_waitcnt lgkmcnt(0)
	s_barrier
	s_waitcnt lgkmcnt(0)
	v_mfma_f32_16x16x32_bf16 v[126:129], v[130:133], v[162:165], v[126:129]
	v_mfma_f32_16x16x32_bf16 v[122:125], v[138:141], v[162:165], v[122:125]
	v_mfma_f32_16x16x32_bf16 v[110:113], v[130:133], v[186:189], v[110:113]
	v_mfma_f32_16x16x32_bf16 v[106:109], v[138:141], v[186:189], v[106:109]
	v_mfma_f32_16x16x32_bf16 v[94:97], v[130:133], v[194:197], v[94:97]
	v_mfma_f32_16x16x32_bf16 v[90:93], v[138:141], v[194:197], v[90:93]
	v_mfma_f32_16x16x32_bf16 v[78:81], v[130:133], v[202:205], v[78:81]
	v_mfma_f32_16x16x32_bf16 v[74:77], v[138:141], v[202:205], v[74:77]
	v_mfma_f32_16x16x32_bf16 v[126:129], v[134:137], v[166:169], v[126:129]
	v_mfma_f32_16x16x32_bf16 v[122:125], v[142:145], v[166:169], v[122:125]
	v_mfma_f32_16x16x32_bf16 v[110:113], v[134:137], v[190:193], v[110:113]
	v_mfma_f32_16x16x32_bf16 v[106:109], v[142:145], v[190:193], v[106:109]
	v_mfma_f32_16x16x32_bf16 v[94:97], v[134:137], v[198:201], v[94:97]
	v_mfma_f32_16x16x32_bf16 v[90:93], v[142:145], v[198:201], v[90:93]
	v_mfma_f32_16x16x32_bf16 v[78:81], v[134:137], v[206:209], v[78:81]
	v_mfma_f32_16x16x32_bf16 v[74:77], v[142:145], v[206:209], v[74:77]
	v_mfma_f32_16x16x32_bf16 v[118:121], v[146:149], v[162:165], v[118:121]
	v_mfma_f32_16x16x32_bf16 v[114:117], v[154:157], v[162:165], v[114:117]
	v_mfma_f32_16x16x32_bf16 v[102:105], v[146:149], v[186:189], v[102:105]
	v_mfma_f32_16x16x32_bf16 v[98:101], v[154:157], v[186:189], v[98:101]
	v_mfma_f32_16x16x32_bf16 v[86:89], v[146:149], v[194:197], v[86:89]
	v_mfma_f32_16x16x32_bf16 v[82:85], v[154:157], v[194:197], v[82:85]
	v_mfma_f32_16x16x32_bf16 v[70:73], v[146:149], v[202:205], v[70:73]
	v_mfma_f32_16x16x32_bf16 v[66:69], v[154:157], v[202:205], v[66:69]
	v_mfma_f32_16x16x32_bf16 v[118:121], v[150:153], v[166:169], v[118:121]
	v_mfma_f32_16x16x32_bf16 v[114:117], v[158:161], v[166:169], v[114:117]
	v_mfma_f32_16x16x32_bf16 v[102:105], v[150:153], v[190:193], v[102:105]
	v_mfma_f32_16x16x32_bf16 v[98:101], v[158:161], v[190:193], v[98:101]
	v_mfma_f32_16x16x32_bf16 v[86:89], v[150:153], v[198:201], v[86:89]
	v_mfma_f32_16x16x32_bf16 v[82:85], v[158:161], v[198:201], v[82:85]
	v_mfma_f32_16x16x32_bf16 v[70:73], v[150:153], v[206:209], v[70:73]
	s_setprio 3
	s_barrier
	v_mfma_f32_16x16x32_bf16 v[66:69], v[158:161], v[206:209], v[66:69]
	s_setprio 0
	s_add_i32 s18, s56, s43
	v_lshl_add_u64 v[216:217], s[38:39], 0, v[172:173]
	s_mov_b32 m0, s18
	ds_read_b128 v[162:165], v214 offset:16384
	ds_read_b128 v[166:169], v214 offset:17408
	ds_read_b128 v[186:189], v214 offset:18432
	ds_read_b128 v[190:193], v214 offset:19456
	ds_read_b128 v[194:197], v214 offset:20480
	ds_read_b128 v[198:201], v214 offset:21504
	ds_read_b128 v[202:205], v214 offset:22528
	ds_read_b128 v[206:209], v214 offset:23552
	global_load_lds_dwordx4 v[216:217], off
	s_add_i32 m0, s18, 0x2000
	s_add_u32 s18, s38, 0x380000
	v_lshl_add_u64 v[218:219], s[38:39], 0, v[176:177]
	s_addc_u32 s19, s39, 0
	s_add_i32 s72, s57, s43
	global_load_lds_dwordx4 v[218:219], off
	v_lshl_add_u64 v[220:221], s[18:19], 0, v[172:173]
	s_mov_b32 m0, s72
	v_lshl_add_u64 v[222:223], s[40:41], 0, v[174:175]
	global_load_lds_dwordx4 v[220:221], off
	v_lshl_add_u64 v[220:221], s[18:19], 0, v[176:177]
	s_add_i32 m0, s72, 0x2000
	s_nop 0
	global_load_lds_dwordx4 v[220:221], off
	v_lshl_add_u64 v[220:221], s[40:41], 0, v[170:171]
	s_mov_b32 m0, s44
	s_nop 0
	global_load_lds_dwordx4 v[220:221], off
	s_mov_b32 m0, s45
	s_nop 0
	global_load_lds_dwordx4 v[222:223], off
	s_waitcnt vmcnt(8)
	s_waitcnt lgkmcnt(0)
	s_barrier
	s_waitcnt lgkmcnt(0)
	v_mfma_f32_16x16x32_bf16 v[62:65], v[130:133], v[162:165], v[62:65]
	v_mfma_f32_16x16x32_bf16 v[58:61], v[138:141], v[162:165], v[58:61]
	v_mfma_f32_16x16x32_bf16 v[46:49], v[130:133], v[186:189], v[46:49]
	v_mfma_f32_16x16x32_bf16 v[42:45], v[138:141], v[186:189], v[42:45]
	v_mfma_f32_16x16x32_bf16 v[30:33], v[130:133], v[194:197], v[30:33]
	v_mfma_f32_16x16x32_bf16 v[26:29], v[138:141], v[194:197], v[26:29]
	v_mfma_f32_16x16x32_bf16 v[14:17], v[130:133], v[202:205], v[14:17]
	v_mfma_f32_16x16x32_bf16 v[10:13], v[138:141], v[202:205], v[10:13]
	v_mfma_f32_16x16x32_bf16 v[62:65], v[134:137], v[166:169], v[62:65]
	v_mfma_f32_16x16x32_bf16 v[58:61], v[142:145], v[166:169], v[58:61]
	v_mfma_f32_16x16x32_bf16 v[46:49], v[134:137], v[190:193], v[46:49]
	v_mfma_f32_16x16x32_bf16 v[42:45], v[142:145], v[190:193], v[42:45]
	v_mfma_f32_16x16x32_bf16 v[30:33], v[134:137], v[198:201], v[30:33]
	v_mfma_f32_16x16x32_bf16 v[26:29], v[142:145], v[198:201], v[26:29]
	v_mfma_f32_16x16x32_bf16 v[14:17], v[134:137], v[206:209], v[14:17]
	v_mfma_f32_16x16x32_bf16 v[10:13], v[142:145], v[206:209], v[10:13]
	v_mfma_f32_16x16x32_bf16 v[54:57], v[146:149], v[162:165], v[54:57]
	v_mfma_f32_16x16x32_bf16 v[50:53], v[154:157], v[162:165], v[50:53]
	v_mfma_f32_16x16x32_bf16 v[38:41], v[146:149], v[186:189], v[38:41]
	v_mfma_f32_16x16x32_bf16 v[34:37], v[154:157], v[186:189], v[34:37]
	v_mfma_f32_16x16x32_bf16 v[22:25], v[146:149], v[194:197], v[22:25]
	v_mfma_f32_16x16x32_bf16 v[18:21], v[154:157], v[194:197], v[18:21]
	v_mfma_f32_16x16x32_bf16 v[6:9], v[146:149], v[202:205], v[6:9]
	v_mfma_f32_16x16x32_bf16 v[2:5], v[154:157], v[202:205], v[2:5]
	v_mfma_f32_16x16x32_bf16 v[54:57], v[150:153], v[166:169], v[54:57]
	v_mfma_f32_16x16x32_bf16 v[50:53], v[158:161], v[166:169], v[50:53]
	v_mfma_f32_16x16x32_bf16 v[38:41], v[150:153], v[190:193], v[38:41]
	v_mfma_f32_16x16x32_bf16 v[34:37], v[158:161], v[190:193], v[34:37]
	v_mfma_f32_16x16x32_bf16 v[22:25], v[150:153], v[198:201], v[22:25]
	v_mfma_f32_16x16x32_bf16 v[18:21], v[158:161], v[198:201], v[18:21]
	v_mfma_f32_16x16x32_bf16 v[6:9], v[150:153], v[206:209], v[6:9]
	s_setprio 3
	s_barrier
	v_mfma_f32_16x16x32_bf16 v[2:5], v[158:161], v[206:209], v[2:5]
	s_setprio 0
	s_add_i32 s72, 0, 0x18000
	s_add_i32 s73, 0, 0x1c000
	v_add_u32_e32 v142, s72, v211
	v_add_u32_e32 v158, s73, v211
	ds_read_b128 v[130:133], v142
	ds_read_b128 v[134:137], v142 offset:1024
	ds_read_b128 v[138:141], v142 offset:2048
	ds_read_b128 v[142:145], v142 offset:3072
	ds_read_b128 v[146:149], v158
	ds_read_b128 v[150:153], v158 offset:1024
	ds_read_b128 v[154:157], v158 offset:2048
	ds_read_b128 v[158:161], v158 offset:3072
	s_add_u32 s18, s40, 0x380000
	s_addc_u32 s19, s41, 0
	s_mov_b32 m0, s46
	v_lshl_add_u64 v[224:225], s[18:19], 0, v[170:171]
	ds_read_b128 v[162:165], v214 offset:32768
	ds_read_b128 v[166:169], v214 offset:33792
	ds_read_b128 v[186:189], v214 offset:34816
	ds_read_b128 v[190:193], v214 offset:35840
	ds_read_b128 v[194:197], v214 offset:36864
	ds_read_b128 v[198:201], v214 offset:37888
	ds_read_b128 v[202:205], v214 offset:38912
	ds_read_b128 v[206:209], v214 offset:39936
	global_load_lds_dwordx4 v[224:225], off
	v_lshl_add_u64 v[224:225], s[18:19], 0, v[174:175]
	s_mov_b32 m0, s47
	s_nop 0
	global_load_lds_dwordx4 v[224:225], off
	s_waitcnt vmcnt(8)
	s_waitcnt lgkmcnt(0)
	s_barrier
	s_waitcnt lgkmcnt(0)
	v_mfma_f32_16x16x32_bf16 v[126:129], v[130:133], v[162:165], v[126:129]
	v_mfma_f32_16x16x32_bf16 v[122:125], v[138:141], v[162:165], v[122:125]
	v_mfma_f32_16x16x32_bf16 v[110:113], v[130:133], v[186:189], v[110:113]
	v_mfma_f32_16x16x32_bf16 v[106:109], v[138:141], v[186:189], v[106:109]
	v_mfma_f32_16x16x32_bf16 v[94:97], v[130:133], v[194:197], v[94:97]
	v_mfma_f32_16x16x32_bf16 v[90:93], v[138:141], v[194:197], v[90:93]
	v_mfma_f32_16x16x32_bf16 v[78:81], v[130:133], v[202:205], v[78:81]
	v_mfma_f32_16x16x32_bf16 v[74:77], v[138:141], v[202:205], v[74:77]
	v_mfma_f32_16x16x32_bf16 v[126:129], v[134:137], v[166:169], v[126:129]
	v_mfma_f32_16x16x32_bf16 v[122:125], v[142:145], v[166:169], v[122:125]
	v_mfma_f32_16x16x32_bf16 v[110:113], v[134:137], v[190:193], v[110:113]
	v_mfma_f32_16x16x32_bf16 v[106:109], v[142:145], v[190:193], v[106:109]
	v_mfma_f32_16x16x32_bf16 v[94:97], v[134:137], v[198:201], v[94:97]
	v_mfma_f32_16x16x32_bf16 v[90:93], v[142:145], v[198:201], v[90:93]
	v_mfma_f32_16x16x32_bf16 v[78:81], v[134:137], v[206:209], v[78:81]
	v_mfma_f32_16x16x32_bf16 v[74:77], v[142:145], v[206:209], v[74:77]
	v_mfma_f32_16x16x32_bf16 v[118:121], v[146:149], v[162:165], v[118:121]
	v_mfma_f32_16x16x32_bf16 v[114:117], v[154:157], v[162:165], v[114:117]
	v_mfma_f32_16x16x32_bf16 v[102:105], v[146:149], v[186:189], v[102:105]
	v_mfma_f32_16x16x32_bf16 v[98:101], v[154:157], v[186:189], v[98:101]
	v_mfma_f32_16x16x32_bf16 v[86:89], v[146:149], v[194:197], v[86:89]
	v_mfma_f32_16x16x32_bf16 v[82:85], v[154:157], v[194:197], v[82:85]
	v_mfma_f32_16x16x32_bf16 v[70:73], v[146:149], v[202:205], v[70:73]
	v_mfma_f32_16x16x32_bf16 v[66:69], v[154:157], v[202:205], v[66:69]
	v_mfma_f32_16x16x32_bf16 v[118:121], v[150:153], v[166:169], v[118:121]
	v_mfma_f32_16x16x32_bf16 v[114:117], v[158:161], v[166:169], v[114:117]
	v_mfma_f32_16x16x32_bf16 v[102:105], v[150:153], v[190:193], v[102:105]
	v_mfma_f32_16x16x32_bf16 v[98:101], v[158:161], v[190:193], v[98:101]
	v_mfma_f32_16x16x32_bf16 v[86:89], v[150:153], v[198:201], v[86:89]
	v_mfma_f32_16x16x32_bf16 v[82:85], v[158:161], v[198:201], v[82:85]
	v_mfma_f32_16x16x32_bf16 v[70:73], v[150:153], v[206:209], v[70:73]
	s_setprio 3
	s_barrier
	v_mfma_f32_16x16x32_bf16 v[66:69], v[158:161], v[206:209], v[66:69]
	s_setprio 0
	s_add_i32 s18, s72, s43
	v_lshl_add_u64 v[216:217], v[216:217], 0, s[8:9]
	s_mov_b32 m0, s18
	ds_read_b128 v[162:165], v214 offset:49152
	ds_read_b128 v[166:169], v214 offset:50176
	ds_read_b128 v[186:189], v214 offset:51200
	ds_read_b128 v[190:193], v214 offset:52224
	ds_read_b128 v[194:197], v214 offset:53248
	ds_read_b128 v[198:201], v214 offset:54272
	ds_read_b128 v[202:205], v214 offset:55296
	ds_read_b128 v[206:209], v214 offset:56320
	global_load_lds_dwordx4 v[216:217], off
	s_add_i32 m0, s18, 0x2000
	s_add_u32 s18, s38, 0x380080
	v_lshl_add_u64 v[216:217], v[218:219], 0, s[8:9]
	s_addc_u32 s19, s39, 0
	s_add_i32 s38, s73, s43
	global_load_lds_dwordx4 v[216:217], off
	v_lshl_add_u64 v[216:217], s[18:19], 0, v[172:173]
	s_mov_b32 m0, s38
	s_nop 0
	global_load_lds_dwordx4 v[216:217], off
	v_lshl_add_u64 v[216:217], s[18:19], 0, v[176:177]
	s_add_i32 m0, s38, 0x2000
	s_nop 0
	global_load_lds_dwordx4 v[216:217], off
	v_lshl_add_u64 v[216:217], v[220:221], 0, s[8:9]
	s_mov_b32 m0, s51
	s_nop 0
	global_load_lds_dwordx4 v[216:217], off
	v_lshl_add_u64 v[216:217], v[222:223], 0, s[8:9]
	s_mov_b32 m0, s54
	s_nop 0
	global_load_lds_dwordx4 v[216:217], off
	s_waitcnt vmcnt(8)
	s_waitcnt lgkmcnt(0)
	s_barrier
	s_waitcnt lgkmcnt(0)
	v_mfma_f32_16x16x32_bf16 v[62:65], v[130:133], v[162:165], v[62:65]
	v_mfma_f32_16x16x32_bf16 v[58:61], v[138:141], v[162:165], v[58:61]
	v_mfma_f32_16x16x32_bf16 v[46:49], v[130:133], v[186:189], v[46:49]
	v_mfma_f32_16x16x32_bf16 v[42:45], v[138:141], v[186:189], v[42:45]
	v_mfma_f32_16x16x32_bf16 v[30:33], v[130:133], v[194:197], v[30:33]
	v_mfma_f32_16x16x32_bf16 v[26:29], v[138:141], v[194:197], v[26:29]
	v_mfma_f32_16x16x32_bf16 v[14:17], v[130:133], v[202:205], v[14:17]
	v_mfma_f32_16x16x32_bf16 v[10:13], v[138:141], v[202:205], v[10:13]
	v_mfma_f32_16x16x32_bf16 v[62:65], v[134:137], v[166:169], v[62:65]
	v_mfma_f32_16x16x32_bf16 v[58:61], v[142:145], v[166:169], v[58:61]
	v_mfma_f32_16x16x32_bf16 v[46:49], v[134:137], v[190:193], v[46:49]
	v_mfma_f32_16x16x32_bf16 v[42:45], v[142:145], v[190:193], v[42:45]
	v_mfma_f32_16x16x32_bf16 v[30:33], v[134:137], v[198:201], v[30:33]
	v_mfma_f32_16x16x32_bf16 v[26:29], v[142:145], v[198:201], v[26:29]
	v_mfma_f32_16x16x32_bf16 v[14:17], v[134:137], v[206:209], v[14:17]
	v_mfma_f32_16x16x32_bf16 v[10:13], v[142:145], v[206:209], v[10:13]
	v_mfma_f32_16x16x32_bf16 v[54:57], v[146:149], v[162:165], v[54:57]
	v_mfma_f32_16x16x32_bf16 v[50:53], v[154:157], v[162:165], v[50:53]
	v_mfma_f32_16x16x32_bf16 v[38:41], v[146:149], v[186:189], v[38:41]
	v_mfma_f32_16x16x32_bf16 v[34:37], v[154:157], v[186:189], v[34:37]
	v_mfma_f32_16x16x32_bf16 v[22:25], v[146:149], v[194:197], v[22:25]
	v_mfma_f32_16x16x32_bf16 v[18:21], v[154:157], v[194:197], v[18:21]
	v_mfma_f32_16x16x32_bf16 v[6:9], v[146:149], v[202:205], v[6:9]
	v_mfma_f32_16x16x32_bf16 v[2:5], v[154:157], v[202:205], v[2:5]
	v_mfma_f32_16x16x32_bf16 v[54:57], v[150:153], v[166:169], v[54:57]
	v_mfma_f32_16x16x32_bf16 v[50:53], v[158:161], v[166:169], v[50:53]
	v_mfma_f32_16x16x32_bf16 v[38:41], v[150:153], v[190:193], v[38:41]
	v_mfma_f32_16x16x32_bf16 v[34:37], v[158:161], v[190:193], v[34:37]
	v_mfma_f32_16x16x32_bf16 v[22:25], v[150:153], v[198:201], v[22:25]
	v_mfma_f32_16x16x32_bf16 v[18:21], v[158:161], v[198:201], v[18:21]
	v_mfma_f32_16x16x32_bf16 v[6:9], v[150:153], v[206:209], v[6:9]
	s_setprio 3
	s_barrier
	v_mfma_f32_16x16x32_bf16 v[2:5], v[158:161], v[206:209], v[2:5]
	s_setprio 0
	s_add_i32 s71, s71, 2
	s_add_u32 s69, s69, 0x100
	s_addc_u32 s70, s70, 0
	s_cmpk_gt_u32 s71, 0xdd
	s_mov_b64 s[18:19], s[36:37]
	s_cbranch_scc0 .LBB0_2241
	s_and_b64 vcc, exec, s[10:11]
	s_cbranch_vccz .LBB0_2244
	s_barrier
